# v7 + s_nop pads so that every MFMA block of the six GEMM K-loops starts at byte phase 4 mod 8
# speedup vs baseline: 1.0040x; 1.0040x over previous
; #define PG8_STAGE(bufoff, gbase, voff) do { _Pragma("unroll") for (int _i = 0; _i < 2; ++_i) \
;         __builtin_amdgcn_global_load_lds((const unsigned*)((const char*)(gbase) + (voff)[_i]), (PG8_LAS unsigned*)(lds + (bufoff) + ldsw + _i * 8192), 16, 0, 0); } while (0)
; #define PG8_LDA(dst, b, h) do { _Pragma("unroll") for (int m = 0; m < 4; ++m) _Pragma("unroll") for (int k = 0; k < 2; ++k) dst[m][k] = *(const PG8_LAS bf16x8*)(lds + PG8_SA(b, h) + aoff + m * 2048 + k * 1024); } while (0)
; #define PG8_LDB(dst, b, h) do { _Pragma("unroll") for (int n = 0; n < 2; ++n) _Pragma("unroll") for (int k = 0; k < 2; ++k) dst[n][k] = *(const PG8_LAS bf16x8*)(lds + PG8_SB(b, h) + boff + n * 2048 + k * 1024); } while (0)
; #define PG8_WAIT_V(n) asm volatile("s_waitcnt vmcnt(" #n ")" ::: "memory")
; #define PG8_WAIT_L(n) asm volatile("s_waitcnt lgkmcnt(" #n ")" ::: "memory")
; #define PG8_BAR __builtin_amdgcn_s_barrier()
; #define PG8_SCHED __builtin_amdgcn_sched_barrier(0)
; template <class Epi, class Sched, bool ALIGN_EPI = false, bool SP2 = false>
; __device__ __forceinline__ void gemm_phase(PG8_LAS unsigned char* lds, const Gemm g, const Sched& S, const Epi& E, const int wave_id) {
;     ...
;         const bool has_next = S.next(ui + 1, nxt);
;         const char* nA = has_next ? (const char*)g.A + (size_t)nxt.pm * tstep : cA; const char* nB = has_next ? (const char*)g.Bt + (size_t)nxt.pn * tstep : cB;
;         for (int t = 0; t < nt; t += 2) {
;             const bool last = (t == nt - 2);
;             const char* a1 = cA + (size_t)(t + 1) * kstep;
;             const char* a2 = last ? nA : cA + (size_t)(t + 2) * kstep; const char* b2 = last ? nB : cB + (size_t)(t + 2) * kstep;
;             const char* a3 = a2 + kstep; const char* b3 = b2 + kstep;
;             if (last && has_next) S.a_ready(nxt);
;             if constexpr (SP2) {
;             PG8_LDB(B0, 0, 0); PG8_LDB(B1, 0, 1); PG8_SCHED; PG8_LDA(At, 0, 0); PG8_STAGE(PG8_SA(1, 1), a1 + hstep, voffA);
;             PG8_WAIT_V(8); PG8_WAIT_L(0); PG8_BAR; PG8_MMA(0, 0, At, B0); PG8_MMA(0, 1, At, B1); PG8_BAR; PG8_SCHED;
;     ...
; #pragma unroll
;         for (int a = 0; a < 2; ++a)
; #pragma unroll
;             for (int b = 0; b < 2; ++b)
; #pragma unroll
;                 for (int m = 0; m < 4; ++m)
; #pragma unroll
;                     for (int n = 0; n < 2; ++n) acc[a][b][m][n] = (f32x4){0.f, 0.f, 0.f, 0.f};
.LBB0_389:
	s_ashr_i32 s23, s22, 31
	s_lshl_b64 s[24:25], s[22:23], 19
	s_add_u32 s24, s44, s24
	s_addc_u32 s25, s45, s25
	s_and_b64 s[26:27], s[4:5], exec
	s_cselect_b32 s23, s25, s31
	s_cselect_b32 s59, s24, s30
	s_ashr_i32 s21, s20, 31
	s_lshl_b64 s[26:27], s[20:21], 19
	s_add_u32 s26, s46, s26
	s_addc_u32 s27, s47, s27
	s_and_b64 s[36:37], s[4:5], exec
	s_cselect_b32 s21, s27, s35
	s_cselect_b32 s60, s26, s34
	s_add_u32 s30, s30, 0x40080
	s_addc_u32 s31, s31, 0
	s_add_u32 s61, s34, 0x100
	v_mov_b32_e32 v0, 0
	s_addc_u32 s62, s35, 0
	s_mov_b32 s63, -2
	v_mov_b32_e32 v1, v0
	v_mov_b32_e32 v2, v0
	v_mov_b32_e32 v3, v0
	v_mov_b32_e32 v4, v0
	v_mov_b32_e32 v5, v0
	v_mov_b32_e32 v6, v0
	v_mov_b32_e32 v7, v0
	v_mov_b32_e32 v16, v0
	v_mov_b32_e32 v17, v0
	v_mov_b32_e32 v18, v0
	v_mov_b32_e32 v19, v0
	v_mov_b32_e32 v20, v0
	v_mov_b32_e32 v21, v0
	v_mov_b32_e32 v22, v0
	v_mov_b32_e32 v23, v0
	v_mov_b32_e32 v32, v0
	v_mov_b32_e32 v33, v0
	v_mov_b32_e32 v34, v0
	v_mov_b32_e32 v35, v0
	v_mov_b32_e32 v36, v0
	v_mov_b32_e32 v37, v0
	v_mov_b32_e32 v38, v0
	v_mov_b32_e32 v39, v0
	v_mov_b32_e32 v48, v0
	v_mov_b32_e32 v49, v0
	v_mov_b32_e32 v50, v0
	v_mov_b32_e32 v51, v0
	v_mov_b32_e32 v52, v0
	v_mov_b32_e32 v53, v0
	v_mov_b32_e32 v54, v0
	v_mov_b32_e32 v55, v0
	v_mov_b32_e32 v8, v0
	v_mov_b32_e32 v9, v0
	v_mov_b32_e32 v10, v0
	v_mov_b32_e32 v11, v0
	v_mov_b32_e32 v12, v0
	v_mov_b32_e32 v13, v0
	v_mov_b32_e32 v14, v0
	v_mov_b32_e32 v15, v0
	v_mov_b32_e32 v24, v0
	v_mov_b32_e32 v25, v0
	v_mov_b32_e32 v26, v0
	v_mov_b32_e32 v27, v0
	v_mov_b32_e32 v28, v0
	v_mov_b32_e32 v29, v0
	v_mov_b32_e32 v30, v0
	v_mov_b32_e32 v31, v0
	v_mov_b32_e32 v40, v0
	v_mov_b32_e32 v41, v0
	v_mov_b32_e32 v42, v0
	v_mov_b32_e32 v43, v0
	v_mov_b32_e32 v44, v0
	v_mov_b32_e32 v45, v0
	v_mov_b32_e32 v46, v0
	v_mov_b32_e32 v47, v0
	v_mov_b32_e32 v56, v0
	v_mov_b32_e32 v57, v0
	v_mov_b32_e32 v58, v0
	v_mov_b32_e32 v59, v0
	v_mov_b32_e32 v60, v0
	v_mov_b32_e32 v61, v0
	v_mov_b32_e32 v62, v0
	v_mov_b32_e32 v63, v0
	v_mov_b32_e32 v64, v0
	v_mov_b32_e32 v65, v0
	v_mov_b32_e32 v66, v0
	v_mov_b32_e32 v67, v0
	v_mov_b32_e32 v68, v0
	v_mov_b32_e32 v69, v0
	v_mov_b32_e32 v70, v0
	v_mov_b32_e32 v71, v0
	v_mov_b32_e32 v80, v0
	v_mov_b32_e32 v81, v0
	v_mov_b32_e32 v82, v0
	v_mov_b32_e32 v83, v0
	v_mov_b32_e32 v84, v0
	v_mov_b32_e32 v85, v0
	v_mov_b32_e32 v86, v0
	v_mov_b32_e32 v87, v0
	v_mov_b32_e32 v96, v0
	v_mov_b32_e32 v97, v0
	v_mov_b32_e32 v98, v0
	v_mov_b32_e32 v99, v0
	v_mov_b32_e32 v100, v0
	v_mov_b32_e32 v101, v0
	v_mov_b32_e32 v102, v0
	v_mov_b32_e32 v103, v0
	v_mov_b32_e32 v112, v0
	v_mov_b32_e32 v113, v0
	v_mov_b32_e32 v114, v0
	v_mov_b32_e32 v115, v0
	v_mov_b32_e32 v116, v0
	v_mov_b32_e32 v117, v0
	v_mov_b32_e32 v118, v0
	v_mov_b32_e32 v119, v0
	v_mov_b32_e32 v72, v0
	v_mov_b32_e32 v73, v0
	v_mov_b32_e32 v74, v0
	v_mov_b32_e32 v75, v0
	v_mov_b32_e32 v76, v0
	v_mov_b32_e32 v77, v0
	v_mov_b32_e32 v78, v0
	v_mov_b32_e32 v79, v0
	v_mov_b32_e32 v88, v0
	v_mov_b32_e32 v89, v0
	v_mov_b32_e32 v90, v0
	v_mov_b32_e32 v91, v0
	v_mov_b32_e32 v92, v0
	v_mov_b32_e32 v93, v0
	v_mov_b32_e32 v94, v0
	v_mov_b32_e32 v95, v0
	v_mov_b32_e32 v104, v0
	v_mov_b32_e32 v105, v0
	v_mov_b32_e32 v106, v0
	v_mov_b32_e32 v107, v0
	v_mov_b32_e32 v108, v0
	v_mov_b32_e32 v109, v0
	v_mov_b32_e32 v110, v0
	v_mov_b32_e32 v111, v0
	v_mov_b32_e32 v120, v0
	v_mov_b32_e32 v121, v0
	v_mov_b32_e32 v122, v0
	v_mov_b32_e32 v123, v0
	v_mov_b32_e32 v124, v0
	v_mov_b32_e32 v125, v0
	v_mov_b32_e32 v126, v0
	v_mov_b32_e32 v127, v0
	s_nop 0
.LBB0_390:
	ds_read_b128 v[144:147], v151
	ds_read_b128 v[154:157], v151 offset:1024
	ds_read_b128 v[158:161], v151 offset:2048
	ds_read_b128 v[162:165], v151 offset:3072
	ds_read_b128 v[166:169], v152
	ds_read_b128 v[170:173], v152 offset:1024
	ds_read_b128 v[174:177], v152 offset:2048
	ds_read_b128 v[178:181], v152 offset:3072
	s_add_u32 s34, s30, 0xfffc0080
	s_addc_u32 s35, s31, -1
	s_cmp_eq_u32 s63, 12
	s_cselect_b32 s37, s23, s35
	s_cselect_b32 s36, s59, s34
	s_cselect_b32 s35, s21, s62
	s_cselect_b32 s34, s60, s61
	v_lshl_add_u64 v[214:215], s[30:31], 0, v[136:137]
	s_add_i32 m0, s40, 0xc000
	ds_read_b128 v[182:185], v153
	ds_read_b128 v[186:189], v153 offset:1024
	ds_read_b128 v[190:193], v153 offset:2048
	ds_read_b128 v[194:197], v153 offset:3072
	ds_read_b128 v[198:201], v153 offset:4096
	ds_read_b128 v[202:205], v153 offset:5120
	ds_read_b128 v[206:209], v153 offset:6144
	ds_read_b128 v[210:213], v153 offset:7168
	global_load_lds_dwordx4 v[214:215], off
	v_lshl_add_u64 v[214:215], s[30:31], 0, v[138:139]
	s_add_i32 m0, s40, 0xe000
	s_nop 0
	global_load_lds_dwordx4 v[214:215], off
	s_waitcnt vmcnt(8)
	s_waitcnt lgkmcnt(0)
	s_barrier
; #define PG8_STAGE(bufoff, gbase, voff) do { _Pragma("unroll") for (int _i = 0; _i < 2; ++_i) \
;         __builtin_amdgcn_global_load_lds((const unsigned*)((const char*)(gbase) + (voff)[_i]), (PG8_LAS unsigned*)(lds + (bufoff) + ldsw + _i * 8192), 16, 0, 0); } while (0)
; #define PG8_LDA(dst, b, h) do { _Pragma("unroll") for (int m = 0; m < 4; ++m) _Pragma("unroll") for (int k = 0; k < 2; ++k) dst[m][k] = *(const PG8_LAS bf16x8*)(lds + PG8_SA(b, h) + aoff + m * 2048 + k * 1024); } while (0)
; #define PG8_MMA(ai, bj, At, Bt) do { __builtin_amdgcn_s_setprio(1); _Pragma("unroll") for (int m = 0; m < 4; ++m) _Pragma("unroll") for (int n = 0; n < 2; ++n) _Pragma("unroll") for (int k = 0; k < 2; ++k) \
;         acc[ai][bj][m][n] = __builtin_amdgcn_mfma_f32_16x16x32_bf16(Bt[n][k], At[m][k], acc[ai][bj][m][n], 0, 0, 0); __builtin_amdgcn_s_setprio(0); } while (0)
; #define PG8_WAIT_V(n) asm volatile("s_waitcnt vmcnt(" #n ")" ::: "memory")
; #define PG8_WAIT_L(n) asm volatile("s_waitcnt lgkmcnt(" #n ")" ::: "memory")
; #define PG8_BAR __builtin_amdgcn_s_barrier()
; #define PG8_SCHED __builtin_amdgcn_sched_barrier(0)
; template <class Epi, class Sched, bool ALIGN_EPI = false, bool SP2 = false>
; __device__ __forceinline__ void gemm_phase(PG8_LAS unsigned char* lds, const Gemm g, const Sched& S, const Epi& E, const int wave_id) {
;     ...
;             PG8_WAIT_V(8); PG8_WAIT_L(0); PG8_BAR; PG8_MMA(0, 0, At, B0); PG8_MMA(0, 1, At, B1); PG8_BAR; PG8_SCHED;
;             PG8_LDA(At, 0, 1); PG8_STAGE(PG8_SB(0, 0), b2, voffB); PG8_STAGE(PG8_SB(0, 1), b2 + hstep, voffB); PG8_STAGE(PG8_SA(0, 0), a2, voffA);
;             PG8_WAIT_V(8); PG8_WAIT_L(0); PG8_BAR; PG8_MMA(1, 0, At, B0); PG8_MMA(1, 1, At, B1); PG8_BAR; PG8_SCHED;
	s_setprio 1
	s_waitcnt lgkmcnt(0)
	v_mfma_f32_16x16x32_bf16 v[124:127], v[144:147], v[182:185], v[124:127]
	v_mfma_f32_16x16x32_bf16 v[120:123], v[158:161], v[182:185], v[120:123]
	v_mfma_f32_16x16x32_bf16 v[108:111], v[144:147], v[190:193], v[108:111]
	v_mfma_f32_16x16x32_bf16 v[104:107], v[158:161], v[190:193], v[104:107]
	v_mfma_f32_16x16x32_bf16 v[92:95], v[144:147], v[198:201], v[92:95]
	v_mfma_f32_16x16x32_bf16 v[88:91], v[158:161], v[198:201], v[88:91]
	v_mfma_f32_16x16x32_bf16 v[76:79], v[144:147], v[206:209], v[76:79]
	v_mfma_f32_16x16x32_bf16 v[72:75], v[158:161], v[206:209], v[72:75]
	v_mfma_f32_16x16x32_bf16 v[124:127], v[154:157], v[186:189], v[124:127]
	v_mfma_f32_16x16x32_bf16 v[120:123], v[162:165], v[186:189], v[120:123]
	v_mfma_f32_16x16x32_bf16 v[108:111], v[154:157], v[194:197], v[108:111]
	v_mfma_f32_16x16x32_bf16 v[104:107], v[162:165], v[194:197], v[104:107]
	v_mfma_f32_16x16x32_bf16 v[92:95], v[154:157], v[202:205], v[92:95]
	v_mfma_f32_16x16x32_bf16 v[88:91], v[162:165], v[202:205], v[88:91]
	v_mfma_f32_16x16x32_bf16 v[76:79], v[154:157], v[210:213], v[76:79]
	v_mfma_f32_16x16x32_bf16 v[72:75], v[162:165], v[210:213], v[72:75]
	s_setprio 0
	s_setprio 1
	v_mfma_f32_16x16x32_bf16 v[116:119], v[166:169], v[182:185], v[116:119]
	v_mfma_f32_16x16x32_bf16 v[112:115], v[174:177], v[182:185], v[112:115]
	v_mfma_f32_16x16x32_bf16 v[100:103], v[166:169], v[190:193], v[100:103]
	v_mfma_f32_16x16x32_bf16 v[96:99], v[174:177], v[190:193], v[96:99]
	v_mfma_f32_16x16x32_bf16 v[84:87], v[166:169], v[198:201], v[84:87]
	v_mfma_f32_16x16x32_bf16 v[80:83], v[174:177], v[198:201], v[80:83]
	v_mfma_f32_16x16x32_bf16 v[68:71], v[166:169], v[206:209], v[68:71]
	v_mfma_f32_16x16x32_bf16 v[64:67], v[174:177], v[206:209], v[64:67]
	v_mfma_f32_16x16x32_bf16 v[116:119], v[170:173], v[186:189], v[116:119]
	v_mfma_f32_16x16x32_bf16 v[112:115], v[178:181], v[186:189], v[112:115]
	v_mfma_f32_16x16x32_bf16 v[100:103], v[170:173], v[194:197], v[100:103]
	v_mfma_f32_16x16x32_bf16 v[96:99], v[178:181], v[194:197], v[96:99]
	v_mfma_f32_16x16x32_bf16 v[84:87], v[170:173], v[202:205], v[84:87]
	v_mfma_f32_16x16x32_bf16 v[80:83], v[178:181], v[202:205], v[80:83]
	v_mfma_f32_16x16x32_bf16 v[68:71], v[170:173], v[210:213], v[68:71]
	v_mfma_f32_16x16x32_bf16 v[64:67], v[178:181], v[210:213], v[64:67]
	s_setprio 0
	s_barrier
	s_nop 0
	s_add_i32 s64, s55, s39
	v_lshl_add_u64 v[214:215], s[34:35], 0, v[132:133]
	s_mov_b32 m0, s64
	ds_read_b128 v[182:185], v153 offset:16384
	ds_read_b128 v[186:189], v153 offset:17408
	ds_read_b128 v[190:193], v153 offset:18432
	ds_read_b128 v[194:197], v153 offset:19456
	ds_read_b128 v[198:201], v153 offset:20480
	ds_read_b128 v[202:205], v153 offset:21504
	ds_read_b128 v[206:209], v153 offset:22528
	ds_read_b128 v[210:213], v153 offset:23552
	global_load_lds_dwordx4 v[214:215], off
	s_add_i32 m0, s64, 0x2000
	s_add_u32 s64, s34, 0x40000
	v_lshl_add_u64 v[216:217], s[34:35], 0, v[128:129]
	s_addc_u32 s65, s35, 0
	s_add_i32 s66, s56, s39
	global_load_lds_dwordx4 v[216:217], off
	v_lshl_add_u64 v[218:219], s[64:65], 0, v[132:133]
	s_mov_b32 m0, s66
	v_lshl_add_u64 v[220:221], s[36:37], 0, v[130:131]
	global_load_lds_dwordx4 v[218:219], off
	v_lshl_add_u64 v[218:219], s[64:65], 0, v[128:129]
	s_add_i32 m0, s66, 0x2000
	s_nop 0
	global_load_lds_dwordx4 v[218:219], off
	v_lshl_add_u64 v[218:219], s[36:37], 0, v[134:135]
	s_mov_b32 m0, s40
	s_nop 0
	global_load_lds_dwordx4 v[218:219], off
	s_mov_b32 m0, s41
	s_nop 0
	global_load_lds_dwordx4 v[220:221], off
	s_waitcnt vmcnt(8)
	s_waitcnt lgkmcnt(0)
	s_barrier
	s_setprio 1
	s_waitcnt lgkmcnt(0)
	v_mfma_f32_16x16x32_bf16 v[60:63], v[144:147], v[182:185], v[60:63]
	v_mfma_f32_16x16x32_bf16 v[56:59], v[158:161], v[182:185], v[56:59]
	v_mfma_f32_16x16x32_bf16 v[44:47], v[144:147], v[190:193], v[44:47]
	v_mfma_f32_16x16x32_bf16 v[40:43], v[158:161], v[190:193], v[40:43]
	v_mfma_f32_16x16x32_bf16 v[28:31], v[144:147], v[198:201], v[28:31]
	v_mfma_f32_16x16x32_bf16 v[24:27], v[158:161], v[198:201], v[24:27]
	v_mfma_f32_16x16x32_bf16 v[12:15], v[144:147], v[206:209], v[12:15]
	v_mfma_f32_16x16x32_bf16 v[8:11], v[158:161], v[206:209], v[8:11]
	v_mfma_f32_16x16x32_bf16 v[60:63], v[154:157], v[186:189], v[60:63]
	v_mfma_f32_16x16x32_bf16 v[56:59], v[162:165], v[186:189], v[56:59]
	v_mfma_f32_16x16x32_bf16 v[44:47], v[154:157], v[194:197], v[44:47]
	v_mfma_f32_16x16x32_bf16 v[40:43], v[162:165], v[194:197], v[40:43]
	v_mfma_f32_16x16x32_bf16 v[28:31], v[154:157], v[202:205], v[28:31]
	v_mfma_f32_16x16x32_bf16 v[24:27], v[162:165], v[202:205], v[24:27]
	v_mfma_f32_16x16x32_bf16 v[12:15], v[154:157], v[210:213], v[12:15]
	v_mfma_f32_16x16x32_bf16 v[8:11], v[162:165], v[210:213], v[8:11]
	s_setprio 0
	s_setprio 1
	v_mfma_f32_16x16x32_bf16 v[52:55], v[166:169], v[182:185], v[52:55]
	v_mfma_f32_16x16x32_bf16 v[48:51], v[174:177], v[182:185], v[48:51]
	v_mfma_f32_16x16x32_bf16 v[36:39], v[166:169], v[190:193], v[36:39]
	v_mfma_f32_16x16x32_bf16 v[32:35], v[174:177], v[190:193], v[32:35]
	v_mfma_f32_16x16x32_bf16 v[20:23], v[166:169], v[198:201], v[20:23]
	v_mfma_f32_16x16x32_bf16 v[16:19], v[174:177], v[198:201], v[16:19]
	v_mfma_f32_16x16x32_bf16 v[4:7], v[166:169], v[206:209], v[4:7]
	v_mfma_f32_16x16x32_bf16 v[0:3], v[174:177], v[206:209], v[0:3]
	v_mfma_f32_16x16x32_bf16 v[52:55], v[170:173], v[186:189], v[52:55]
	v_mfma_f32_16x16x32_bf16 v[48:51], v[178:181], v[186:189], v[48:51]
	v_mfma_f32_16x16x32_bf16 v[36:39], v[170:173], v[194:197], v[36:39]
	v_mfma_f32_16x16x32_bf16 v[32:35], v[178:181], v[194:197], v[32:35]
	v_mfma_f32_16x16x32_bf16 v[20:23], v[170:173], v[202:205], v[20:23]
	v_mfma_f32_16x16x32_bf16 v[16:19], v[178:181], v[202:205], v[16:19]
	v_mfma_f32_16x16x32_bf16 v[4:7], v[170:173], v[210:213], v[4:7]
	v_mfma_f32_16x16x32_bf16 v[0:3], v[178:181], v[210:213], v[0:3]
	s_setprio 0
	s_barrier
; #define PG8_STAGE(bufoff, gbase, voff) do { _Pragma("unroll") for (int _i = 0; _i < 2; ++_i) \
;         __builtin_amdgcn_global_load_lds((const unsigned*)((const char*)(gbase) + (voff)[_i]), (PG8_LAS unsigned*)(lds + (bufoff) + ldsw + _i * 8192), 16, 0, 0); } while (0)
; #define PG8_LDA(dst, b, h) do { _Pragma("unroll") for (int m = 0; m < 4; ++m) _Pragma("unroll") for (int k = 0; k < 2; ++k) dst[m][k] = *(const PG8_LAS bf16x8*)(lds + PG8_SA(b, h) + aoff + m * 2048 + k * 1024); } while (0)
; #define PG8_LDB(dst, b, h) do { _Pragma("unroll") for (int n = 0; n < 2; ++n) _Pragma("unroll") for (int k = 0; k < 2; ++k) dst[n][k] = *(const PG8_LAS bf16x8*)(lds + PG8_SB(b, h) + boff + n * 2048 + k * 1024); } while (0)
; #define PG8_MMA(ai, bj, At, Bt) do { __builtin_amdgcn_s_setprio(1); _Pragma("unroll") for (int m = 0; m < 4; ++m) _Pragma("unroll") for (int n = 0; n < 2; ++n) _Pragma("unroll") for (int k = 0; k < 2; ++k) \
;         acc[ai][bj][m][n] = __builtin_amdgcn_mfma_f32_16x16x32_bf16(Bt[n][k], At[m][k], acc[ai][bj][m][n], 0, 0, 0); __builtin_amdgcn_s_setprio(0); } while (0)
; #define PG8_WAIT_V(n) asm volatile("s_waitcnt vmcnt(" #n ")" ::: "memory")
; #define PG8_WAIT_L(n) asm volatile("s_waitcnt lgkmcnt(" #n ")" ::: "memory")
; #define PG8_BAR __builtin_amdgcn_s_barrier()
; #define PG8_SCHED __builtin_amdgcn_sched_barrier(0)
; template <class Epi, class Sched, bool ALIGN_EPI = false, bool SP2 = false>
; __device__ __forceinline__ void gemm_phase(PG8_LAS unsigned char* lds, const Gemm g, const Sched& S, const Epi& E, const int wave_id) {
;     ...
;             PG8_WAIT_V(8); PG8_WAIT_L(0); PG8_BAR; PG8_MMA(1, 0, At, B0); PG8_MMA(1, 1, At, B1); PG8_BAR; PG8_SCHED;
;             PG8_LDB(B0, 1, 0); PG8_LDB(B1, 1, 1); PG8_SCHED; PG8_LDA(At, 1, 0); PG8_STAGE(PG8_SA(0, 1), a2 + hstep, voffA);
;             PG8_WAIT_V(8); PG8_WAIT_L(0); PG8_BAR; PG8_MMA(0, 0, At, B0); PG8_MMA(0, 1, At, B1); PG8_BAR; PG8_SCHED;
	s_nop 0
	s_add_i32 s64, 0, 0x18000
	s_add_i32 s65, 0, 0x1c000
	v_add_u32_e32 v162, s64, v150
	v_add_u32_e32 v178, s65, v150
	ds_read_b128 v[144:147], v162
	ds_read_b128 v[154:157], v162 offset:1024
	ds_read_b128 v[158:161], v162 offset:2048
	ds_read_b128 v[162:165], v162 offset:3072
	ds_read_b128 v[166:169], v178
	ds_read_b128 v[170:173], v178 offset:1024
	ds_read_b128 v[174:177], v178 offset:2048
	ds_read_b128 v[178:181], v178 offset:3072
	s_add_u32 s36, s36, 0x40000
	s_addc_u32 s37, s37, 0
	s_mov_b32 m0, s42
	v_lshl_add_u64 v[222:223], s[36:37], 0, v[134:135]
	ds_read_b128 v[182:185], v153 offset:32768
	ds_read_b128 v[186:189], v153 offset:33792
	ds_read_b128 v[190:193], v153 offset:34816
	ds_read_b128 v[194:197], v153 offset:35840
	ds_read_b128 v[198:201], v153 offset:36864
	ds_read_b128 v[202:205], v153 offset:37888
	ds_read_b128 v[206:209], v153 offset:38912
	ds_read_b128 v[210:213], v153 offset:39936
	global_load_lds_dwordx4 v[222:223], off
	v_lshl_add_u64 v[222:223], s[36:37], 0, v[130:131]
	s_mov_b32 m0, s43
	s_nop 0
	global_load_lds_dwordx4 v[222:223], off
	s_waitcnt vmcnt(8)
	s_waitcnt lgkmcnt(0)
	s_barrier
	s_setprio 1
	s_waitcnt lgkmcnt(0)
	v_mfma_f32_16x16x32_bf16 v[124:127], v[144:147], v[182:185], v[124:127]
	v_mfma_f32_16x16x32_bf16 v[120:123], v[158:161], v[182:185], v[120:123]
	v_mfma_f32_16x16x32_bf16 v[108:111], v[144:147], v[190:193], v[108:111]
	v_mfma_f32_16x16x32_bf16 v[104:107], v[158:161], v[190:193], v[104:107]
	v_mfma_f32_16x16x32_bf16 v[92:95], v[144:147], v[198:201], v[92:95]
	v_mfma_f32_16x16x32_bf16 v[88:91], v[158:161], v[198:201], v[88:91]
	v_mfma_f32_16x16x32_bf16 v[76:79], v[144:147], v[206:209], v[76:79]
	v_mfma_f32_16x16x32_bf16 v[72:75], v[158:161], v[206:209], v[72:75]
	v_mfma_f32_16x16x32_bf16 v[124:127], v[154:157], v[186:189], v[124:127]
	v_mfma_f32_16x16x32_bf16 v[120:123], v[162:165], v[186:189], v[120:123]
	v_mfma_f32_16x16x32_bf16 v[108:111], v[154:157], v[194:197], v[108:111]
	v_mfma_f32_16x16x32_bf16 v[104:107], v[162:165], v[194:197], v[104:107]
	v_mfma_f32_16x16x32_bf16 v[92:95], v[154:157], v[202:205], v[92:95]
	v_mfma_f32_16x16x32_bf16 v[88:91], v[162:165], v[202:205], v[88:91]
	v_mfma_f32_16x16x32_bf16 v[76:79], v[154:157], v[210:213], v[76:79]
	v_mfma_f32_16x16x32_bf16 v[72:75], v[162:165], v[210:213], v[72:75]
	s_setprio 0
	s_setprio 1
	v_mfma_f32_16x16x32_bf16 v[116:119], v[166:169], v[182:185], v[116:119]
	v_mfma_f32_16x16x32_bf16 v[112:115], v[174:177], v[182:185], v[112:115]
	v_mfma_f32_16x16x32_bf16 v[100:103], v[166:169], v[190:193], v[100:103]
	v_mfma_f32_16x16x32_bf16 v[96:99], v[174:177], v[190:193], v[96:99]
	v_mfma_f32_16x16x32_bf16 v[84:87], v[166:169], v[198:201], v[84:87]
	v_mfma_f32_16x16x32_bf16 v[80:83], v[174:177], v[198:201], v[80:83]
	v_mfma_f32_16x16x32_bf16 v[68:71], v[166:169], v[206:209], v[68:71]
	v_mfma_f32_16x16x32_bf16 v[64:67], v[174:177], v[206:209], v[64:67]
	v_mfma_f32_16x16x32_bf16 v[116:119], v[170:173], v[186:189], v[116:119]
	v_mfma_f32_16x16x32_bf16 v[112:115], v[178:181], v[186:189], v[112:115]
	v_mfma_f32_16x16x32_bf16 v[100:103], v[170:173], v[194:197], v[100:103]
	v_mfma_f32_16x16x32_bf16 v[96:99], v[178:181], v[194:197], v[96:99]
	v_mfma_f32_16x16x32_bf16 v[84:87], v[170:173], v[202:205], v[84:87]
	v_mfma_f32_16x16x32_bf16 v[80:83], v[178:181], v[202:205], v[80:83]
	v_mfma_f32_16x16x32_bf16 v[68:71], v[170:173], v[210:213], v[68:71]
	v_mfma_f32_16x16x32_bf16 v[64:67], v[178:181], v[210:213], v[64:67]
	s_setprio 0
	s_barrier
; #define PG8_STAGE(bufoff, gbase, voff) do { _Pragma("unroll") for (int _i = 0; _i < 2; ++_i) \
;         __builtin_amdgcn_global_load_lds((const unsigned*)((const char*)(gbase) + (voff)[_i]), (PG8_LAS unsigned*)(lds + (bufoff) + ldsw + _i * 8192), 16, 0, 0); } while (0)
; #define PG8_LDA(dst, b, h) do { _Pragma("unroll") for (int m = 0; m < 4; ++m) _Pragma("unroll") for (int k = 0; k < 2; ++k) dst[m][k] = *(const PG8_LAS bf16x8*)(lds + PG8_SA(b, h) + aoff + m * 2048 + k * 1024); } while (0)
; #define PG8_MMA(ai, bj, At, Bt) do { __builtin_amdgcn_s_setprio(1); _Pragma("unroll") for (int m = 0; m < 4; ++m) _Pragma("unroll") for (int n = 0; n < 2; ++n) _Pragma("unroll") for (int k = 0; k < 2; ++k) \
;         acc[ai][bj][m][n] = __builtin_amdgcn_mfma_f32_16x16x32_bf16(Bt[n][k], At[m][k], acc[ai][bj][m][n], 0, 0, 0); __builtin_amdgcn_s_setprio(0); } while (0)
; #define PG8_WAIT_V(n) asm volatile("s_waitcnt vmcnt(" #n ")" ::: "memory")
; #define PG8_WAIT_L(n) asm volatile("s_waitcnt lgkmcnt(" #n ")" ::: "memory")
; #define PG8_BAR __builtin_amdgcn_s_barrier()
; #define PG8_SCHED __builtin_amdgcn_sched_barrier(0)
; template <class Epi, class Sched, bool ALIGN_EPI = false, bool SP2 = false>
; __device__ __forceinline__ void gemm_phase(PG8_LAS unsigned char* lds, const Gemm g, const Sched& S, const Epi& E, const int wave_id) {
;     ...
;             PG8_WAIT_V(8); PG8_WAIT_L(0); PG8_BAR; PG8_MMA(0, 0, At, B0); PG8_MMA(0, 1, At, B1); PG8_BAR; PG8_SCHED;
;             PG8_LDA(At, 1, 1); PG8_STAGE(PG8_SB(1, 0), b3, voffB); PG8_STAGE(PG8_SB(1, 1), b3 + hstep, voffB); PG8_STAGE(PG8_SA(1, 0), a3, voffA);
;             PG8_WAIT_V(8); PG8_WAIT_L(0); PG8_BAR; PG8_MMA(1, 0, At, B0); PG8_MMA(1, 1, At, B1); PG8_BAR; PG8_SCHED;
;     ...
;         if constexpr (ALIGN_EPI) { if (wr == 0) PG8_BAR; }
	s_add_i32 s36, s64, s39
	v_lshl_add_u64 v[214:215], v[214:215], 0, s[16:17]
	s_mov_b32 m0, s36
	ds_read_b128 v[182:185], v153 offset:49152
	ds_read_b128 v[186:189], v153 offset:50176
	ds_read_b128 v[190:193], v153 offset:51200
	ds_read_b128 v[194:197], v153 offset:52224
	ds_read_b128 v[198:201], v153 offset:53248
	ds_read_b128 v[202:205], v153 offset:54272
	ds_read_b128 v[206:209], v153 offset:55296
	ds_read_b128 v[210:213], v153 offset:56320
	global_load_lds_dwordx4 v[214:215], off
	s_add_i32 m0, s36, 0x2000
	s_add_u32 s34, s34, 0x40080
	v_lshl_add_u64 v[214:215], v[216:217], 0, s[16:17]
	s_addc_u32 s35, s35, 0
	s_add_i32 s36, s65, s39
	global_load_lds_dwordx4 v[214:215], off
	v_lshl_add_u64 v[214:215], s[34:35], 0, v[132:133]
	s_mov_b32 m0, s36
	s_nop 0
	global_load_lds_dwordx4 v[214:215], off
	v_lshl_add_u64 v[214:215], s[34:35], 0, v[128:129]
	s_add_i32 m0, s36, 0x2000
	s_nop 0
	global_load_lds_dwordx4 v[214:215], off
	v_lshl_add_u64 v[214:215], v[218:219], 0, s[16:17]
	s_mov_b32 m0, s51
	s_nop 0
	global_load_lds_dwordx4 v[214:215], off
	v_lshl_add_u64 v[214:215], v[220:221], 0, s[16:17]
	s_mov_b32 m0, s52
	s_nop 0
	global_load_lds_dwordx4 v[214:215], off
	s_waitcnt vmcnt(8)
	s_waitcnt lgkmcnt(0)
	s_barrier
	s_setprio 1
	s_waitcnt lgkmcnt(0)
	v_mfma_f32_16x16x32_bf16 v[60:63], v[144:147], v[182:185], v[60:63]
	v_mfma_f32_16x16x32_bf16 v[56:59], v[158:161], v[182:185], v[56:59]
	v_mfma_f32_16x16x32_bf16 v[44:47], v[144:147], v[190:193], v[44:47]
	v_mfma_f32_16x16x32_bf16 v[40:43], v[158:161], v[190:193], v[40:43]
	v_mfma_f32_16x16x32_bf16 v[28:31], v[144:147], v[198:201], v[28:31]
	v_mfma_f32_16x16x32_bf16 v[24:27], v[158:161], v[198:201], v[24:27]
	v_mfma_f32_16x16x32_bf16 v[12:15], v[144:147], v[206:209], v[12:15]
	v_mfma_f32_16x16x32_bf16 v[8:11], v[158:161], v[206:209], v[8:11]
	v_mfma_f32_16x16x32_bf16 v[60:63], v[154:157], v[186:189], v[60:63]
	v_mfma_f32_16x16x32_bf16 v[56:59], v[162:165], v[186:189], v[56:59]
	v_mfma_f32_16x16x32_bf16 v[44:47], v[154:157], v[194:197], v[44:47]
	v_mfma_f32_16x16x32_bf16 v[40:43], v[162:165], v[194:197], v[40:43]
	v_mfma_f32_16x16x32_bf16 v[28:31], v[154:157], v[202:205], v[28:31]
	v_mfma_f32_16x16x32_bf16 v[24:27], v[162:165], v[202:205], v[24:27]
	v_mfma_f32_16x16x32_bf16 v[12:15], v[154:157], v[210:213], v[12:15]
	v_mfma_f32_16x16x32_bf16 v[8:11], v[162:165], v[210:213], v[8:11]
	s_setprio 0
	s_setprio 1
	v_mfma_f32_16x16x32_bf16 v[52:55], v[166:169], v[182:185], v[52:55]
	v_mfma_f32_16x16x32_bf16 v[48:51], v[174:177], v[182:185], v[48:51]
	v_mfma_f32_16x16x32_bf16 v[36:39], v[166:169], v[190:193], v[36:39]
	v_mfma_f32_16x16x32_bf16 v[32:35], v[174:177], v[190:193], v[32:35]
	v_mfma_f32_16x16x32_bf16 v[20:23], v[166:169], v[198:201], v[20:23]
	v_mfma_f32_16x16x32_bf16 v[16:19], v[174:177], v[198:201], v[16:19]
	v_mfma_f32_16x16x32_bf16 v[4:7], v[166:169], v[206:209], v[4:7]
	v_mfma_f32_16x16x32_bf16 v[0:3], v[174:177], v[206:209], v[0:3]
	v_mfma_f32_16x16x32_bf16 v[52:55], v[170:173], v[186:189], v[52:55]
	v_mfma_f32_16x16x32_bf16 v[48:51], v[178:181], v[186:189], v[48:51]
	v_mfma_f32_16x16x32_bf16 v[36:39], v[170:173], v[194:197], v[36:39]
	v_mfma_f32_16x16x32_bf16 v[32:35], v[178:181], v[194:197], v[32:35]
	v_mfma_f32_16x16x32_bf16 v[20:23], v[170:173], v[202:205], v[20:23]
	v_mfma_f32_16x16x32_bf16 v[16:19], v[178:181], v[202:205], v[16:19]
	v_mfma_f32_16x16x32_bf16 v[4:7], v[170:173], v[210:213], v[4:7]
	v_mfma_f32_16x16x32_bf16 v[0:3], v[178:181], v[210:213], v[0:3]
	s_setprio 0
	s_barrier
	s_add_i32 s63, s63, 2
	s_add_u32 s30, s30, 0x100
	s_addc_u32 s31, s31, 0
	s_add_u32 s61, s61, 0x100
	s_addc_u32 s62, s62, 0
	s_cmp_gt_u32 s63, 13
	s_cbranch_scc0 .LBB0_390
	s_and_b64 vcc, exec, s[18:19]
	s_cbranch_vccz .LBB0_393
	s_barrier

; #define PG8_STAGE(bufoff, gbase, voff) do { _Pragma("unroll") for (int _i = 0; _i < 2; ++_i) \
;         __builtin_amdgcn_global_load_lds((const unsigned*)((const char*)(gbase) + (voff)[_i]), (PG8_LAS unsigned*)(lds + (bufoff) + ldsw + _i * 8192), 16, 0, 0); } while (0)
; #define PG8_LDA(dst, b, h) do { _Pragma("unroll") for (int m = 0; m < 4; ++m) _Pragma("unroll") for (int k = 0; k < 2; ++k) dst[m][k] = *(const PG8_LAS bf16x8*)(lds + PG8_SA(b, h) + aoff + m * 2048 + k * 1024); } while (0)
; #define PG8_LDB(dst, b, h) do { _Pragma("unroll") for (int n = 0; n < 2; ++n) _Pragma("unroll") for (int k = 0; k < 2; ++k) dst[n][k] = *(const PG8_LAS bf16x8*)(lds + PG8_SB(b, h) + boff + n * 2048 + k * 1024); } while (0)
; #define PG8_WAIT_V(n) asm volatile("s_waitcnt vmcnt(" #n ")" ::: "memory")
; #define PG8_WAIT_L(n) asm volatile("s_waitcnt lgkmcnt(" #n ")" ::: "memory")
; #define PG8_BAR __builtin_amdgcn_s_barrier()
; #define PG8_SCHED __builtin_amdgcn_sched_barrier(0)
; template <class Epi, class Sched, bool ALIGN_EPI = false, bool SP2 = false>
; __device__ __forceinline__ void gemm_phase(PG8_LAS unsigned char* lds, const Gemm g, const Sched& S, const Epi& E, const int wave_id) {
;     ...
;         const bool has_next = S.next(ui + 1, nxt);
;         const char* nA = has_next ? (const char*)g.A + (size_t)nxt.pm * tstep : cA; const char* nB = has_next ? (const char*)g.Bt + (size_t)nxt.pn * tstep : cB;
;         for (int t = 0; t < nt; t += 2) {
;             const bool last = (t == nt - 2);
;             const char* a1 = cA + (size_t)(t + 1) * kstep;
;             const char* a2 = last ? nA : cA + (size_t)(t + 2) * kstep; const char* b2 = last ? nB : cB + (size_t)(t + 2) * kstep;
;             const char* a3 = a2 + kstep; const char* b3 = b2 + kstep;
;             if (last && has_next) S.a_ready(nxt);
;             if constexpr (SP2) {
;             PG8_LDB(B0, 0, 0); PG8_LDB(B1, 0, 1); PG8_SCHED; PG8_LDA(At, 0, 0); PG8_STAGE(PG8_SA(1, 1), a1 + hstep, voffA);
;             PG8_WAIT_V(8); PG8_WAIT_L(0); PG8_BAR; PG8_MMA(0, 0, At, B0); PG8_MMA(0, 1, At, B1); PG8_BAR; PG8_SCHED;
;     ...
; #pragma unroll
;         for (int a = 0; a < 2; ++a)
; #pragma unroll
;             for (int b = 0; b < 2; ++b)
; #pragma unroll
;                 for (int m = 0; m < 4; ++m)
; #pragma unroll
;                     for (int n = 0; n < 2; ++n) acc[a][b][m][n] = (f32x4){0.f, 0.f, 0.f, 0.f};
.LBB0_694:
	s_ashr_i32 s61, s60, 31
	s_lshl_b64 s[16:17], s[60:61], 19
	s_add_u32 s62, s80, s16
	s_addc_u32 s63, s83, s17
	s_and_b64 s[16:17], s[8:9], exec
	s_cselect_b32 s11, s63, s13
	s_cselect_b32 s61, s62, s12
	s_ashr_i32 s59, s58, 31
	s_lshl_b64 s[16:17], s[58:59], 19
	s_add_u32 s64, s22, s16
	s_addc_u32 s65, s23, s17
	s_and_b64 s[16:17], s[8:9], exec
	s_cselect_b32 s59, s65, s15
	s_cselect_b32 s67, s64, s14
	s_add_u32 s12, s12, 0x40080
	s_addc_u32 s13, s13, 0
	s_add_u32 s68, s14, 0x100
	v_mov_b32_e32 v0, 0
	s_addc_u32 s69, s15, 0
	s_mov_b32 s72, -2
	v_mov_b32_e32 v1, v0
	v_mov_b32_e32 v2, v0
	v_mov_b32_e32 v3, v0
	v_mov_b32_e32 v4, v0
	v_mov_b32_e32 v5, v0
	v_mov_b32_e32 v6, v0
	v_mov_b32_e32 v7, v0
	v_mov_b32_e32 v8, v0
	v_mov_b32_e32 v9, v0
	v_mov_b32_e32 v10, v0
	v_mov_b32_e32 v11, v0
	v_mov_b32_e32 v12, v0
	v_mov_b32_e32 v13, v0
	v_mov_b32_e32 v14, v0
	v_mov_b32_e32 v15, v0
	v_mov_b32_e32 v16, v0
	v_mov_b32_e32 v17, v0
	v_mov_b32_e32 v18, v0
	v_mov_b32_e32 v19, v0
	v_mov_b32_e32 v20, v0
	v_mov_b32_e32 v21, v0
	v_mov_b32_e32 v22, v0
	v_mov_b32_e32 v23, v0
	v_mov_b32_e32 v24, v0
	v_mov_b32_e32 v25, v0
	v_mov_b32_e32 v26, v0
	v_mov_b32_e32 v27, v0
	v_mov_b32_e32 v28, v0
	v_mov_b32_e32 v29, v0
	v_mov_b32_e32 v30, v0
	v_mov_b32_e32 v31, v0
	v_mov_b32_e32 v68, v0
	v_mov_b32_e32 v69, v0
	v_mov_b32_e32 v70, v0
	v_mov_b32_e32 v71, v0
	v_mov_b32_e32 v84, v0
	v_mov_b32_e32 v85, v0
	v_mov_b32_e32 v86, v0
	v_mov_b32_e32 v87, v0
	v_mov_b32_e32 v72, v0
	v_mov_b32_e32 v73, v0
	v_mov_b32_e32 v74, v0
	v_mov_b32_e32 v75, v0
	v_mov_b32_e32 v92, v0
	v_mov_b32_e32 v93, v0
	v_mov_b32_e32 v94, v0
	v_mov_b32_e32 v95, v0
	v_mov_b32_e32 v88, v0
	v_mov_b32_e32 v89, v0
	v_mov_b32_e32 v90, v0
	v_mov_b32_e32 v91, v0
	v_mov_b32_e32 v100, v0
	v_mov_b32_e32 v101, v0
	v_mov_b32_e32 v102, v0
	v_mov_b32_e32 v103, v0
	v_mov_b32_e32 v96, v0
	v_mov_b32_e32 v97, v0
	v_mov_b32_e32 v98, v0
	v_mov_b32_e32 v99, v0
	v_mov_b32_e32 v108, v0
	v_mov_b32_e32 v109, v0
	v_mov_b32_e32 v110, v0
	v_mov_b32_e32 v111, v0
	v_mov_b32_e32 v44, v0
	v_mov_b32_e32 v45, v0
	v_mov_b32_e32 v46, v0
	v_mov_b32_e32 v47, v0
	v_mov_b32_e32 v48, v0
	v_mov_b32_e32 v49, v0
	v_mov_b32_e32 v50, v0
	v_mov_b32_e32 v51, v0
	v_mov_b32_e32 v52, v0
	v_mov_b32_e32 v53, v0
	v_mov_b32_e32 v54, v0
	v_mov_b32_e32 v55, v0
	v_mov_b32_e32 v56, v0
	v_mov_b32_e32 v57, v0
	v_mov_b32_e32 v58, v0
	v_mov_b32_e32 v59, v0
	v_mov_b32_e32 v60, v0
	v_mov_b32_e32 v61, v0
	v_mov_b32_e32 v62, v0
	v_mov_b32_e32 v63, v0
	v_mov_b32_e32 v64, v0
	v_mov_b32_e32 v65, v0
	v_mov_b32_e32 v66, v0
	v_mov_b32_e32 v67, v0
	v_mov_b32_e32 v76, v0
	v_mov_b32_e32 v77, v0
	v_mov_b32_e32 v78, v0
	v_mov_b32_e32 v79, v0
	v_mov_b32_e32 v80, v0
	v_mov_b32_e32 v81, v0
	v_mov_b32_e32 v82, v0
	v_mov_b32_e32 v83, v0
	v_mov_b32_e32 v104, v0
	v_mov_b32_e32 v105, v0
	v_mov_b32_e32 v106, v0
	v_mov_b32_e32 v107, v0
	v_mov_b32_e32 v112, v0
	v_mov_b32_e32 v113, v0
	v_mov_b32_e32 v114, v0
	v_mov_b32_e32 v115, v0
	v_mov_b32_e32 v116, v0
	v_mov_b32_e32 v117, v0
	v_mov_b32_e32 v118, v0
	v_mov_b32_e32 v119, v0
	v_mov_b32_e32 v120, v0
	v_mov_b32_e32 v121, v0
	v_mov_b32_e32 v122, v0
	v_mov_b32_e32 v123, v0
	v_mov_b32_e32 v124, v0
	v_mov_b32_e32 v125, v0
	v_mov_b32_e32 v126, v0
	v_mov_b32_e32 v127, v0
	v_mov_b32_e32 v128, v0
	v_mov_b32_e32 v129, v0
	v_mov_b32_e32 v130, v0
	v_mov_b32_e32 v131, v0
	v_mov_b32_e32 v132, v0
	v_mov_b32_e32 v133, v0
	v_mov_b32_e32 v134, v0
	v_mov_b32_e32 v135, v0
	v_mov_b32_e32 v136, v0
	v_mov_b32_e32 v137, v0
	v_mov_b32_e32 v138, v0
	v_mov_b32_e32 v139, v0
	s_nop 0
.LBB0_695:
	s_add_u32 s14, s12, 0xfffc0080
	s_addc_u32 s15, s13, -1
	s_add_i32 s73, 0, 0x10000
	s_cmp_eq_u32 s72, 12
	s_cselect_b32 s17, s11, s15
	s_cselect_b32 s16, s61, s14
	s_cselect_b32 s15, s59, s69
	s_cselect_b32 s14, s67, s68
	s_add_i32 s34, 0, 0x14000
	v_add_u32_e32 v156, s73, v168
	v_add_u32_e32 v164, s34, v168
	ds_read_b128 v[32:35], v156
	ds_read_b128 v[36:39], v156 offset:1024
	ds_read_b128 v[40:43], v156 offset:2048
	ds_read_b128 v[156:159], v156 offset:3072
	ds_read_b128 v[160:163], v164
	ds_read_b128 v[170:173], v164 offset:1024
	ds_read_b128 v[174:177], v164 offset:2048
	ds_read_b128 v[178:181], v164 offset:3072
	v_lshl_add_u64 v[164:165], s[12:13], 0, v[152:153]
	s_add_i32 m0, s84, 0xc000
	ds_read_b128 v[182:185], v169
	ds_read_b128 v[186:189], v169 offset:1024
	ds_read_b128 v[190:193], v169 offset:2048
	ds_read_b128 v[194:197], v169 offset:3072
	ds_read_b128 v[202:205], v169 offset:4096
	ds_read_b128 v[206:209], v169 offset:5120
	ds_read_b128 v[212:215], v169 offset:6144
	ds_read_b128 v[216:219], v169 offset:7168
	global_load_lds_dwordx4 v[164:165], off
	v_lshl_add_u64 v[164:165], s[12:13], 0, v[154:155]
	s_add_i32 m0, s84, 0xe000
	s_nop 0
	global_load_lds_dwordx4 v[164:165], off
	s_waitcnt vmcnt(8)
	s_waitcnt lgkmcnt(0)
	s_barrier
; #define PG8_STAGE(bufoff, gbase, voff) do { _Pragma("unroll") for (int _i = 0; _i < 2; ++_i) \
;         __builtin_amdgcn_global_load_lds((const unsigned*)((const char*)(gbase) + (voff)[_i]), (PG8_LAS unsigned*)(lds + (bufoff) + ldsw + _i * 8192), 16, 0, 0); } while (0)
; #define PG8_LDA(dst, b, h) do { _Pragma("unroll") for (int m = 0; m < 4; ++m) _Pragma("unroll") for (int k = 0; k < 2; ++k) dst[m][k] = *(const PG8_LAS bf16x8*)(lds + PG8_SA(b, h) + aoff + m * 2048 + k * 1024); } while (0)
; #define PG8_MMA(ai, bj, At, Bt) do { __builtin_amdgcn_s_setprio(1); _Pragma("unroll") for (int m = 0; m < 4; ++m) _Pragma("unroll") for (int n = 0; n < 2; ++n) _Pragma("unroll") for (int k = 0; k < 2; ++k) \
;         acc[ai][bj][m][n] = __builtin_amdgcn_mfma_f32_16x16x32_bf16(Bt[n][k], At[m][k], acc[ai][bj][m][n], 0, 0, 0); __builtin_amdgcn_s_setprio(0); } while (0)
; #define PG8_WAIT_V(n) asm volatile("s_waitcnt vmcnt(" #n ")" ::: "memory")
; #define PG8_WAIT_L(n) asm volatile("s_waitcnt lgkmcnt(" #n ")" ::: "memory")
; #define PG8_BAR __builtin_amdgcn_s_barrier()
; #define PG8_SCHED __builtin_amdgcn_sched_barrier(0)
; template <class Epi, class Sched, bool ALIGN_EPI = false, bool SP2 = false>
; __device__ __forceinline__ void gemm_phase(PG8_LAS unsigned char* lds, const Gemm g, const Sched& S, const Epi& E, const int wave_id) {
;     ...
;             PG8_WAIT_V(8); PG8_WAIT_L(0); PG8_BAR; PG8_MMA(0, 0, At, B0); PG8_MMA(0, 1, At, B1); PG8_BAR; PG8_SCHED;
;             PG8_LDA(At, 0, 1); PG8_STAGE(PG8_SB(0, 0), b2, voffB); PG8_STAGE(PG8_SB(0, 1), b2 + hstep, voffB); PG8_STAGE(PG8_SA(0, 0), a2, voffA);
;             PG8_WAIT_V(8); PG8_WAIT_L(0); PG8_BAR; PG8_MMA(1, 0, At, B0); PG8_MMA(1, 1, At, B1); PG8_BAR; PG8_SCHED;
	s_setprio 1
	s_waitcnt lgkmcnt(0)
	v_mfma_f32_16x16x32_bf16 v[136:139], v[32:35], v[182:185], v[136:139]
	v_mfma_f32_16x16x32_bf16 v[132:135], v[40:43], v[182:185], v[132:135]
	v_mfma_f32_16x16x32_bf16 v[128:131], v[32:35], v[190:193], v[128:131]
	v_mfma_f32_16x16x32_bf16 v[124:127], v[40:43], v[190:193], v[124:127]
	v_mfma_f32_16x16x32_bf16 v[120:123], v[32:35], v[202:205], v[120:123]
	v_mfma_f32_16x16x32_bf16 v[116:119], v[40:43], v[202:205], v[116:119]
	v_mfma_f32_16x16x32_bf16 v[112:115], v[32:35], v[212:215], v[112:115]
	v_mfma_f32_16x16x32_bf16 v[104:107], v[40:43], v[212:215], v[104:107]
	v_mfma_f32_16x16x32_bf16 v[136:139], v[36:39], v[186:189], v[136:139]
	v_mfma_f32_16x16x32_bf16 v[132:135], v[156:159], v[186:189], v[132:135]
	v_mfma_f32_16x16x32_bf16 v[128:131], v[36:39], v[194:197], v[128:131]
	v_mfma_f32_16x16x32_bf16 v[124:127], v[156:159], v[194:197], v[124:127]
	v_mfma_f32_16x16x32_bf16 v[120:123], v[36:39], v[206:209], v[120:123]
	v_mfma_f32_16x16x32_bf16 v[116:119], v[156:159], v[206:209], v[116:119]
	v_mfma_f32_16x16x32_bf16 v[112:115], v[36:39], v[216:219], v[112:115]
	v_mfma_f32_16x16x32_bf16 v[104:107], v[156:159], v[216:219], v[104:107]
	s_setprio 0
	s_setprio 1
	v_mfma_f32_16x16x32_bf16 v[80:83], v[160:163], v[182:185], v[80:83]
	v_mfma_f32_16x16x32_bf16 v[76:79], v[174:177], v[182:185], v[76:79]
	v_mfma_f32_16x16x32_bf16 v[64:67], v[160:163], v[190:193], v[64:67]
	v_mfma_f32_16x16x32_bf16 v[60:63], v[174:177], v[190:193], v[60:63]
	v_mfma_f32_16x16x32_bf16 v[56:59], v[160:163], v[202:205], v[56:59]
	v_mfma_f32_16x16x32_bf16 v[52:55], v[174:177], v[202:205], v[52:55]
	v_mfma_f32_16x16x32_bf16 v[48:51], v[160:163], v[212:215], v[48:51]
	v_mfma_f32_16x16x32_bf16 v[44:47], v[174:177], v[212:215], v[44:47]
	v_mfma_f32_16x16x32_bf16 v[80:83], v[170:173], v[186:189], v[80:83]
	v_mfma_f32_16x16x32_bf16 v[76:79], v[178:181], v[186:189], v[76:79]
	v_mfma_f32_16x16x32_bf16 v[64:67], v[170:173], v[194:197], v[64:67]
	v_mfma_f32_16x16x32_bf16 v[60:63], v[178:181], v[194:197], v[60:63]
	v_mfma_f32_16x16x32_bf16 v[56:59], v[170:173], v[206:209], v[56:59]
	v_mfma_f32_16x16x32_bf16 v[52:55], v[178:181], v[206:209], v[52:55]
	v_mfma_f32_16x16x32_bf16 v[48:51], v[170:173], v[216:219], v[48:51]
	v_mfma_f32_16x16x32_bf16 v[44:47], v[178:181], v[216:219], v[44:47]
	s_setprio 0
	s_barrier
	s_nop 0
	s_add_i32 s73, s73, s25
	v_lshl_add_u64 v[164:165], s[14:15], 0, v[146:147]
	s_mov_b32 m0, s73
	ds_read_b128 v[182:185], v169 offset:16384
	ds_read_b128 v[186:189], v169 offset:17408
	ds_read_b128 v[190:193], v169 offset:18432
	ds_read_b128 v[194:197], v169 offset:19456
	ds_read_b128 v[202:205], v169 offset:20480
	ds_read_b128 v[206:209], v169 offset:21504
	ds_read_b128 v[212:215], v169 offset:22528
	ds_read_b128 v[216:219], v169 offset:23552
	global_load_lds_dwordx4 v[164:165], off
	s_add_i32 m0, s73, 0x2000
	s_add_u32 vcc_lo, s14, 0x40000
	v_lshl_add_u64 v[198:199], s[14:15], 0, v[150:151]
	s_addc_u32 vcc_hi, s15, 0
	s_add_i32 s34, s34, s25
	global_load_lds_dwordx4 v[198:199], off
	v_lshl_add_u64 v[210:211], vcc, 0, v[146:147]
	s_mov_b32 m0, s34
	v_lshl_add_u64 v[224:225], s[16:17], 0, v[148:149]
	global_load_lds_dwordx4 v[210:211], off
	v_lshl_add_u64 v[210:211], vcc, 0, v[150:151]
	s_add_i32 m0, s34, 0x2000
	s_nop 0
	global_load_lds_dwordx4 v[210:211], off
	v_lshl_add_u64 v[210:211], s[16:17], 0, v[144:145]
	s_mov_b32 m0, s84
	s_nop 0
	global_load_lds_dwordx4 v[210:211], off
	s_mov_b32 m0, s85
	s_nop 0
	global_load_lds_dwordx4 v[224:225], off
	s_waitcnt vmcnt(8)
	s_waitcnt lgkmcnt(0)
	s_barrier
	s_setprio 1
	s_waitcnt lgkmcnt(0)
	v_mfma_f32_16x16x32_bf16 v[108:111], v[32:35], v[182:185], v[108:111]
	v_mfma_f32_16x16x32_bf16 v[96:99], v[40:43], v[182:185], v[96:99]
	v_mfma_f32_16x16x32_bf16 v[100:103], v[32:35], v[190:193], v[100:103]
	v_mfma_f32_16x16x32_bf16 v[88:91], v[40:43], v[190:193], v[88:91]
	v_mfma_f32_16x16x32_bf16 v[92:95], v[32:35], v[202:205], v[92:95]
	v_mfma_f32_16x16x32_bf16 v[72:75], v[40:43], v[202:205], v[72:75]
	v_mfma_f32_16x16x32_bf16 v[32:35], v[32:35], v[212:215], v[84:87]
	v_mfma_f32_16x16x32_bf16 v[108:111], v[36:39], v[186:189], v[108:111]
	v_mfma_f32_16x16x32_bf16 v[96:99], v[156:159], v[186:189], v[96:99]
	v_mfma_f32_16x16x32_bf16 v[100:103], v[36:39], v[194:197], v[100:103]
	v_mfma_f32_16x16x32_bf16 v[88:91], v[156:159], v[194:197], v[88:91]
	v_mfma_f32_16x16x32_bf16 v[92:95], v[36:39], v[206:209], v[92:95]
	v_mfma_f32_16x16x32_bf16 v[72:75], v[156:159], v[206:209], v[72:75]
	v_mfma_f32_16x16x32_bf16 v[32:35], v[36:39], v[216:219], v[32:35]
	v_mfma_f32_16x16x32_bf16 v[36:39], v[40:43], v[212:215], v[68:71]
	v_mfma_f32_16x16x32_bf16 v[36:39], v[156:159], v[216:219], v[36:39]
	s_setprio 0
	s_setprio 1
	v_mfma_f32_16x16x32_bf16 v[28:31], v[160:163], v[182:185], v[28:31]
	v_mfma_f32_16x16x32_bf16 v[24:27], v[174:177], v[182:185], v[24:27]
	v_mfma_f32_16x16x32_bf16 v[20:23], v[160:163], v[190:193], v[20:23]
	v_mfma_f32_16x16x32_bf16 v[16:19], v[174:177], v[190:193], v[16:19]
	v_mfma_f32_16x16x32_bf16 v[12:15], v[160:163], v[202:205], v[12:15]
	v_mfma_f32_16x16x32_bf16 v[8:11], v[174:177], v[202:205], v[8:11]
	v_mfma_f32_16x16x32_bf16 v[4:7], v[160:163], v[212:215], v[4:7]
	v_mfma_f32_16x16x32_bf16 v[0:3], v[174:177], v[212:215], v[0:3]
	v_mfma_f32_16x16x32_bf16 v[28:31], v[170:173], v[186:189], v[28:31]
	v_mfma_f32_16x16x32_bf16 v[24:27], v[178:181], v[186:189], v[24:27]
	v_mfma_f32_16x16x32_bf16 v[20:23], v[170:173], v[194:197], v[20:23]
	v_mfma_f32_16x16x32_bf16 v[16:19], v[178:181], v[194:197], v[16:19]
	v_mfma_f32_16x16x32_bf16 v[12:15], v[170:173], v[206:209], v[12:15]
	v_mfma_f32_16x16x32_bf16 v[8:11], v[178:181], v[206:209], v[8:11]
	v_mfma_f32_16x16x32_bf16 v[4:7], v[170:173], v[216:219], v[4:7]
	v_mfma_f32_16x16x32_bf16 v[0:3], v[178:181], v[216:219], v[0:3]
	s_setprio 0
	s_barrier
; #define PG8_STAGE(bufoff, gbase, voff) do { _Pragma("unroll") for (int _i = 0; _i < 2; ++_i) \
;         __builtin_amdgcn_global_load_lds((const unsigned*)((const char*)(gbase) + (voff)[_i]), (PG8_LAS unsigned*)(lds + (bufoff) + ldsw + _i * 8192), 16, 0, 0); } while (0)
; #define PG8_LDA(dst, b, h) do { _Pragma("unroll") for (int m = 0; m < 4; ++m) _Pragma("unroll") for (int k = 0; k < 2; ++k) dst[m][k] = *(const PG8_LAS bf16x8*)(lds + PG8_SA(b, h) + aoff + m * 2048 + k * 1024); } while (0)
; #define PG8_LDB(dst, b, h) do { _Pragma("unroll") for (int n = 0; n < 2; ++n) _Pragma("unroll") for (int k = 0; k < 2; ++k) dst[n][k] = *(const PG8_LAS bf16x8*)(lds + PG8_SB(b, h) + boff + n * 2048 + k * 1024); } while (0)
; #define PG8_MMA(ai, bj, At, Bt) do { __builtin_amdgcn_s_setprio(1); _Pragma("unroll") for (int m = 0; m < 4; ++m) _Pragma("unroll") for (int n = 0; n < 2; ++n) _Pragma("unroll") for (int k = 0; k < 2; ++k) \
;         acc[ai][bj][m][n] = __builtin_amdgcn_mfma_f32_16x16x32_bf16(Bt[n][k], At[m][k], acc[ai][bj][m][n], 0, 0, 0); __builtin_amdgcn_s_setprio(0); } while (0)
; #define PG8_WAIT_V(n) asm volatile("s_waitcnt vmcnt(" #n ")" ::: "memory")
; #define PG8_WAIT_L(n) asm volatile("s_waitcnt lgkmcnt(" #n ")" ::: "memory")
; #define PG8_BAR __builtin_amdgcn_s_barrier()
; #define PG8_SCHED __builtin_amdgcn_sched_barrier(0)
; template <class Epi, class Sched, bool ALIGN_EPI = false, bool SP2 = false>
; __device__ __forceinline__ void gemm_phase(PG8_LAS unsigned char* lds, const Gemm g, const Sched& S, const Epi& E, const int wave_id) {
;     ...
;             PG8_WAIT_V(8); PG8_WAIT_L(0); PG8_BAR; PG8_MMA(1, 0, At, B0); PG8_MMA(1, 1, At, B1); PG8_BAR; PG8_SCHED;
;             PG8_LDB(B0, 1, 0); PG8_LDB(B1, 1, 1); PG8_SCHED; PG8_LDA(At, 1, 0); PG8_STAGE(PG8_SA(0, 1), a2 + hstep, voffA);
;             PG8_WAIT_V(8); PG8_WAIT_L(0); PG8_BAR; PG8_MMA(0, 0, At, B0); PG8_MMA(0, 1, At, B1); PG8_BAR; PG8_SCHED;
	s_nop 0
	s_add_i32 s34, 0, 0x18000
	v_add_u32_e32 v84, s34, v168
	s_add_i32 s73, 0, 0x1c000
	ds_read_b128 v[40:43], v84
	ds_read_b128 v[68:71], v84 offset:1024
	ds_read_b128 v[156:159], v84 offset:2048
	ds_read_b128 v[160:163], v84 offset:3072
	v_add_u32_e32 v84, s73, v168
	ds_read_b128 v[170:173], v84
	ds_read_b128 v[174:177], v84 offset:1024
	ds_read_b128 v[178:181], v84 offset:2048
	ds_read_b128 v[182:185], v84 offset:3072
	s_add_u32 s16, s16, 0x40000
	s_addc_u32 s17, s17, 0
	s_mov_b32 m0, s86
	v_lshl_add_u64 v[220:221], s[16:17], 0, v[144:145]
	ds_read_b128 v[84:87], v169 offset:32768
	ds_read_b128 v[186:189], v169 offset:33792
	ds_read_b128 v[190:193], v169 offset:34816
	ds_read_b128 v[194:197], v169 offset:35840
	ds_read_b128 v[202:205], v169 offset:36864
	ds_read_b128 v[206:209], v169 offset:37888
	ds_read_b128 v[212:215], v169 offset:38912
	ds_read_b128 v[216:219], v169 offset:39936
	global_load_lds_dwordx4 v[220:221], off
	v_lshl_add_u64 v[220:221], s[16:17], 0, v[148:149]
	s_mov_b32 m0, s87
	s_nop 0
	global_load_lds_dwordx4 v[220:221], off
	s_waitcnt vmcnt(8)
	s_waitcnt lgkmcnt(0)
	s_barrier
	s_setprio 1
	s_waitcnt lgkmcnt(0)
	v_mfma_f32_16x16x32_bf16 v[136:139], v[40:43], v[84:87], v[136:139]
	v_mfma_f32_16x16x32_bf16 v[132:135], v[156:159], v[84:87], v[132:135]
	v_mfma_f32_16x16x32_bf16 v[128:131], v[40:43], v[190:193], v[128:131]
	v_mfma_f32_16x16x32_bf16 v[124:127], v[156:159], v[190:193], v[124:127]
	v_mfma_f32_16x16x32_bf16 v[120:123], v[40:43], v[202:205], v[120:123]
	v_mfma_f32_16x16x32_bf16 v[116:119], v[156:159], v[202:205], v[116:119]
	v_mfma_f32_16x16x32_bf16 v[112:115], v[40:43], v[212:215], v[112:115]
	v_mfma_f32_16x16x32_bf16 v[104:107], v[156:159], v[212:215], v[104:107]
	v_mfma_f32_16x16x32_bf16 v[136:139], v[68:71], v[186:189], v[136:139]
	v_mfma_f32_16x16x32_bf16 v[132:135], v[160:163], v[186:189], v[132:135]
	v_mfma_f32_16x16x32_bf16 v[128:131], v[68:71], v[194:197], v[128:131]
	v_mfma_f32_16x16x32_bf16 v[124:127], v[160:163], v[194:197], v[124:127]
	v_mfma_f32_16x16x32_bf16 v[120:123], v[68:71], v[206:209], v[120:123]
	v_mfma_f32_16x16x32_bf16 v[116:119], v[160:163], v[206:209], v[116:119]
	v_mfma_f32_16x16x32_bf16 v[112:115], v[68:71], v[216:219], v[112:115]
	v_mfma_f32_16x16x32_bf16 v[104:107], v[160:163], v[216:219], v[104:107]
	s_setprio 0
	s_setprio 1
	v_mfma_f32_16x16x32_bf16 v[80:83], v[170:173], v[84:87], v[80:83]
	v_mfma_f32_16x16x32_bf16 v[76:79], v[178:181], v[84:87], v[76:79]
	v_mfma_f32_16x16x32_bf16 v[64:67], v[170:173], v[190:193], v[64:67]
	v_mfma_f32_16x16x32_bf16 v[60:63], v[178:181], v[190:193], v[60:63]
	v_mfma_f32_16x16x32_bf16 v[56:59], v[170:173], v[202:205], v[56:59]
	v_mfma_f32_16x16x32_bf16 v[52:55], v[178:181], v[202:205], v[52:55]
	v_mfma_f32_16x16x32_bf16 v[48:51], v[170:173], v[212:215], v[48:51]
	v_mfma_f32_16x16x32_bf16 v[44:47], v[178:181], v[212:215], v[44:47]
	v_mfma_f32_16x16x32_bf16 v[80:83], v[174:177], v[186:189], v[80:83]
	v_mfma_f32_16x16x32_bf16 v[76:79], v[182:185], v[186:189], v[76:79]
	v_mfma_f32_16x16x32_bf16 v[64:67], v[174:177], v[194:197], v[64:67]
	v_mfma_f32_16x16x32_bf16 v[60:63], v[182:185], v[194:197], v[60:63]
	v_mfma_f32_16x16x32_bf16 v[56:59], v[174:177], v[206:209], v[56:59]
	v_mfma_f32_16x16x32_bf16 v[52:55], v[182:185], v[206:209], v[52:55]
	v_mfma_f32_16x16x32_bf16 v[48:51], v[174:177], v[216:219], v[48:51]
	v_mfma_f32_16x16x32_bf16 v[44:47], v[182:185], v[216:219], v[44:47]
	s_setprio 0
	s_barrier
; #define PG8_STAGE(bufoff, gbase, voff) do { _Pragma("unroll") for (int _i = 0; _i < 2; ++_i) \
;         __builtin_amdgcn_global_load_lds((const unsigned*)((const char*)(gbase) + (voff)[_i]), (PG8_LAS unsigned*)(lds + (bufoff) + ldsw + _i * 8192), 16, 0, 0); } while (0)
; #define PG8_LDA(dst, b, h) do { _Pragma("unroll") for (int m = 0; m < 4; ++m) _Pragma("unroll") for (int k = 0; k < 2; ++k) dst[m][k] = *(const PG8_LAS bf16x8*)(lds + PG8_SA(b, h) + aoff + m * 2048 + k * 1024); } while (0)
; #define PG8_MMA(ai, bj, At, Bt) do { __builtin_amdgcn_s_setprio(1); _Pragma("unroll") for (int m = 0; m < 4; ++m) _Pragma("unroll") for (int n = 0; n < 2; ++n) _Pragma("unroll") for (int k = 0; k < 2; ++k) \
;         acc[ai][bj][m][n] = __builtin_amdgcn_mfma_f32_16x16x32_bf16(Bt[n][k], At[m][k], acc[ai][bj][m][n], 0, 0, 0); __builtin_amdgcn_s_setprio(0); } while (0)
; #define PG8_WAIT_V(n) asm volatile("s_waitcnt vmcnt(" #n ")" ::: "memory")
; #define PG8_WAIT_L(n) asm volatile("s_waitcnt lgkmcnt(" #n ")" ::: "memory")
; #define PG8_BAR __builtin_amdgcn_s_barrier()
; #define PG8_SCHED __builtin_amdgcn_sched_barrier(0)
; template <class Epi, class Sched, bool ALIGN_EPI = false, bool SP2 = false>
; __device__ __forceinline__ void gemm_phase(PG8_LAS unsigned char* lds, const Gemm g, const Sched& S, const Epi& E, const int wave_id) {
;     ...
;             PG8_WAIT_V(8); PG8_WAIT_L(0); PG8_BAR; PG8_MMA(0, 0, At, B0); PG8_MMA(0, 1, At, B1); PG8_BAR; PG8_SCHED;
;             PG8_LDA(At, 1, 1); PG8_STAGE(PG8_SB(1, 0), b3, voffB); PG8_STAGE(PG8_SB(1, 1), b3 + hstep, voffB); PG8_STAGE(PG8_SA(1, 0), a3, voffA);
;             PG8_WAIT_V(8); PG8_WAIT_L(0); PG8_BAR; PG8_MMA(1, 0, At, B0); PG8_MMA(1, 1, At, B1); PG8_BAR; PG8_SCHED;
;     ...
;         if constexpr (ALIGN_EPI) { if (wr == 0) PG8_BAR; }
	s_add_i32 s16, s34, s25
	v_lshl_add_u64 v[84:85], v[164:165], 0, s[88:89]
	s_mov_b32 m0, s16
	ds_read_b128 v[186:189], v169 offset:49152
	ds_read_b128 v[190:193], v169 offset:50176
	ds_read_b128 v[194:197], v169 offset:51200
	ds_read_b128 v[202:205], v169 offset:52224
	ds_read_b128 v[206:209], v169 offset:53248
	ds_read_b128 v[212:215], v169 offset:54272
	ds_read_b128 v[216:219], v169 offset:55296
	ds_read_b128 v[220:223], v169 offset:56320
	global_load_lds_dwordx4 v[84:85], off
	s_add_i32 m0, s16, 0x2000
	s_add_u32 s14, s14, 0x40080
	v_lshl_add_u64 v[84:85], v[198:199], 0, s[88:89]
	s_addc_u32 s15, s15, 0
	s_add_i32 s16, s73, s25
	global_load_lds_dwordx4 v[84:85], off
	v_lshl_add_u64 v[84:85], s[14:15], 0, v[146:147]
	s_mov_b32 m0, s16
	s_nop 0
	global_load_lds_dwordx4 v[84:85], off
	v_lshl_add_u64 v[84:85], s[14:15], 0, v[150:151]
	s_add_i32 m0, s16, 0x2000
	s_nop 0
	global_load_lds_dwordx4 v[84:85], off
	v_lshl_add_u64 v[84:85], v[210:211], 0, s[88:89]
	s_mov_b32 m0, s90
	s_nop 0
	global_load_lds_dwordx4 v[84:85], off
	v_lshl_add_u64 v[84:85], v[224:225], 0, s[88:89]
	s_mov_b32 m0, s92
	s_nop 0
	global_load_lds_dwordx4 v[84:85], off
	s_waitcnt vmcnt(8)
	s_waitcnt lgkmcnt(0)
	s_barrier
	s_setprio 1
	s_waitcnt lgkmcnt(0)
	v_mfma_f32_16x16x32_bf16 v[84:87], v[40:43], v[186:189], v[108:111]
	v_mfma_f32_16x16x32_bf16 v[108:111], v[68:71], v[190:193], v[84:87]
	v_mfma_f32_16x16x32_bf16 v[84:87], v[156:159], v[186:189], v[96:99]
	v_mfma_f32_16x16x32_bf16 v[96:99], v[160:163], v[190:193], v[84:87]
	v_mfma_f32_16x16x32_bf16 v[84:87], v[40:43], v[194:197], v[100:103]
	v_mfma_f32_16x16x32_bf16 v[100:103], v[68:71], v[202:205], v[84:87]
	v_mfma_f32_16x16x32_bf16 v[84:87], v[156:159], v[194:197], v[88:91]
	v_mfma_f32_16x16x32_bf16 v[88:91], v[160:163], v[202:205], v[84:87]
	v_mfma_f32_16x16x32_bf16 v[84:87], v[40:43], v[206:209], v[92:95]
	v_mfma_f32_16x16x32_bf16 v[32:35], v[40:43], v[216:219], v[32:35]
	v_mfma_f32_16x16x32_bf16 v[92:95], v[68:71], v[212:215], v[84:87]
	v_mfma_f32_16x16x32_bf16 v[72:75], v[156:159], v[206:209], v[72:75]
	v_mfma_f32_16x16x32_bf16 v[84:87], v[68:71], v[220:223], v[32:35]
	v_mfma_f32_16x16x32_bf16 v[32:35], v[156:159], v[216:219], v[36:39]
	v_mfma_f32_16x16x32_bf16 v[72:75], v[160:163], v[212:215], v[72:75]
	v_mfma_f32_16x16x32_bf16 v[68:71], v[160:163], v[220:223], v[32:35]
	s_setprio 0
	s_setprio 1
	v_mfma_f32_16x16x32_bf16 v[28:31], v[170:173], v[186:189], v[28:31]
	v_mfma_f32_16x16x32_bf16 v[24:27], v[178:181], v[186:189], v[24:27]
	v_mfma_f32_16x16x32_bf16 v[20:23], v[170:173], v[194:197], v[20:23]
	v_mfma_f32_16x16x32_bf16 v[16:19], v[178:181], v[194:197], v[16:19]
	v_mfma_f32_16x16x32_bf16 v[12:15], v[170:173], v[206:209], v[12:15]
	v_mfma_f32_16x16x32_bf16 v[8:11], v[178:181], v[206:209], v[8:11]
	v_mfma_f32_16x16x32_bf16 v[4:7], v[170:173], v[216:219], v[4:7]
	v_mfma_f32_16x16x32_bf16 v[0:3], v[178:181], v[216:219], v[0:3]
	v_mfma_f32_16x16x32_bf16 v[28:31], v[174:177], v[190:193], v[28:31]
	v_mfma_f32_16x16x32_bf16 v[24:27], v[182:185], v[190:193], v[24:27]
	v_mfma_f32_16x16x32_bf16 v[20:23], v[174:177], v[202:205], v[20:23]
	v_mfma_f32_16x16x32_bf16 v[16:19], v[182:185], v[202:205], v[16:19]
	v_mfma_f32_16x16x32_bf16 v[12:15], v[174:177], v[212:215], v[12:15]
	v_mfma_f32_16x16x32_bf16 v[8:11], v[182:185], v[212:215], v[8:11]
	v_mfma_f32_16x16x32_bf16 v[4:7], v[174:177], v[220:223], v[4:7]
	v_mfma_f32_16x16x32_bf16 v[0:3], v[182:185], v[220:223], v[0:3]
	s_setprio 0
	s_barrier
	s_add_i32 s72, s72, 2
	s_add_u32 s12, s12, 0x100
	s_addc_u32 s13, s13, 0
	s_add_u32 s68, s68, 0x100
	s_addc_u32 s69, s69, 0
	s_cmp_gt_u32 s72, 13
	s_cbranch_scc0 .LBB0_695
	s_and_b64 vcc, exec, s[40:41]
	s_cbranch_vccz .LBB0_698
	s_barrier

; #define PG8_STAGE(bufoff, gbase, voff) do { _Pragma("unroll") for (int _i = 0; _i < 2; ++_i) \
;         __builtin_amdgcn_global_load_lds((const unsigned*)((const char*)(gbase) + (voff)[_i]), (PG8_LAS unsigned*)(lds + (bufoff) + ldsw + _i * 8192), 16, 0, 0); } while (0)
; #define PG8_LDA(dst, b, h) do { _Pragma("unroll") for (int m = 0; m < 4; ++m) _Pragma("unroll") for (int k = 0; k < 2; ++k) dst[m][k] = *(const PG8_LAS bf16x8*)(lds + PG8_SA(b, h) + aoff + m * 2048 + k * 1024); } while (0)
; #define PG8_LDB(dst, b, h) do { _Pragma("unroll") for (int n = 0; n < 2; ++n) _Pragma("unroll") for (int k = 0; k < 2; ++k) dst[n][k] = *(const PG8_LAS bf16x8*)(lds + PG8_SB(b, h) + boff + n * 2048 + k * 1024); } while (0)
; #define PG8_MMA(ai, bj, At, Bt) do { __builtin_amdgcn_s_setprio(1); _Pragma("unroll") for (int m = 0; m < 4; ++m) _Pragma("unroll") for (int n = 0; n < 2; ++n) _Pragma("unroll") for (int k = 0; k < 2; ++k) \
;         acc[ai][bj][m][n] = __builtin_amdgcn_mfma_f32_16x16x32_bf16(Bt[n][k], At[m][k], acc[ai][bj][m][n], 0, 0, 0); __builtin_amdgcn_s_setprio(0); } while (0)
; #define PG8_WAIT_V(n) asm volatile("s_waitcnt vmcnt(" #n ")" ::: "memory")
; #define PG8_WAIT_L(n) asm volatile("s_waitcnt lgkmcnt(" #n ")" ::: "memory")
; #define PG8_BAR __builtin_amdgcn_s_barrier()
; #define PG8_SCHED __builtin_amdgcn_sched_barrier(0)
; template <class Epi, class Sched, bool ALIGN_EPI = false, bool SP2 = false>
; __device__ __forceinline__ void gemm_phase(PG8_LAS unsigned char* lds, const Gemm g, const Sched& S, const Epi& E, const int wave_id) {
;     ...
;             PG8_LDB(B0, 0, 0); PG8_LDB(B1, 0, 1); PG8_SCHED; PG8_LDA(At, 0, 0); PG8_STAGE(PG8_SA(1, 1), a1 + hstep, voffA);
;             PG8_WAIT_V(8); PG8_WAIT_L(0); PG8_BAR; PG8_MMA(0, 0, At, B0); PG8_MMA(0, 1, At, B1); PG8_BAR; PG8_SCHED;
;             PG8_LDA(At, 0, 1); PG8_STAGE(PG8_SB(0, 0), b2, voffB); PG8_STAGE(PG8_SB(0, 1), b2 + hstep, voffB); PG8_STAGE(PG8_SA(0, 0), a2, voffA);
.LBB0_1027:
	s_add_u32 s14, s12, 0xfffc0080
	s_addc_u32 s15, s13, -1
	s_add_i32 s49, 0, 0x10000
	s_cmp_eq_u32 s48, 12
	s_cselect_b32 s17, s0, s15
	s_cselect_b32 s16, s1, s14
	v_add_u32_e32 v152, s49, v156
	s_cselect_b32 s15, s9, s43
	s_cselect_b32 s14, s11, s41
	s_add_i32 s52, 0, 0x14000
	ds_read_b128 v[144:147], v152
	ds_read_b128 v[148:151], v152 offset:1024
	ds_read_b128 v[158:161], v152 offset:2048
	ds_read_b128 v[162:165], v152 offset:3072
	v_add_u32_e32 v152, s52, v156
	ds_read_b128 v[166:169], v152
	ds_read_b128 v[170:173], v152 offset:1024
	ds_read_b128 v[174:177], v152 offset:2048
	ds_read_b128 v[178:181], v152 offset:3072
	v_lshl_add_u64 v[152:153], s[12:13], 0, v[140:141]
	s_add_i32 m0, s67, 0xc000
	ds_read_b128 v[182:185], v157
	ds_read_b128 v[186:189], v157 offset:1024
	ds_read_b128 v[190:193], v157 offset:2048
	ds_read_b128 v[194:197], v157 offset:3072
	ds_read_b128 v[202:205], v157 offset:4096
	ds_read_b128 v[212:215], v157 offset:5120
	ds_read_b128 v[216:219], v157 offset:6144
	ds_read_b128 v[220:223], v157 offset:7168
	global_load_lds_dwordx4 v[152:153], off
	v_lshl_add_u64 v[152:153], s[12:13], 0, v[142:143]
	s_add_i32 m0, s67, 0xe000
	s_nop 0
	global_load_lds_dwordx4 v[152:153], off
	s_waitcnt vmcnt(8)
	s_waitcnt lgkmcnt(0)
	s_barrier
	s_setprio 1
	s_waitcnt lgkmcnt(0)
	v_mfma_f32_16x16x32_bf16 v[124:127], v[144:147], v[182:185], v[124:127]
	v_mfma_f32_16x16x32_bf16 v[120:123], v[158:161], v[182:185], v[120:123]
	v_mfma_f32_16x16x32_bf16 v[108:111], v[144:147], v[190:193], v[108:111]
	v_mfma_f32_16x16x32_bf16 v[104:107], v[158:161], v[190:193], v[104:107]
	v_mfma_f32_16x16x32_bf16 v[92:95], v[144:147], v[202:205], v[92:95]
	v_mfma_f32_16x16x32_bf16 v[88:91], v[158:161], v[202:205], v[88:91]
	v_mfma_f32_16x16x32_bf16 v[76:79], v[144:147], v[216:219], v[76:79]
	v_mfma_f32_16x16x32_bf16 v[72:75], v[158:161], v[216:219], v[72:75]
	v_mfma_f32_16x16x32_bf16 v[124:127], v[148:151], v[186:189], v[124:127]
	v_mfma_f32_16x16x32_bf16 v[120:123], v[162:165], v[186:189], v[120:123]
	v_mfma_f32_16x16x32_bf16 v[108:111], v[148:151], v[194:197], v[108:111]
	v_mfma_f32_16x16x32_bf16 v[104:107], v[162:165], v[194:197], v[104:107]
	v_mfma_f32_16x16x32_bf16 v[92:95], v[148:151], v[212:215], v[92:95]
	v_mfma_f32_16x16x32_bf16 v[88:91], v[162:165], v[212:215], v[88:91]
	v_mfma_f32_16x16x32_bf16 v[76:79], v[148:151], v[220:223], v[76:79]
	v_mfma_f32_16x16x32_bf16 v[72:75], v[162:165], v[220:223], v[72:75]
	s_setprio 0
	s_setprio 1
	v_mfma_f32_16x16x32_bf16 v[116:119], v[166:169], v[182:185], v[116:119]
	v_mfma_f32_16x16x32_bf16 v[112:115], v[174:177], v[182:185], v[112:115]
	v_mfma_f32_16x16x32_bf16 v[100:103], v[166:169], v[190:193], v[100:103]
	v_mfma_f32_16x16x32_bf16 v[96:99], v[174:177], v[190:193], v[96:99]
	v_mfma_f32_16x16x32_bf16 v[84:87], v[166:169], v[202:205], v[84:87]
	v_mfma_f32_16x16x32_bf16 v[80:83], v[174:177], v[202:205], v[80:83]
	v_mfma_f32_16x16x32_bf16 v[68:71], v[166:169], v[216:219], v[68:71]
	v_mfma_f32_16x16x32_bf16 v[64:67], v[174:177], v[216:219], v[64:67]
	v_mfma_f32_16x16x32_bf16 v[116:119], v[170:173], v[186:189], v[116:119]
	v_mfma_f32_16x16x32_bf16 v[112:115], v[178:181], v[186:189], v[112:115]
	v_mfma_f32_16x16x32_bf16 v[100:103], v[170:173], v[194:197], v[100:103]
	v_mfma_f32_16x16x32_bf16 v[96:99], v[178:181], v[194:197], v[96:99]
	v_mfma_f32_16x16x32_bf16 v[84:87], v[170:173], v[212:215], v[84:87]
	v_mfma_f32_16x16x32_bf16 v[80:83], v[178:181], v[212:215], v[80:83]
	v_mfma_f32_16x16x32_bf16 v[68:71], v[170:173], v[220:223], v[68:71]
	v_mfma_f32_16x16x32_bf16 v[64:67], v[178:181], v[220:223], v[64:67]
	s_setprio 0
	s_barrier
	s_nop 0
	s_add_i32 s49, s49, s27
	v_lshl_add_u64 v[152:153], s[14:15], 0, v[134:135]
	s_mov_b32 m0, s49
	ds_read_b128 v[182:185], v157 offset:16384
	ds_read_b128 v[186:189], v157 offset:17408
	ds_read_b128 v[190:193], v157 offset:18432
	ds_read_b128 v[194:197], v157 offset:19456
	ds_read_b128 v[202:205], v157 offset:20480
	ds_read_b128 v[212:215], v157 offset:21504
	ds_read_b128 v[216:219], v157 offset:22528
	ds_read_b128 v[220:223], v157 offset:23552
	global_load_lds_dwordx4 v[152:153], off
	s_add_i32 m0, s49, 0x2000
	s_add_u32 s50, s14, 0x40000
	v_lshl_add_u64 v[198:199], s[14:15], 0, v[138:139]
	s_addc_u32 s51, s15, 0
	s_add_i32 s49, s52, s27
	global_load_lds_dwordx4 v[198:199], off
	v_lshl_add_u64 v[206:207], s[50:51], 0, v[134:135]
	s_mov_b32 m0, s49
	v_lshl_add_u64 v[208:209], s[16:17], 0, v[136:137]
	global_load_lds_dwordx4 v[206:207], off
	v_lshl_add_u64 v[206:207], s[50:51], 0, v[138:139]
	s_add_i32 m0, s49, 0x2000
	s_nop 0
	global_load_lds_dwordx4 v[206:207], off
	v_lshl_add_u64 v[206:207], s[16:17], 0, v[132:133]
	s_mov_b32 m0, s67
	s_nop 0
	global_load_lds_dwordx4 v[206:207], off
	s_mov_b32 m0, s68
	s_nop 0
	global_load_lds_dwordx4 v[208:209], off
	s_waitcnt vmcnt(8)
	s_waitcnt lgkmcnt(0)
	s_barrier
; #define PG8_STAGE(bufoff, gbase, voff) do { _Pragma("unroll") for (int _i = 0; _i < 2; ++_i) \
;         __builtin_amdgcn_global_load_lds((const unsigned*)((const char*)(gbase) + (voff)[_i]), (PG8_LAS unsigned*)(lds + (bufoff) + ldsw + _i * 8192), 16, 0, 0); } while (0)
; #define PG8_LDA(dst, b, h) do { _Pragma("unroll") for (int m = 0; m < 4; ++m) _Pragma("unroll") for (int k = 0; k < 2; ++k) dst[m][k] = *(const PG8_LAS bf16x8*)(lds + PG8_SA(b, h) + aoff + m * 2048 + k * 1024); } while (0)
; #define PG8_LDB(dst, b, h) do { _Pragma("unroll") for (int n = 0; n < 2; ++n) _Pragma("unroll") for (int k = 0; k < 2; ++k) dst[n][k] = *(const PG8_LAS bf16x8*)(lds + PG8_SB(b, h) + boff + n * 2048 + k * 1024); } while (0)
; #define PG8_MMA(ai, bj, At, Bt) do { __builtin_amdgcn_s_setprio(1); _Pragma("unroll") for (int m = 0; m < 4; ++m) _Pragma("unroll") for (int n = 0; n < 2; ++n) _Pragma("unroll") for (int k = 0; k < 2; ++k) \
;         acc[ai][bj][m][n] = __builtin_amdgcn_mfma_f32_16x16x32_bf16(Bt[n][k], At[m][k], acc[ai][bj][m][n], 0, 0, 0); __builtin_amdgcn_s_setprio(0); } while (0)
; #define PG8_WAIT_V(n) asm volatile("s_waitcnt vmcnt(" #n ")" ::: "memory")
; #define PG8_WAIT_L(n) asm volatile("s_waitcnt lgkmcnt(" #n ")" ::: "memory")
; #define PG8_BAR __builtin_amdgcn_s_barrier()
; #define PG8_SCHED __builtin_amdgcn_sched_barrier(0)
; template <class Epi, class Sched, bool ALIGN_EPI = false, bool SP2 = false>
; __device__ __forceinline__ void gemm_phase(PG8_LAS unsigned char* lds, const Gemm g, const Sched& S, const Epi& E, const int wave_id) {
;     ...
;             PG8_WAIT_V(8); PG8_WAIT_L(0); PG8_BAR; PG8_MMA(1, 0, At, B0); PG8_MMA(1, 1, At, B1); PG8_BAR; PG8_SCHED;
;             PG8_LDB(B0, 1, 0); PG8_LDB(B1, 1, 1); PG8_SCHED; PG8_LDA(At, 1, 0); PG8_STAGE(PG8_SA(0, 1), a2 + hstep, voffA);
;             PG8_WAIT_V(8); PG8_WAIT_L(0); PG8_BAR; PG8_MMA(0, 0, At, B0); PG8_MMA(0, 1, At, B1); PG8_BAR; PG8_SCHED;
	s_setprio 1
	s_waitcnt lgkmcnt(0)
	v_mfma_f32_16x16x32_bf16 v[60:63], v[144:147], v[182:185], v[60:63]
	v_mfma_f32_16x16x32_bf16 v[56:59], v[158:161], v[182:185], v[56:59]
	v_mfma_f32_16x16x32_bf16 v[44:47], v[144:147], v[190:193], v[44:47]
	v_mfma_f32_16x16x32_bf16 v[40:43], v[158:161], v[190:193], v[40:43]
	v_mfma_f32_16x16x32_bf16 v[28:31], v[144:147], v[202:205], v[28:31]
	v_mfma_f32_16x16x32_bf16 v[24:27], v[158:161], v[202:205], v[24:27]
	v_mfma_f32_16x16x32_bf16 v[12:15], v[144:147], v[216:219], v[12:15]
	v_mfma_f32_16x16x32_bf16 v[8:11], v[158:161], v[216:219], v[8:11]
	v_mfma_f32_16x16x32_bf16 v[60:63], v[148:151], v[186:189], v[60:63]
	v_mfma_f32_16x16x32_bf16 v[56:59], v[162:165], v[186:189], v[56:59]
	v_mfma_f32_16x16x32_bf16 v[44:47], v[148:151], v[194:197], v[44:47]
	v_mfma_f32_16x16x32_bf16 v[40:43], v[162:165], v[194:197], v[40:43]
	v_mfma_f32_16x16x32_bf16 v[28:31], v[148:151], v[212:215], v[28:31]
	v_mfma_f32_16x16x32_bf16 v[24:27], v[162:165], v[212:215], v[24:27]
	v_mfma_f32_16x16x32_bf16 v[12:15], v[148:151], v[220:223], v[12:15]
	v_mfma_f32_16x16x32_bf16 v[8:11], v[162:165], v[220:223], v[8:11]
	s_setprio 0
	s_setprio 1
	v_mfma_f32_16x16x32_bf16 v[52:55], v[166:169], v[182:185], v[52:55]
	v_mfma_f32_16x16x32_bf16 v[48:51], v[174:177], v[182:185], v[48:51]
	v_mfma_f32_16x16x32_bf16 v[36:39], v[166:169], v[190:193], v[36:39]
	v_mfma_f32_16x16x32_bf16 v[32:35], v[174:177], v[190:193], v[32:35]
	v_mfma_f32_16x16x32_bf16 v[20:23], v[166:169], v[202:205], v[20:23]
	v_mfma_f32_16x16x32_bf16 v[16:19], v[174:177], v[202:205], v[16:19]
	v_mfma_f32_16x16x32_bf16 v[4:7], v[166:169], v[216:219], v[4:7]
	v_mfma_f32_16x16x32_bf16 v[0:3], v[174:177], v[216:219], v[0:3]
	v_mfma_f32_16x16x32_bf16 v[52:55], v[170:173], v[186:189], v[52:55]
	v_mfma_f32_16x16x32_bf16 v[48:51], v[178:181], v[186:189], v[48:51]
	v_mfma_f32_16x16x32_bf16 v[36:39], v[170:173], v[194:197], v[36:39]
	v_mfma_f32_16x16x32_bf16 v[32:35], v[178:181], v[194:197], v[32:35]
	v_mfma_f32_16x16x32_bf16 v[20:23], v[170:173], v[212:215], v[20:23]
	v_mfma_f32_16x16x32_bf16 v[16:19], v[178:181], v[212:215], v[16:19]
	v_mfma_f32_16x16x32_bf16 v[4:7], v[170:173], v[220:223], v[4:7]
	v_mfma_f32_16x16x32_bf16 v[0:3], v[178:181], v[220:223], v[0:3]
	s_setprio 0
	s_barrier
	s_nop 0
	s_add_i32 s49, 0, 0x18000
	s_add_i32 s50, 0, 0x1c000
	v_add_u32_e32 v162, s49, v156
	v_add_u32_e32 v178, s50, v156
	ds_read_b128 v[144:147], v162
	ds_read_b128 v[148:151], v162 offset:1024
	ds_read_b128 v[158:161], v162 offset:2048
	ds_read_b128 v[162:165], v162 offset:3072
	ds_read_b128 v[166:169], v178
	ds_read_b128 v[170:173], v178 offset:1024
	ds_read_b128 v[174:177], v178 offset:2048
	ds_read_b128 v[178:181], v178 offset:3072
	s_add_u32 s16, s16, 0x40000
	s_addc_u32 s17, s17, 0
	s_mov_b32 m0, s69
	v_lshl_add_u64 v[210:211], s[16:17], 0, v[132:133]
	ds_read_b128 v[182:185], v157 offset:32768
	ds_read_b128 v[186:189], v157 offset:33792
	ds_read_b128 v[190:193], v157 offset:34816
	ds_read_b128 v[194:197], v157 offset:35840
	ds_read_b128 v[202:205], v157 offset:36864
	ds_read_b128 v[212:215], v157 offset:37888
	ds_read_b128 v[216:219], v157 offset:38912
	ds_read_b128 v[220:223], v157 offset:39936
	global_load_lds_dwordx4 v[210:211], off
	v_lshl_add_u64 v[210:211], s[16:17], 0, v[136:137]
	s_mov_b32 m0, s72
	s_nop 0
	global_load_lds_dwordx4 v[210:211], off
	s_waitcnt vmcnt(8)
	s_waitcnt lgkmcnt(0)
	s_barrier
	s_setprio 1
	s_waitcnt lgkmcnt(0)
	v_mfma_f32_16x16x32_bf16 v[124:127], v[144:147], v[182:185], v[124:127]
	v_mfma_f32_16x16x32_bf16 v[120:123], v[158:161], v[182:185], v[120:123]
	v_mfma_f32_16x16x32_bf16 v[108:111], v[144:147], v[190:193], v[108:111]
	v_mfma_f32_16x16x32_bf16 v[104:107], v[158:161], v[190:193], v[104:107]
	v_mfma_f32_16x16x32_bf16 v[92:95], v[144:147], v[202:205], v[92:95]
	v_mfma_f32_16x16x32_bf16 v[88:91], v[158:161], v[202:205], v[88:91]
	v_mfma_f32_16x16x32_bf16 v[76:79], v[144:147], v[216:219], v[76:79]
	v_mfma_f32_16x16x32_bf16 v[72:75], v[158:161], v[216:219], v[72:75]
	v_mfma_f32_16x16x32_bf16 v[124:127], v[148:151], v[186:189], v[124:127]
	v_mfma_f32_16x16x32_bf16 v[120:123], v[162:165], v[186:189], v[120:123]
	v_mfma_f32_16x16x32_bf16 v[108:111], v[148:151], v[194:197], v[108:111]
	v_mfma_f32_16x16x32_bf16 v[104:107], v[162:165], v[194:197], v[104:107]
	v_mfma_f32_16x16x32_bf16 v[92:95], v[148:151], v[212:215], v[92:95]
	v_mfma_f32_16x16x32_bf16 v[88:91], v[162:165], v[212:215], v[88:91]
	v_mfma_f32_16x16x32_bf16 v[76:79], v[148:151], v[220:223], v[76:79]
	v_mfma_f32_16x16x32_bf16 v[72:75], v[162:165], v[220:223], v[72:75]
	s_setprio 0
	s_setprio 1
	v_mfma_f32_16x16x32_bf16 v[116:119], v[166:169], v[182:185], v[116:119]
	v_mfma_f32_16x16x32_bf16 v[112:115], v[174:177], v[182:185], v[112:115]
	v_mfma_f32_16x16x32_bf16 v[100:103], v[166:169], v[190:193], v[100:103]
	v_mfma_f32_16x16x32_bf16 v[96:99], v[174:177], v[190:193], v[96:99]
	v_mfma_f32_16x16x32_bf16 v[84:87], v[166:169], v[202:205], v[84:87]
	v_mfma_f32_16x16x32_bf16 v[80:83], v[174:177], v[202:205], v[80:83]
	v_mfma_f32_16x16x32_bf16 v[68:71], v[166:169], v[216:219], v[68:71]
	v_mfma_f32_16x16x32_bf16 v[64:67], v[174:177], v[216:219], v[64:67]
	v_mfma_f32_16x16x32_bf16 v[116:119], v[170:173], v[186:189], v[116:119]
	v_mfma_f32_16x16x32_bf16 v[112:115], v[178:181], v[186:189], v[112:115]
	v_mfma_f32_16x16x32_bf16 v[100:103], v[170:173], v[194:197], v[100:103]
	v_mfma_f32_16x16x32_bf16 v[96:99], v[178:181], v[194:197], v[96:99]
	v_mfma_f32_16x16x32_bf16 v[84:87], v[170:173], v[212:215], v[84:87]
	v_mfma_f32_16x16x32_bf16 v[80:83], v[178:181], v[212:215], v[80:83]
	v_mfma_f32_16x16x32_bf16 v[68:71], v[170:173], v[220:223], v[68:71]
	v_mfma_f32_16x16x32_bf16 v[64:67], v[178:181], v[220:223], v[64:67]
	s_setprio 0
	s_barrier
; #define PG8_STAGE(bufoff, gbase, voff) do { _Pragma("unroll") for (int _i = 0; _i < 2; ++_i) \
;         __builtin_amdgcn_global_load_lds((const unsigned*)((const char*)(gbase) + (voff)[_i]), (PG8_LAS unsigned*)(lds + (bufoff) + ldsw + _i * 8192), 16, 0, 0); } while (0)
; #define PG8_LDA(dst, b, h) do { _Pragma("unroll") for (int m = 0; m < 4; ++m) _Pragma("unroll") for (int k = 0; k < 2; ++k) dst[m][k] = *(const PG8_LAS bf16x8*)(lds + PG8_SA(b, h) + aoff + m * 2048 + k * 1024); } while (0)
; #define PG8_MMA(ai, bj, At, Bt) do { __builtin_amdgcn_s_setprio(1); _Pragma("unroll") for (int m = 0; m < 4; ++m) _Pragma("unroll") for (int n = 0; n < 2; ++n) _Pragma("unroll") for (int k = 0; k < 2; ++k) \
;         acc[ai][bj][m][n] = __builtin_amdgcn_mfma_f32_16x16x32_bf16(Bt[n][k], At[m][k], acc[ai][bj][m][n], 0, 0, 0); __builtin_amdgcn_s_setprio(0); } while (0)
; #define PG8_WAIT_V(n) asm volatile("s_waitcnt vmcnt(" #n ")" ::: "memory")
; #define PG8_WAIT_L(n) asm volatile("s_waitcnt lgkmcnt(" #n ")" ::: "memory")
; #define PG8_BAR __builtin_amdgcn_s_barrier()
; #define PG8_SCHED __builtin_amdgcn_sched_barrier(0)
; template <class Epi, class Sched, bool ALIGN_EPI = false, bool SP2 = false>
; __device__ __forceinline__ void gemm_phase(PG8_LAS unsigned char* lds, const Gemm g, const Sched& S, const Epi& E, const int wave_id) {
;     ...
;             PG8_WAIT_V(8); PG8_WAIT_L(0); PG8_BAR; PG8_MMA(0, 0, At, B0); PG8_MMA(0, 1, At, B1); PG8_BAR; PG8_SCHED;
;             PG8_LDA(At, 1, 1); PG8_STAGE(PG8_SB(1, 0), b3, voffB); PG8_STAGE(PG8_SB(1, 1), b3 + hstep, voffB); PG8_STAGE(PG8_SA(1, 0), a3, voffA);
;             PG8_WAIT_V(8); PG8_WAIT_L(0); PG8_BAR; PG8_MMA(1, 0, At, B0); PG8_MMA(1, 1, At, B1); PG8_BAR; PG8_SCHED;
;     ...
;         if constexpr (ALIGN_EPI) { if (wr == 0) PG8_BAR; }
	s_add_i32 s16, s49, s27
	v_lshl_add_u64 v[152:153], v[152:153], 0, s[88:89]
	s_mov_b32 m0, s16
	ds_read_b128 v[182:185], v157 offset:49152
	ds_read_b128 v[186:189], v157 offset:50176
	ds_read_b128 v[190:193], v157 offset:51200
	ds_read_b128 v[194:197], v157 offset:52224
	ds_read_b128 v[202:205], v157 offset:53248
	ds_read_b128 v[212:215], v157 offset:54272
	ds_read_b128 v[216:219], v157 offset:55296
	ds_read_b128 v[220:223], v157 offset:56320
	global_load_lds_dwordx4 v[152:153], off
	s_add_i32 m0, s16, 0x2000
	s_add_u32 s14, s14, 0x40080
	v_lshl_add_u64 v[152:153], v[198:199], 0, s[88:89]
	s_addc_u32 s15, s15, 0
	s_add_i32 s16, s50, s27
	global_load_lds_dwordx4 v[152:153], off
	v_lshl_add_u64 v[152:153], s[14:15], 0, v[134:135]
	s_mov_b32 m0, s16
	s_nop 0
	global_load_lds_dwordx4 v[152:153], off
	v_lshl_add_u64 v[152:153], s[14:15], 0, v[138:139]
	s_add_i32 m0, s16, 0x2000
	s_nop 0
	global_load_lds_dwordx4 v[152:153], off
	v_lshl_add_u64 v[152:153], v[206:207], 0, s[88:89]
	s_mov_b32 m0, s73
	s_nop 0
	global_load_lds_dwordx4 v[152:153], off
	v_lshl_add_u64 v[152:153], v[208:209], 0, s[88:89]
	s_mov_b32 m0, s74
	s_nop 0
	global_load_lds_dwordx4 v[152:153], off
	s_waitcnt vmcnt(8)
	s_waitcnt lgkmcnt(0)
	s_barrier
	s_setprio 1
	s_waitcnt lgkmcnt(0)
	v_mfma_f32_16x16x32_bf16 v[60:63], v[144:147], v[182:185], v[60:63]
	v_mfma_f32_16x16x32_bf16 v[56:59], v[158:161], v[182:185], v[56:59]
	v_mfma_f32_16x16x32_bf16 v[44:47], v[144:147], v[190:193], v[44:47]
	v_mfma_f32_16x16x32_bf16 v[40:43], v[158:161], v[190:193], v[40:43]
	v_mfma_f32_16x16x32_bf16 v[28:31], v[144:147], v[202:205], v[28:31]
	v_mfma_f32_16x16x32_bf16 v[24:27], v[158:161], v[202:205], v[24:27]
	v_mfma_f32_16x16x32_bf16 v[12:15], v[144:147], v[216:219], v[12:15]
	v_mfma_f32_16x16x32_bf16 v[8:11], v[158:161], v[216:219], v[8:11]
	v_mfma_f32_16x16x32_bf16 v[60:63], v[148:151], v[186:189], v[60:63]
	v_mfma_f32_16x16x32_bf16 v[56:59], v[162:165], v[186:189], v[56:59]
	v_mfma_f32_16x16x32_bf16 v[44:47], v[148:151], v[194:197], v[44:47]
	v_mfma_f32_16x16x32_bf16 v[40:43], v[162:165], v[194:197], v[40:43]
	v_mfma_f32_16x16x32_bf16 v[28:31], v[148:151], v[212:215], v[28:31]
	v_mfma_f32_16x16x32_bf16 v[24:27], v[162:165], v[212:215], v[24:27]
	v_mfma_f32_16x16x32_bf16 v[12:15], v[148:151], v[220:223], v[12:15]
	v_mfma_f32_16x16x32_bf16 v[8:11], v[162:165], v[220:223], v[8:11]
	s_setprio 0
	s_setprio 1
	v_mfma_f32_16x16x32_bf16 v[52:55], v[166:169], v[182:185], v[52:55]
	v_mfma_f32_16x16x32_bf16 v[48:51], v[174:177], v[182:185], v[48:51]
	v_mfma_f32_16x16x32_bf16 v[36:39], v[166:169], v[190:193], v[36:39]
	v_mfma_f32_16x16x32_bf16 v[32:35], v[174:177], v[190:193], v[32:35]
	v_mfma_f32_16x16x32_bf16 v[20:23], v[166:169], v[202:205], v[20:23]
	v_mfma_f32_16x16x32_bf16 v[16:19], v[174:177], v[202:205], v[16:19]
	v_mfma_f32_16x16x32_bf16 v[4:7], v[166:169], v[216:219], v[4:7]
	v_mfma_f32_16x16x32_bf16 v[0:3], v[174:177], v[216:219], v[0:3]
	v_mfma_f32_16x16x32_bf16 v[52:55], v[170:173], v[186:189], v[52:55]
	v_mfma_f32_16x16x32_bf16 v[48:51], v[178:181], v[186:189], v[48:51]
	v_mfma_f32_16x16x32_bf16 v[36:39], v[170:173], v[194:197], v[36:39]
	v_mfma_f32_16x16x32_bf16 v[32:35], v[178:181], v[194:197], v[32:35]
	v_mfma_f32_16x16x32_bf16 v[20:23], v[170:173], v[212:215], v[20:23]
	v_mfma_f32_16x16x32_bf16 v[16:19], v[178:181], v[212:215], v[16:19]
	v_mfma_f32_16x16x32_bf16 v[4:7], v[170:173], v[220:223], v[4:7]
	v_mfma_f32_16x16x32_bf16 v[0:3], v[178:181], v[220:223], v[0:3]
	s_setprio 0
	s_barrier
	s_add_i32 s48, s48, 2
	s_add_u32 s12, s12, 0x100
	s_addc_u32 s13, s13, 0
	s_add_u32 s41, s41, 0x100
	s_addc_u32 s43, s43, 0
	s_cmp_gt_u32 s48, 13
	s_cbranch_scc0 .LBB0_1027
	s_and_b64 vcc, exec, s[38:39]
	s_cbranch_vccz .LBB0_1030
	s_barrier

; #define PG8_STAGE(bufoff, gbase, voff) do { _Pragma("unroll") for (int _i = 0; _i < 2; ++_i) \
;         __builtin_amdgcn_global_load_lds((const unsigned*)((const char*)(gbase) + (voff)[_i]), (PG8_LAS unsigned*)(lds + (bufoff) + ldsw + _i * 8192), 16, 0, 0); } while (0)
; #define PG8_LDA(dst, b, h) do { _Pragma("unroll") for (int m = 0; m < 4; ++m) _Pragma("unroll") for (int k = 0; k < 2; ++k) dst[m][k] = *(const PG8_LAS bf16x8*)(lds + PG8_SA(b, h) + aoff + m * 2048 + k * 1024); } while (0)
; #define PG8_LDB(dst, b, h) do { _Pragma("unroll") for (int n = 0; n < 2; ++n) _Pragma("unroll") for (int k = 0; k < 2; ++k) dst[n][k] = *(const PG8_LAS bf16x8*)(lds + PG8_SB(b, h) + boff + n * 2048 + k * 1024); } while (0)
; #define PG8_MMA(ai, bj, At, Bt) do { __builtin_amdgcn_s_setprio(1); _Pragma("unroll") for (int m = 0; m < 4; ++m) _Pragma("unroll") for (int n = 0; n < 2; ++n) _Pragma("unroll") for (int k = 0; k < 2; ++k) \
;         acc[ai][bj][m][n] = __builtin_amdgcn_mfma_f32_16x16x32_bf16(Bt[n][k], At[m][k], acc[ai][bj][m][n], 0, 0, 0); __builtin_amdgcn_s_setprio(0); } while (0)
; #define PG8_WAIT_V(n) asm volatile("s_waitcnt vmcnt(" #n ")" ::: "memory")
; #define PG8_WAIT_L(n) asm volatile("s_waitcnt lgkmcnt(" #n ")" ::: "memory")
; #define PG8_BAR __builtin_amdgcn_s_barrier()
; #define PG8_SCHED __builtin_amdgcn_sched_barrier(0)
; template <class Epi, class Sched, bool ALIGN_EPI = false, bool SP2 = false>
; __device__ __forceinline__ void gemm_phase(PG8_LAS unsigned char* lds, const Gemm g, const Sched& S, const Epi& E, const int wave_id) {
;     ...
;             PG8_LDB(B0, 0, 0); PG8_LDB(B1, 0, 1); PG8_SCHED; PG8_LDA(At, 0, 0); PG8_STAGE(PG8_SA(1, 1), a1 + hstep, voffA);
;             PG8_WAIT_V(8); PG8_WAIT_L(0); PG8_BAR; PG8_MMA(0, 0, At, B0); PG8_MMA(0, 1, At, B1); PG8_BAR; PG8_SCHED;
;             PG8_LDA(At, 0, 1); PG8_STAGE(PG8_SB(0, 0), b2, voffB); PG8_STAGE(PG8_SB(0, 1), b2 + hstep, voffB); PG8_STAGE(PG8_SA(0, 0), a2, voffA);
.LBB0_1718:
	s_add_u32 s34, s36, 0xfff80080
	s_addc_u32 s35, s37, -1
	s_add_i32 s63, 0, 0x10000
	s_cmp_eq_u32 s62, 28
	s_cselect_b32 s39, s23, s35
	s_cselect_b32 s38, s29, s34
	s_cselect_b32 s35, s21, s61
	s_cselect_b32 s34, s31, s60
	s_add_i32 s67, 0, 0x14000
	v_add_u32_e32 v154, s63, v140
	v_add_u32_e32 v170, s67, v140
	ds_read_b128 v[142:145], v154
	ds_read_b128 v[146:149], v154 offset:1024
	ds_read_b128 v[150:153], v154 offset:2048
	ds_read_b128 v[154:157], v154 offset:3072
	ds_read_b128 v[158:161], v170
	ds_read_b128 v[162:165], v170 offset:1024
	ds_read_b128 v[166:169], v170 offset:2048
	ds_read_b128 v[170:173], v170 offset:3072
	v_lshl_add_u64 v[198:199], s[36:37], 0, v[134:135]
	s_add_i32 m0, s49, 0xc000
	ds_read_b128 v[174:177], v141
	ds_read_b128 v[178:181], v141 offset:1024
	ds_read_b128 v[182:185], v141 offset:2048
	ds_read_b128 v[186:189], v141 offset:3072
	ds_read_b128 v[190:193], v141 offset:4096
	ds_read_b128 v[194:197], v141 offset:5120
	ds_read_b128 v[202:205], v141 offset:6144
	ds_read_b128 v[206:209], v141 offset:7168
	global_load_lds_dwordx4 v[198:199], off
	v_lshl_add_u64 v[198:199], s[36:37], 0, v[136:137]
	s_add_i32 m0, s49, 0xe000
	s_nop 0
	global_load_lds_dwordx4 v[198:199], off
	s_waitcnt vmcnt(8)
	s_waitcnt lgkmcnt(0)
	s_barrier
	s_setprio 1
	s_waitcnt lgkmcnt(0)
	v_mfma_f32_16x16x32_bf16 v[112:115], v[142:145], v[174:177], v[112:115]
	v_mfma_f32_16x16x32_bf16 v[116:119], v[150:153], v[174:177], v[116:119]
	v_mfma_f32_16x16x32_bf16 v[96:99], v[142:145], v[182:185], v[96:99]
	v_mfma_f32_16x16x32_bf16 v[100:103], v[150:153], v[182:185], v[100:103]
	v_mfma_f32_16x16x32_bf16 v[80:83], v[142:145], v[190:193], v[80:83]
	v_mfma_f32_16x16x32_bf16 v[84:87], v[150:153], v[190:193], v[84:87]
	v_mfma_f32_16x16x32_bf16 v[60:63], v[142:145], v[202:205], v[60:63]
	v_mfma_f32_16x16x32_bf16 v[68:71], v[150:153], v[202:205], v[68:71]
	v_mfma_f32_16x16x32_bf16 v[112:115], v[146:149], v[178:181], v[112:115]
	v_mfma_f32_16x16x32_bf16 v[116:119], v[154:157], v[178:181], v[116:119]
	v_mfma_f32_16x16x32_bf16 v[96:99], v[146:149], v[186:189], v[96:99]
	v_mfma_f32_16x16x32_bf16 v[100:103], v[154:157], v[186:189], v[100:103]
	v_mfma_f32_16x16x32_bf16 v[80:83], v[146:149], v[194:197], v[80:83]
	v_mfma_f32_16x16x32_bf16 v[84:87], v[154:157], v[194:197], v[84:87]
	v_mfma_f32_16x16x32_bf16 v[60:63], v[146:149], v[206:209], v[60:63]
	v_mfma_f32_16x16x32_bf16 v[68:71], v[154:157], v[206:209], v[68:71]
	s_setprio 0
	s_setprio 1
	v_mfma_f32_16x16x32_bf16 v[120:123], v[158:161], v[174:177], v[120:123]
	v_mfma_f32_16x16x32_bf16 v[124:127], v[166:169], v[174:177], v[124:127]
	v_mfma_f32_16x16x32_bf16 v[104:107], v[158:161], v[182:185], v[104:107]
	v_mfma_f32_16x16x32_bf16 v[108:111], v[166:169], v[182:185], v[108:111]
	v_mfma_f32_16x16x32_bf16 v[88:91], v[158:161], v[190:193], v[88:91]
	v_mfma_f32_16x16x32_bf16 v[92:95], v[166:169], v[190:193], v[92:95]
	v_mfma_f32_16x16x32_bf16 v[72:75], v[158:161], v[202:205], v[72:75]
	v_mfma_f32_16x16x32_bf16 v[76:79], v[166:169], v[202:205], v[76:79]
	v_mfma_f32_16x16x32_bf16 v[120:123], v[162:165], v[178:181], v[120:123]
	v_mfma_f32_16x16x32_bf16 v[124:127], v[170:173], v[178:181], v[124:127]
	v_mfma_f32_16x16x32_bf16 v[104:107], v[162:165], v[186:189], v[104:107]
	v_mfma_f32_16x16x32_bf16 v[108:111], v[170:173], v[186:189], v[108:111]
	v_mfma_f32_16x16x32_bf16 v[88:91], v[162:165], v[194:197], v[88:91]
	v_mfma_f32_16x16x32_bf16 v[92:95], v[170:173], v[194:197], v[92:95]
	v_mfma_f32_16x16x32_bf16 v[72:75], v[162:165], v[206:209], v[72:75]
	v_mfma_f32_16x16x32_bf16 v[76:79], v[170:173], v[206:209], v[76:79]
	s_setprio 0
	s_barrier
	s_nop 0
	s_add_i32 s63, s63, s46
	v_lshl_add_u64 v[198:199], s[34:35], 0, v[200:201]
	s_mov_b32 m0, s63
	ds_read_b128 v[174:177], v141 offset:16384
	ds_read_b128 v[178:181], v141 offset:17408
	ds_read_b128 v[182:185], v141 offset:18432
	ds_read_b128 v[186:189], v141 offset:19456
	ds_read_b128 v[190:193], v141 offset:20480
	ds_read_b128 v[194:197], v141 offset:21504
	ds_read_b128 v[202:205], v141 offset:22528
	ds_read_b128 v[206:209], v141 offset:23552
	global_load_lds_dwordx4 v[198:199], off
	s_add_i32 m0, s63, 0x2000
	s_add_u32 s64, s34, 0x80000
	v_lshl_add_u64 v[210:211], s[34:35], 0, v[132:133]
	s_addc_u32 s65, s35, 0
	s_add_i32 s63, s67, s46
	global_load_lds_dwordx4 v[210:211], off
	v_lshl_add_u64 v[212:213], s[64:65], 0, v[200:201]
	s_mov_b32 m0, s63
	v_lshl_add_u64 v[214:215], s[38:39], 0, v[130:131]
	global_load_lds_dwordx4 v[212:213], off
	v_lshl_add_u64 v[212:213], s[64:65], 0, v[132:133]
	s_add_i32 m0, s63, 0x2000
	s_nop 0
	global_load_lds_dwordx4 v[212:213], off
	v_lshl_add_u64 v[212:213], s[38:39], 0, v[128:129]
	s_mov_b32 m0, s49
	s_nop 0
	global_load_lds_dwordx4 v[212:213], off
	s_mov_b32 m0, s50
	s_nop 0
	global_load_lds_dwordx4 v[214:215], off
	s_waitcnt vmcnt(8)
	s_waitcnt lgkmcnt(0)
	s_barrier
; #define PG8_STAGE(bufoff, gbase, voff) do { _Pragma("unroll") for (int _i = 0; _i < 2; ++_i) \
;         __builtin_amdgcn_global_load_lds((const unsigned*)((const char*)(gbase) + (voff)[_i]), (PG8_LAS unsigned*)(lds + (bufoff) + ldsw + _i * 8192), 16, 0, 0); } while (0)
; #define PG8_LDA(dst, b, h) do { _Pragma("unroll") for (int m = 0; m < 4; ++m) _Pragma("unroll") for (int k = 0; k < 2; ++k) dst[m][k] = *(const PG8_LAS bf16x8*)(lds + PG8_SA(b, h) + aoff + m * 2048 + k * 1024); } while (0)
; #define PG8_LDB(dst, b, h) do { _Pragma("unroll") for (int n = 0; n < 2; ++n) _Pragma("unroll") for (int k = 0; k < 2; ++k) dst[n][k] = *(const PG8_LAS bf16x8*)(lds + PG8_SB(b, h) + boff + n * 2048 + k * 1024); } while (0)
; #define PG8_MMA(ai, bj, At, Bt) do { __builtin_amdgcn_s_setprio(1); _Pragma("unroll") for (int m = 0; m < 4; ++m) _Pragma("unroll") for (int n = 0; n < 2; ++n) _Pragma("unroll") for (int k = 0; k < 2; ++k) \
;         acc[ai][bj][m][n] = __builtin_amdgcn_mfma_f32_16x16x32_bf16(Bt[n][k], At[m][k], acc[ai][bj][m][n], 0, 0, 0); __builtin_amdgcn_s_setprio(0); } while (0)
; #define PG8_WAIT_V(n) asm volatile("s_waitcnt vmcnt(" #n ")" ::: "memory")
; #define PG8_WAIT_L(n) asm volatile("s_waitcnt lgkmcnt(" #n ")" ::: "memory")
; #define PG8_BAR __builtin_amdgcn_s_barrier()
; #define PG8_SCHED __builtin_amdgcn_sched_barrier(0)
; template <class Epi, class Sched, bool ALIGN_EPI = false, bool SP2 = false>
; __device__ __forceinline__ void gemm_phase(PG8_LAS unsigned char* lds, const Gemm g, const Sched& S, const Epi& E, const int wave_id) {
;     ...
;             PG8_WAIT_V(8); PG8_WAIT_L(0); PG8_BAR; PG8_MMA(1, 0, At, B0); PG8_MMA(1, 1, At, B1); PG8_BAR; PG8_SCHED;
;             PG8_LDB(B0, 1, 0); PG8_LDB(B1, 1, 1); PG8_SCHED; PG8_LDA(At, 1, 0); PG8_STAGE(PG8_SA(0, 1), a2 + hstep, voffA);
;             PG8_WAIT_V(8); PG8_WAIT_L(0); PG8_BAR; PG8_MMA(0, 0, At, B0); PG8_MMA(0, 1, At, B1); PG8_BAR; PG8_SCHED;
	s_setprio 1
	s_waitcnt lgkmcnt(0)
	v_mfma_f32_16x16x32_bf16 v[48:51], v[142:145], v[174:177], v[48:51]
	v_mfma_f32_16x16x32_bf16 v[52:55], v[150:153], v[174:177], v[52:55]
	v_mfma_f32_16x16x32_bf16 v[32:35], v[142:145], v[182:185], v[32:35]
	v_mfma_f32_16x16x32_bf16 v[36:39], v[150:153], v[182:185], v[36:39]
	v_mfma_f32_16x16x32_bf16 v[16:19], v[142:145], v[190:193], v[16:19]
	v_mfma_f32_16x16x32_bf16 v[20:23], v[150:153], v[190:193], v[20:23]
	v_mfma_f32_16x16x32_bf16 v[0:3], v[142:145], v[202:205], v[0:3]
	v_mfma_f32_16x16x32_bf16 v[4:7], v[150:153], v[202:205], v[4:7]
	v_mfma_f32_16x16x32_bf16 v[48:51], v[146:149], v[178:181], v[48:51]
	v_mfma_f32_16x16x32_bf16 v[52:55], v[154:157], v[178:181], v[52:55]
	v_mfma_f32_16x16x32_bf16 v[32:35], v[146:149], v[186:189], v[32:35]
	v_mfma_f32_16x16x32_bf16 v[36:39], v[154:157], v[186:189], v[36:39]
	v_mfma_f32_16x16x32_bf16 v[16:19], v[146:149], v[194:197], v[16:19]
	v_mfma_f32_16x16x32_bf16 v[20:23], v[154:157], v[194:197], v[20:23]
	v_mfma_f32_16x16x32_bf16 v[0:3], v[146:149], v[206:209], v[0:3]
	v_mfma_f32_16x16x32_bf16 v[4:7], v[154:157], v[206:209], v[4:7]
	s_setprio 0
	s_setprio 1
	v_mfma_f32_16x16x32_bf16 v[56:59], v[158:161], v[174:177], v[56:59]
	v_mfma_f32_16x16x32_bf16 v[64:67], v[166:169], v[174:177], v[64:67]
	v_mfma_f32_16x16x32_bf16 v[40:43], v[158:161], v[182:185], v[40:43]
	v_mfma_f32_16x16x32_bf16 v[44:47], v[166:169], v[182:185], v[44:47]
	v_mfma_f32_16x16x32_bf16 v[24:27], v[158:161], v[190:193], v[24:27]
	v_mfma_f32_16x16x32_bf16 v[28:31], v[166:169], v[190:193], v[28:31]
	v_mfma_f32_16x16x32_bf16 v[8:11], v[158:161], v[202:205], v[8:11]
	v_mfma_f32_16x16x32_bf16 v[12:15], v[166:169], v[202:205], v[12:15]
	v_mfma_f32_16x16x32_bf16 v[56:59], v[162:165], v[178:181], v[56:59]
	v_mfma_f32_16x16x32_bf16 v[64:67], v[170:173], v[178:181], v[64:67]
	v_mfma_f32_16x16x32_bf16 v[40:43], v[162:165], v[186:189], v[40:43]
	v_mfma_f32_16x16x32_bf16 v[44:47], v[170:173], v[186:189], v[44:47]
	v_mfma_f32_16x16x32_bf16 v[24:27], v[162:165], v[194:197], v[24:27]
	v_mfma_f32_16x16x32_bf16 v[28:31], v[170:173], v[194:197], v[28:31]
	v_mfma_f32_16x16x32_bf16 v[8:11], v[162:165], v[206:209], v[8:11]
	v_mfma_f32_16x16x32_bf16 v[12:15], v[170:173], v[206:209], v[12:15]
	s_setprio 0
	s_barrier
	s_nop 0
	s_add_i32 s63, 0, 0x18000
	s_add_i32 s64, 0, 0x1c000
	v_add_u32_e32 v154, s63, v140
	v_add_u32_e32 v170, s64, v140
	ds_read_b128 v[142:145], v154
	ds_read_b128 v[146:149], v154 offset:1024
	ds_read_b128 v[150:153], v154 offset:2048
	ds_read_b128 v[154:157], v154 offset:3072
	ds_read_b128 v[158:161], v170
	ds_read_b128 v[162:165], v170 offset:1024
	ds_read_b128 v[166:169], v170 offset:2048
	ds_read_b128 v[170:173], v170 offset:3072
	s_add_u32 s38, s38, 0x80000
	s_addc_u32 s39, s39, 0
	s_mov_b32 m0, s51
	v_lshl_add_u64 v[216:217], s[38:39], 0, v[128:129]
	ds_read_b128 v[174:177], v141 offset:32768
	ds_read_b128 v[178:181], v141 offset:33792
	ds_read_b128 v[182:185], v141 offset:34816
	ds_read_b128 v[186:189], v141 offset:35840
	ds_read_b128 v[190:193], v141 offset:36864
	ds_read_b128 v[194:197], v141 offset:37888
	ds_read_b128 v[202:205], v141 offset:38912
	ds_read_b128 v[206:209], v141 offset:39936
	global_load_lds_dwordx4 v[216:217], off
	v_lshl_add_u64 v[216:217], s[38:39], 0, v[130:131]
	s_mov_b32 m0, s52
	s_nop 0
	global_load_lds_dwordx4 v[216:217], off
	s_waitcnt vmcnt(8)
	s_waitcnt lgkmcnt(0)
	s_barrier
	s_setprio 1
	s_waitcnt lgkmcnt(0)
	v_mfma_f32_16x16x32_bf16 v[112:115], v[142:145], v[174:177], v[112:115]
	v_mfma_f32_16x16x32_bf16 v[116:119], v[150:153], v[174:177], v[116:119]
	v_mfma_f32_16x16x32_bf16 v[96:99], v[142:145], v[182:185], v[96:99]
	v_mfma_f32_16x16x32_bf16 v[100:103], v[150:153], v[182:185], v[100:103]
	v_mfma_f32_16x16x32_bf16 v[80:83], v[142:145], v[190:193], v[80:83]
	v_mfma_f32_16x16x32_bf16 v[84:87], v[150:153], v[190:193], v[84:87]
	v_mfma_f32_16x16x32_bf16 v[60:63], v[142:145], v[202:205], v[60:63]
	v_mfma_f32_16x16x32_bf16 v[68:71], v[150:153], v[202:205], v[68:71]
	v_mfma_f32_16x16x32_bf16 v[112:115], v[146:149], v[178:181], v[112:115]
	v_mfma_f32_16x16x32_bf16 v[116:119], v[154:157], v[178:181], v[116:119]
	v_mfma_f32_16x16x32_bf16 v[96:99], v[146:149], v[186:189], v[96:99]
	v_mfma_f32_16x16x32_bf16 v[100:103], v[154:157], v[186:189], v[100:103]
	v_mfma_f32_16x16x32_bf16 v[80:83], v[146:149], v[194:197], v[80:83]
	v_mfma_f32_16x16x32_bf16 v[84:87], v[154:157], v[194:197], v[84:87]
	v_mfma_f32_16x16x32_bf16 v[60:63], v[146:149], v[206:209], v[60:63]
	v_mfma_f32_16x16x32_bf16 v[68:71], v[154:157], v[206:209], v[68:71]
	s_setprio 0
	s_setprio 1
	v_mfma_f32_16x16x32_bf16 v[120:123], v[158:161], v[174:177], v[120:123]
	v_mfma_f32_16x16x32_bf16 v[124:127], v[166:169], v[174:177], v[124:127]
	v_mfma_f32_16x16x32_bf16 v[104:107], v[158:161], v[182:185], v[104:107]
	v_mfma_f32_16x16x32_bf16 v[108:111], v[166:169], v[182:185], v[108:111]
	v_mfma_f32_16x16x32_bf16 v[88:91], v[158:161], v[190:193], v[88:91]
	v_mfma_f32_16x16x32_bf16 v[92:95], v[166:169], v[190:193], v[92:95]
	v_mfma_f32_16x16x32_bf16 v[72:75], v[158:161], v[202:205], v[72:75]
	v_mfma_f32_16x16x32_bf16 v[76:79], v[166:169], v[202:205], v[76:79]
	v_mfma_f32_16x16x32_bf16 v[120:123], v[162:165], v[178:181], v[120:123]
	v_mfma_f32_16x16x32_bf16 v[124:127], v[170:173], v[178:181], v[124:127]
	v_mfma_f32_16x16x32_bf16 v[104:107], v[162:165], v[186:189], v[104:107]
	v_mfma_f32_16x16x32_bf16 v[108:111], v[170:173], v[186:189], v[108:111]
	v_mfma_f32_16x16x32_bf16 v[88:91], v[162:165], v[194:197], v[88:91]
	v_mfma_f32_16x16x32_bf16 v[92:95], v[170:173], v[194:197], v[92:95]
	v_mfma_f32_16x16x32_bf16 v[72:75], v[162:165], v[206:209], v[72:75]
	v_mfma_f32_16x16x32_bf16 v[76:79], v[170:173], v[206:209], v[76:79]
	s_setprio 0
	s_barrier
; #define PG8_STAGE(bufoff, gbase, voff) do { _Pragma("unroll") for (int _i = 0; _i < 2; ++_i) \
;         __builtin_amdgcn_global_load_lds((const unsigned*)((const char*)(gbase) + (voff)[_i]), (PG8_LAS unsigned*)(lds + (bufoff) + ldsw + _i * 8192), 16, 0, 0); } while (0)
; #define PG8_LDA(dst, b, h) do { _Pragma("unroll") for (int m = 0; m < 4; ++m) _Pragma("unroll") for (int k = 0; k < 2; ++k) dst[m][k] = *(const PG8_LAS bf16x8*)(lds + PG8_SA(b, h) + aoff + m * 2048 + k * 1024); } while (0)
; #define PG8_MMA(ai, bj, At, Bt) do { __builtin_amdgcn_s_setprio(1); _Pragma("unroll") for (int m = 0; m < 4; ++m) _Pragma("unroll") for (int n = 0; n < 2; ++n) _Pragma("unroll") for (int k = 0; k < 2; ++k) \
;         acc[ai][bj][m][n] = __builtin_amdgcn_mfma_f32_16x16x32_bf16(Bt[n][k], At[m][k], acc[ai][bj][m][n], 0, 0, 0); __builtin_amdgcn_s_setprio(0); } while (0)
; #define PG8_WAIT_V(n) asm volatile("s_waitcnt vmcnt(" #n ")" ::: "memory")
; #define PG8_WAIT_L(n) asm volatile("s_waitcnt lgkmcnt(" #n ")" ::: "memory")
; #define PG8_BAR __builtin_amdgcn_s_barrier()
; #define PG8_SCHED __builtin_amdgcn_sched_barrier(0)
; template <class Epi, class Sched, bool ALIGN_EPI = false, bool SP2 = false>
; __device__ __forceinline__ void gemm_phase(PG8_LAS unsigned char* lds, const Gemm g, const Sched& S, const Epi& E, const int wave_id) {
;     ...
;             PG8_WAIT_V(8); PG8_WAIT_L(0); PG8_BAR; PG8_MMA(0, 0, At, B0); PG8_MMA(0, 1, At, B1); PG8_BAR; PG8_SCHED;
;             PG8_LDA(At, 1, 1); PG8_STAGE(PG8_SB(1, 0), b3, voffB); PG8_STAGE(PG8_SB(1, 1), b3 + hstep, voffB); PG8_STAGE(PG8_SA(1, 0), a3, voffA);
;             PG8_WAIT_V(8); PG8_WAIT_L(0); PG8_BAR; PG8_MMA(1, 0, At, B0); PG8_MMA(1, 1, At, B1); PG8_BAR; PG8_SCHED;
;     ...
;         if constexpr (ALIGN_EPI) { if (wr == 0) PG8_BAR; }
	s_add_i32 s38, s63, s46
	v_lshl_add_u64 v[198:199], v[198:199], 0, s[88:89]
	s_mov_b32 m0, s38
	ds_read_b128 v[174:177], v141 offset:49152
	ds_read_b128 v[178:181], v141 offset:50176
	ds_read_b128 v[182:185], v141 offset:51200
	ds_read_b128 v[186:189], v141 offset:52224
	ds_read_b128 v[190:193], v141 offset:53248
	ds_read_b128 v[194:197], v141 offset:54272
	ds_read_b128 v[202:205], v141 offset:55296
	ds_read_b128 v[206:209], v141 offset:56320
	global_load_lds_dwordx4 v[198:199], off
	s_add_i32 m0, s38, 0x2000
	s_add_u32 s34, s34, 0x80080
	v_lshl_add_u64 v[198:199], v[210:211], 0, s[88:89]
	s_addc_u32 s35, s35, 0
	s_add_i32 s38, s64, s46
	global_load_lds_dwordx4 v[198:199], off
	v_lshl_add_u64 v[198:199], s[34:35], 0, v[200:201]
	s_mov_b32 m0, s38
	s_nop 0
	global_load_lds_dwordx4 v[198:199], off
	v_lshl_add_u64 v[198:199], s[34:35], 0, v[132:133]
	s_add_i32 m0, s38, 0x2000
	s_nop 0
	global_load_lds_dwordx4 v[198:199], off
	v_lshl_add_u64 v[198:199], v[212:213], 0, s[88:89]
	s_mov_b32 m0, s53
	s_nop 0
	global_load_lds_dwordx4 v[198:199], off
	v_lshl_add_u64 v[198:199], v[214:215], 0, s[88:89]
	s_mov_b32 m0, s54
	s_nop 0
	global_load_lds_dwordx4 v[198:199], off
	s_waitcnt vmcnt(8)
	s_waitcnt lgkmcnt(0)
	s_barrier
	s_setprio 1
	s_waitcnt lgkmcnt(0)
	v_mfma_f32_16x16x32_bf16 v[48:51], v[142:145], v[174:177], v[48:51]
	v_mfma_f32_16x16x32_bf16 v[52:55], v[150:153], v[174:177], v[52:55]
	v_mfma_f32_16x16x32_bf16 v[32:35], v[142:145], v[182:185], v[32:35]
	v_mfma_f32_16x16x32_bf16 v[36:39], v[150:153], v[182:185], v[36:39]
	v_mfma_f32_16x16x32_bf16 v[16:19], v[142:145], v[190:193], v[16:19]
	v_mfma_f32_16x16x32_bf16 v[20:23], v[150:153], v[190:193], v[20:23]
	v_mfma_f32_16x16x32_bf16 v[0:3], v[142:145], v[202:205], v[0:3]
	v_mfma_f32_16x16x32_bf16 v[4:7], v[150:153], v[202:205], v[4:7]
	v_mfma_f32_16x16x32_bf16 v[48:51], v[146:149], v[178:181], v[48:51]
	v_mfma_f32_16x16x32_bf16 v[52:55], v[154:157], v[178:181], v[52:55]
	v_mfma_f32_16x16x32_bf16 v[32:35], v[146:149], v[186:189], v[32:35]
	v_mfma_f32_16x16x32_bf16 v[36:39], v[154:157], v[186:189], v[36:39]
	v_mfma_f32_16x16x32_bf16 v[16:19], v[146:149], v[194:197], v[16:19]
	v_mfma_f32_16x16x32_bf16 v[20:23], v[154:157], v[194:197], v[20:23]
	v_mfma_f32_16x16x32_bf16 v[0:3], v[146:149], v[206:209], v[0:3]
	v_mfma_f32_16x16x32_bf16 v[4:7], v[154:157], v[206:209], v[4:7]
	s_setprio 0
	s_setprio 1
	v_mfma_f32_16x16x32_bf16 v[56:59], v[158:161], v[174:177], v[56:59]
	v_mfma_f32_16x16x32_bf16 v[64:67], v[166:169], v[174:177], v[64:67]
	v_mfma_f32_16x16x32_bf16 v[40:43], v[158:161], v[182:185], v[40:43]
	v_mfma_f32_16x16x32_bf16 v[44:47], v[166:169], v[182:185], v[44:47]
	v_mfma_f32_16x16x32_bf16 v[24:27], v[158:161], v[190:193], v[24:27]
	v_mfma_f32_16x16x32_bf16 v[28:31], v[166:169], v[190:193], v[28:31]
	v_mfma_f32_16x16x32_bf16 v[8:11], v[158:161], v[202:205], v[8:11]
	v_mfma_f32_16x16x32_bf16 v[12:15], v[166:169], v[202:205], v[12:15]
	v_mfma_f32_16x16x32_bf16 v[56:59], v[162:165], v[178:181], v[56:59]
	v_mfma_f32_16x16x32_bf16 v[64:67], v[170:173], v[178:181], v[64:67]
	v_mfma_f32_16x16x32_bf16 v[40:43], v[162:165], v[186:189], v[40:43]
	v_mfma_f32_16x16x32_bf16 v[44:47], v[170:173], v[186:189], v[44:47]
	v_mfma_f32_16x16x32_bf16 v[24:27], v[162:165], v[194:197], v[24:27]
	v_mfma_f32_16x16x32_bf16 v[28:31], v[170:173], v[194:197], v[28:31]
	v_mfma_f32_16x16x32_bf16 v[8:11], v[162:165], v[206:209], v[8:11]
	v_mfma_f32_16x16x32_bf16 v[12:15], v[170:173], v[206:209], v[12:15]
	s_setprio 0
	s_barrier
	s_add_i32 s62, s62, 2
	s_add_u32 s36, s36, 0x100
	s_addc_u32 s37, s37, 0
	s_add_u32 s60, s60, 0x100
	s_addc_u32 s61, s61, 0
	s_cmp_gt_u32 s62, 29
	s_cbranch_scc0 .LBB0_1718
	s_and_b64 vcc, exec, s[18:19]
	s_cbranch_vccz .LBB0_1721
	s_barrier

; #define PG8_STAGE(bufoff, gbase, voff) do { _Pragma("unroll") for (int _i = 0; _i < 2; ++_i) \
;         __builtin_amdgcn_global_load_lds((const unsigned*)((const char*)(gbase) + (voff)[_i]), (PG8_LAS unsigned*)(lds + (bufoff) + ldsw + _i * 8192), 16, 0, 0); } while (0)
; #define PG8_LDA(dst, b, h) do { _Pragma("unroll") for (int m = 0; m < 4; ++m) _Pragma("unroll") for (int k = 0; k < 2; ++k) dst[m][k] = *(const PG8_LAS bf16x8*)(lds + PG8_SA(b, h) + aoff + m * 2048 + k * 1024); } while (0)
; #define PG8_LDB(dst, b, h) do { _Pragma("unroll") for (int n = 0; n < 2; ++n) _Pragma("unroll") for (int k = 0; k < 2; ++k) dst[n][k] = *(const PG8_LAS bf16x8*)(lds + PG8_SB(b, h) + boff + n * 2048 + k * 1024); } while (0)
; #define PG8_WAIT_V(n) asm volatile("s_waitcnt vmcnt(" #n ")" ::: "memory")
; #define PG8_WAIT_L(n) asm volatile("s_waitcnt lgkmcnt(" #n ")" ::: "memory")
; #define PG8_BAR __builtin_amdgcn_s_barrier()
; #define PG8_SCHED __builtin_amdgcn_sched_barrier(0)
; template <class Epi, class Sched, bool ALIGN_EPI = false, bool SP2 = false>
; __device__ __forceinline__ void gemm_phase(PG8_LAS unsigned char* lds, const Gemm g, const Sched& S, const Epi& E, const int wave_id) {
;     ...
;         const bool has_next = S.next(ui + 1, nxt);
;         const char* nA = has_next ? (const char*)g.A + (size_t)nxt.pm * tstep : cA; const char* nB = has_next ? (const char*)g.Bt + (size_t)nxt.pn * tstep : cB;
;         for (int t = 0; t < nt; t += 2) {
;             const bool last = (t == nt - 2);
;             const char* a1 = cA + (size_t)(t + 1) * kstep;
;             const char* a2 = last ? nA : cA + (size_t)(t + 2) * kstep; const char* b2 = last ? nB : cB + (size_t)(t + 2) * kstep;
;             const char* a3 = a2 + kstep; const char* b3 = b2 + kstep;
;             if (last && has_next) S.a_ready(nxt);
;             if constexpr (SP2) {
;             PG8_LDB(B0, 0, 0); PG8_LDB(B1, 0, 1); PG8_SCHED; PG8_LDA(At, 0, 0); PG8_STAGE(PG8_SA(1, 1), a1 + hstep, voffA);
;             PG8_WAIT_V(8); PG8_WAIT_L(0); PG8_BAR; PG8_MMA(0, 0, At, B0); PG8_MMA(0, 1, At, B1); PG8_BAR; PG8_SCHED;
;     ...
; #pragma unroll
;         for (int a = 0; a < 2; ++a)
; #pragma unroll
;             for (int b = 0; b < 2; ++b)
; #pragma unroll
;                 for (int m = 0; m < 4; ++m)
; #pragma unroll
;                     for (int n = 0; n < 2; ++n) acc[a][b][m][n] = (f32x4){0.f, 0.f, 0.f, 0.f};
.LBB0_1862:
	s_ashr_i32 s29, s28, 31
	s_lshl_b64 s[30:31], s[28:29], 19
	s_add_u32 s30, s49, s30
	s_addc_u32 s31, s50, s31
	s_and_b64 s[34:35], s[4:5], exec
	s_cselect_b32 s7, s31, s39
	s_cselect_b32 s29, s30, s38
	s_ashr_i32 s27, s26, 31
	s_lshl_b64 s[34:35], s[26:27], 19
	s_add_u32 s34, s14, s34
	s_addc_u32 s35, s15, s35
	s_and_b64 s[42:43], s[4:5], exec
	s_cselect_b32 s27, s35, s41
	s_cselect_b32 s37, s34, s40
	s_add_u32 s38, s38, 0x40080
	s_addc_u32 s39, s39, 0
	s_add_u32 s63, s40, 0x100
	v_mov_b32_e32 v0, 0
	s_addc_u32 s64, s41, 0
	s_mov_b32 s65, -2
	v_mov_b32_e32 v1, v0
	v_mov_b32_e32 v2, v0
	v_mov_b32_e32 v3, v0
	v_mov_b32_e32 v4, v0
	v_mov_b32_e32 v5, v0
	v_mov_b32_e32 v6, v0
	v_mov_b32_e32 v7, v0
	v_mov_b32_e32 v16, v0
	v_mov_b32_e32 v17, v0
	v_mov_b32_e32 v18, v0
	v_mov_b32_e32 v19, v0
	v_mov_b32_e32 v20, v0
	v_mov_b32_e32 v21, v0
	v_mov_b32_e32 v22, v0
	v_mov_b32_e32 v23, v0
	v_mov_b32_e32 v32, v0
	v_mov_b32_e32 v33, v0
	v_mov_b32_e32 v34, v0
	v_mov_b32_e32 v35, v0
	v_mov_b32_e32 v36, v0
	v_mov_b32_e32 v37, v0
	v_mov_b32_e32 v38, v0
	v_mov_b32_e32 v39, v0
	v_mov_b32_e32 v48, v0
	v_mov_b32_e32 v49, v0
	v_mov_b32_e32 v50, v0
	v_mov_b32_e32 v51, v0
	v_mov_b32_e32 v52, v0
	v_mov_b32_e32 v53, v0
	v_mov_b32_e32 v54, v0
	v_mov_b32_e32 v55, v0
	v_mov_b32_e32 v8, v0
	v_mov_b32_e32 v9, v0
	v_mov_b32_e32 v10, v0
	v_mov_b32_e32 v11, v0
	v_mov_b32_e32 v12, v0
	v_mov_b32_e32 v13, v0
	v_mov_b32_e32 v14, v0
	v_mov_b32_e32 v15, v0
	v_mov_b32_e32 v24, v0
	v_mov_b32_e32 v25, v0
	v_mov_b32_e32 v26, v0
	v_mov_b32_e32 v27, v0
	v_mov_b32_e32 v28, v0
	v_mov_b32_e32 v29, v0
	v_mov_b32_e32 v30, v0
	v_mov_b32_e32 v31, v0
	v_mov_b32_e32 v40, v0
	v_mov_b32_e32 v41, v0
	v_mov_b32_e32 v42, v0
	v_mov_b32_e32 v43, v0
	v_mov_b32_e32 v44, v0
	v_mov_b32_e32 v45, v0
	v_mov_b32_e32 v46, v0
	v_mov_b32_e32 v47, v0
	v_mov_b32_e32 v56, v0
	v_mov_b32_e32 v57, v0
	v_mov_b32_e32 v58, v0
	v_mov_b32_e32 v59, v0
	v_mov_b32_e32 v60, v0
	v_mov_b32_e32 v61, v0
	v_mov_b32_e32 v62, v0
	v_mov_b32_e32 v63, v0
	v_mov_b32_e32 v64, v0
	v_mov_b32_e32 v65, v0
	v_mov_b32_e32 v66, v0
	v_mov_b32_e32 v67, v0
	v_mov_b32_e32 v68, v0
	v_mov_b32_e32 v69, v0
	v_mov_b32_e32 v70, v0
	v_mov_b32_e32 v71, v0
	v_mov_b32_e32 v80, v0
	v_mov_b32_e32 v81, v0
	v_mov_b32_e32 v82, v0
	v_mov_b32_e32 v83, v0
	v_mov_b32_e32 v84, v0
	v_mov_b32_e32 v85, v0
	v_mov_b32_e32 v86, v0
	v_mov_b32_e32 v87, v0
	v_mov_b32_e32 v96, v0
	v_mov_b32_e32 v97, v0
	v_mov_b32_e32 v98, v0
	v_mov_b32_e32 v99, v0
	v_mov_b32_e32 v100, v0
	v_mov_b32_e32 v101, v0
	v_mov_b32_e32 v102, v0
	v_mov_b32_e32 v103, v0
	v_mov_b32_e32 v112, v0
	v_mov_b32_e32 v113, v0
	v_mov_b32_e32 v114, v0
	v_mov_b32_e32 v115, v0
	v_mov_b32_e32 v116, v0
	v_mov_b32_e32 v117, v0
	v_mov_b32_e32 v118, v0
	v_mov_b32_e32 v119, v0
	v_mov_b32_e32 v72, v0
	v_mov_b32_e32 v73, v0
	v_mov_b32_e32 v74, v0
	v_mov_b32_e32 v75, v0
	v_mov_b32_e32 v76, v0
	v_mov_b32_e32 v77, v0
	v_mov_b32_e32 v78, v0
	v_mov_b32_e32 v79, v0
	v_mov_b32_e32 v88, v0
	v_mov_b32_e32 v89, v0
	v_mov_b32_e32 v90, v0
	v_mov_b32_e32 v91, v0
	v_mov_b32_e32 v92, v0
	v_mov_b32_e32 v93, v0
	v_mov_b32_e32 v94, v0
	v_mov_b32_e32 v95, v0
	v_mov_b32_e32 v104, v0
	v_mov_b32_e32 v105, v0
	v_mov_b32_e32 v106, v0
	v_mov_b32_e32 v107, v0
	v_mov_b32_e32 v108, v0
	v_mov_b32_e32 v109, v0
	v_mov_b32_e32 v110, v0
	v_mov_b32_e32 v111, v0
	v_mov_b32_e32 v120, v0
	v_mov_b32_e32 v121, v0
	v_mov_b32_e32 v122, v0
	v_mov_b32_e32 v123, v0
	v_mov_b32_e32 v124, v0
	v_mov_b32_e32 v125, v0
	v_mov_b32_e32 v126, v0
	v_mov_b32_e32 v127, v0
	s_nop 0
.LBB0_1863:
	s_add_u32 s40, s38, 0xfffc0080
	s_addc_u32 s41, s39, -1
	s_add_i32 s67, 0, 0x10000
	s_cmp_eq_u32 s65, 12
	s_cselect_b32 s43, s7, s41
	s_cselect_b32 s42, s29, s40
	v_add_u32_e32 v142, s67, v145
	s_cselect_b32 s41, s27, s64
	s_cselect_b32 s40, s37, s63
	s_add_i32 s72, 0, 0x14000
	ds_read_b128 v[138:141], v142
	ds_read_b128 v[148:151], v142 offset:1024
	ds_read_b128 v[152:155], v142 offset:2048
	ds_read_b128 v[156:159], v142 offset:3072
	v_add_u32_e32 v142, s72, v145
	ds_read_b128 v[160:163], v142
	ds_read_b128 v[164:167], v142 offset:1024
	ds_read_b128 v[168:171], v142 offset:2048
	ds_read_b128 v[172:175], v142 offset:3072
	v_lshl_add_u64 v[210:211], s[38:39], 0, v[134:135]
	s_add_i32 m0, s51, 0xc000
	ds_read_b128 v[176:179], v146
	ds_read_b128 v[180:183], v146 offset:1024
	ds_read_b128 v[184:187], v146 offset:2048
	ds_read_b128 v[188:191], v146 offset:3072
	ds_read_b128 v[192:195], v146 offset:4096
	ds_read_b128 v[196:199], v146 offset:5120
	ds_read_b128 v[202:205], v146 offset:6144
	ds_read_b128 v[206:209], v146 offset:7168
	global_load_lds_dwordx4 v[210:211], off
	v_lshl_add_u64 v[210:211], s[38:39], 0, v[136:137]
	s_add_i32 m0, s51, 0xe000
	s_nop 0
	global_load_lds_dwordx4 v[210:211], off
	s_waitcnt vmcnt(8)
	s_waitcnt lgkmcnt(0)
	s_barrier
; #define PG8_STAGE(bufoff, gbase, voff) do { _Pragma("unroll") for (int _i = 0; _i < 2; ++_i) \
;         __builtin_amdgcn_global_load_lds((const unsigned*)((const char*)(gbase) + (voff)[_i]), (PG8_LAS unsigned*)(lds + (bufoff) + ldsw + _i * 8192), 16, 0, 0); } while (0)
; #define PG8_LDA(dst, b, h) do { _Pragma("unroll") for (int m = 0; m < 4; ++m) _Pragma("unroll") for (int k = 0; k < 2; ++k) dst[m][k] = *(const PG8_LAS bf16x8*)(lds + PG8_SA(b, h) + aoff + m * 2048 + k * 1024); } while (0)
; #define PG8_MMA(ai, bj, At, Bt) do { __builtin_amdgcn_s_setprio(1); _Pragma("unroll") for (int m = 0; m < 4; ++m) _Pragma("unroll") for (int n = 0; n < 2; ++n) _Pragma("unroll") for (int k = 0; k < 2; ++k) \
;         acc[ai][bj][m][n] = __builtin_amdgcn_mfma_f32_16x16x32_bf16(Bt[n][k], At[m][k], acc[ai][bj][m][n], 0, 0, 0); __builtin_amdgcn_s_setprio(0); } while (0)
; #define PG8_WAIT_V(n) asm volatile("s_waitcnt vmcnt(" #n ")" ::: "memory")
; #define PG8_WAIT_L(n) asm volatile("s_waitcnt lgkmcnt(" #n ")" ::: "memory")
; #define PG8_BAR __builtin_amdgcn_s_barrier()
; #define PG8_SCHED __builtin_amdgcn_sched_barrier(0)
; template <class Epi, class Sched, bool ALIGN_EPI = false, bool SP2 = false>
; __device__ __forceinline__ void gemm_phase(PG8_LAS unsigned char* lds, const Gemm g, const Sched& S, const Epi& E, const int wave_id) {
;     ...
;             PG8_WAIT_V(8); PG8_WAIT_L(0); PG8_BAR; PG8_MMA(0, 0, At, B0); PG8_MMA(0, 1, At, B1); PG8_BAR; PG8_SCHED;
;             PG8_LDA(At, 0, 1); PG8_STAGE(PG8_SB(0, 0), b2, voffB); PG8_STAGE(PG8_SB(0, 1), b2 + hstep, voffB); PG8_STAGE(PG8_SA(0, 0), a2, voffA);
;             PG8_WAIT_V(8); PG8_WAIT_L(0); PG8_BAR; PG8_MMA(1, 0, At, B0); PG8_MMA(1, 1, At, B1); PG8_BAR; PG8_SCHED;
	s_setprio 1
	s_waitcnt lgkmcnt(0)
	v_mfma_f32_16x16x32_bf16 v[124:127], v[138:141], v[176:179], v[124:127]
	v_mfma_f32_16x16x32_bf16 v[120:123], v[152:155], v[176:179], v[120:123]
	v_mfma_f32_16x16x32_bf16 v[108:111], v[138:141], v[184:187], v[108:111]
	v_mfma_f32_16x16x32_bf16 v[104:107], v[152:155], v[184:187], v[104:107]
	v_mfma_f32_16x16x32_bf16 v[92:95], v[138:141], v[192:195], v[92:95]
	v_mfma_f32_16x16x32_bf16 v[88:91], v[152:155], v[192:195], v[88:91]
	v_mfma_f32_16x16x32_bf16 v[76:79], v[138:141], v[202:205], v[76:79]
	v_mfma_f32_16x16x32_bf16 v[72:75], v[152:155], v[202:205], v[72:75]
	v_mfma_f32_16x16x32_bf16 v[124:127], v[148:151], v[180:183], v[124:127]
	v_mfma_f32_16x16x32_bf16 v[120:123], v[156:159], v[180:183], v[120:123]
	v_mfma_f32_16x16x32_bf16 v[108:111], v[148:151], v[188:191], v[108:111]
	v_mfma_f32_16x16x32_bf16 v[104:107], v[156:159], v[188:191], v[104:107]
	v_mfma_f32_16x16x32_bf16 v[92:95], v[148:151], v[196:199], v[92:95]
	v_mfma_f32_16x16x32_bf16 v[88:91], v[156:159], v[196:199], v[88:91]
	v_mfma_f32_16x16x32_bf16 v[76:79], v[148:151], v[206:209], v[76:79]
	v_mfma_f32_16x16x32_bf16 v[72:75], v[156:159], v[206:209], v[72:75]
	s_setprio 0
	s_setprio 1
	v_mfma_f32_16x16x32_bf16 v[116:119], v[160:163], v[176:179], v[116:119]
	v_mfma_f32_16x16x32_bf16 v[112:115], v[168:171], v[176:179], v[112:115]
	v_mfma_f32_16x16x32_bf16 v[100:103], v[160:163], v[184:187], v[100:103]
	v_mfma_f32_16x16x32_bf16 v[96:99], v[168:171], v[184:187], v[96:99]
	v_mfma_f32_16x16x32_bf16 v[84:87], v[160:163], v[192:195], v[84:87]
	v_mfma_f32_16x16x32_bf16 v[80:83], v[168:171], v[192:195], v[80:83]
	v_mfma_f32_16x16x32_bf16 v[68:71], v[160:163], v[202:205], v[68:71]
	v_mfma_f32_16x16x32_bf16 v[64:67], v[168:171], v[202:205], v[64:67]
	v_mfma_f32_16x16x32_bf16 v[116:119], v[164:167], v[180:183], v[116:119]
	v_mfma_f32_16x16x32_bf16 v[112:115], v[172:175], v[180:183], v[112:115]
	v_mfma_f32_16x16x32_bf16 v[100:103], v[164:167], v[188:191], v[100:103]
	v_mfma_f32_16x16x32_bf16 v[96:99], v[172:175], v[188:191], v[96:99]
	v_mfma_f32_16x16x32_bf16 v[84:87], v[164:167], v[196:199], v[84:87]
	v_mfma_f32_16x16x32_bf16 v[80:83], v[172:175], v[196:199], v[80:83]
	v_mfma_f32_16x16x32_bf16 v[68:71], v[164:167], v[206:209], v[68:71]
	v_mfma_f32_16x16x32_bf16 v[64:67], v[172:175], v[206:209], v[64:67]
	s_setprio 0
	s_barrier
	s_nop 0
	s_add_i32 s67, s67, s17
	v_lshl_add_u64 v[210:211], s[40:41], 0, v[200:201]
	s_mov_b32 m0, s67
	ds_read_b128 v[176:179], v146 offset:16384
	ds_read_b128 v[180:183], v146 offset:17408
	ds_read_b128 v[184:187], v146 offset:18432
	ds_read_b128 v[188:191], v146 offset:19456
	ds_read_b128 v[192:195], v146 offset:20480
	ds_read_b128 v[196:199], v146 offset:21504
	ds_read_b128 v[202:205], v146 offset:22528
	ds_read_b128 v[206:209], v146 offset:23552
	global_load_lds_dwordx4 v[210:211], off
	s_add_i32 m0, s67, 0x2000
	s_add_u32 s68, s40, 0x40000
	v_lshl_add_u64 v[212:213], s[40:41], 0, v[132:133]
	s_addc_u32 s69, s41, 0
	s_add_i32 s67, s72, s17
	global_load_lds_dwordx4 v[212:213], off
	v_lshl_add_u64 v[214:215], s[68:69], 0, v[200:201]
	s_mov_b32 m0, s67
	v_lshl_add_u64 v[216:217], s[42:43], 0, v[130:131]
	global_load_lds_dwordx4 v[214:215], off
	v_lshl_add_u64 v[214:215], s[68:69], 0, v[132:133]
	s_add_i32 m0, s67, 0x2000
	s_nop 0
	global_load_lds_dwordx4 v[214:215], off
	v_lshl_add_u64 v[214:215], s[42:43], 0, v[128:129]
	s_mov_b32 m0, s51
	s_nop 0
	global_load_lds_dwordx4 v[214:215], off
	s_mov_b32 m0, s52
	s_nop 0
	global_load_lds_dwordx4 v[216:217], off
	s_waitcnt vmcnt(8)
	s_waitcnt lgkmcnt(0)
	s_barrier
	s_setprio 1
	s_waitcnt lgkmcnt(0)
	v_mfma_f32_16x16x32_bf16 v[60:63], v[138:141], v[176:179], v[60:63]
	v_mfma_f32_16x16x32_bf16 v[56:59], v[152:155], v[176:179], v[56:59]
	v_mfma_f32_16x16x32_bf16 v[44:47], v[138:141], v[184:187], v[44:47]
	v_mfma_f32_16x16x32_bf16 v[40:43], v[152:155], v[184:187], v[40:43]
	v_mfma_f32_16x16x32_bf16 v[28:31], v[138:141], v[192:195], v[28:31]
	v_mfma_f32_16x16x32_bf16 v[24:27], v[152:155], v[192:195], v[24:27]
	v_mfma_f32_16x16x32_bf16 v[12:15], v[138:141], v[202:205], v[12:15]
	v_mfma_f32_16x16x32_bf16 v[8:11], v[152:155], v[202:205], v[8:11]
	v_mfma_f32_16x16x32_bf16 v[60:63], v[148:151], v[180:183], v[60:63]
	v_mfma_f32_16x16x32_bf16 v[56:59], v[156:159], v[180:183], v[56:59]
	v_mfma_f32_16x16x32_bf16 v[44:47], v[148:151], v[188:191], v[44:47]
	v_mfma_f32_16x16x32_bf16 v[40:43], v[156:159], v[188:191], v[40:43]
	v_mfma_f32_16x16x32_bf16 v[28:31], v[148:151], v[196:199], v[28:31]
	v_mfma_f32_16x16x32_bf16 v[24:27], v[156:159], v[196:199], v[24:27]
	v_mfma_f32_16x16x32_bf16 v[12:15], v[148:151], v[206:209], v[12:15]
	v_mfma_f32_16x16x32_bf16 v[8:11], v[156:159], v[206:209], v[8:11]
	s_setprio 0
	s_setprio 1
	v_mfma_f32_16x16x32_bf16 v[52:55], v[160:163], v[176:179], v[52:55]
	v_mfma_f32_16x16x32_bf16 v[48:51], v[168:171], v[176:179], v[48:51]
	v_mfma_f32_16x16x32_bf16 v[36:39], v[160:163], v[184:187], v[36:39]
	v_mfma_f32_16x16x32_bf16 v[32:35], v[168:171], v[184:187], v[32:35]
	v_mfma_f32_16x16x32_bf16 v[20:23], v[160:163], v[192:195], v[20:23]
	v_mfma_f32_16x16x32_bf16 v[16:19], v[168:171], v[192:195], v[16:19]
	v_mfma_f32_16x16x32_bf16 v[4:7], v[160:163], v[202:205], v[4:7]
	v_mfma_f32_16x16x32_bf16 v[0:3], v[168:171], v[202:205], v[0:3]
	v_mfma_f32_16x16x32_bf16 v[52:55], v[164:167], v[180:183], v[52:55]
	v_mfma_f32_16x16x32_bf16 v[48:51], v[172:175], v[180:183], v[48:51]
	v_mfma_f32_16x16x32_bf16 v[36:39], v[164:167], v[188:191], v[36:39]
	v_mfma_f32_16x16x32_bf16 v[32:35], v[172:175], v[188:191], v[32:35]
	v_mfma_f32_16x16x32_bf16 v[20:23], v[164:167], v[196:199], v[20:23]
	v_mfma_f32_16x16x32_bf16 v[16:19], v[172:175], v[196:199], v[16:19]
	v_mfma_f32_16x16x32_bf16 v[4:7], v[164:167], v[206:209], v[4:7]
	v_mfma_f32_16x16x32_bf16 v[0:3], v[172:175], v[206:209], v[0:3]
	s_setprio 0
	s_barrier
; #define PG8_STAGE(bufoff, gbase, voff) do { _Pragma("unroll") for (int _i = 0; _i < 2; ++_i) \
;         __builtin_amdgcn_global_load_lds((const unsigned*)((const char*)(gbase) + (voff)[_i]), (PG8_LAS unsigned*)(lds + (bufoff) + ldsw + _i * 8192), 16, 0, 0); } while (0)
; #define PG8_LDA(dst, b, h) do { _Pragma("unroll") for (int m = 0; m < 4; ++m) _Pragma("unroll") for (int k = 0; k < 2; ++k) dst[m][k] = *(const PG8_LAS bf16x8*)(lds + PG8_SA(b, h) + aoff + m * 2048 + k * 1024); } while (0)
; #define PG8_LDB(dst, b, h) do { _Pragma("unroll") for (int n = 0; n < 2; ++n) _Pragma("unroll") for (int k = 0; k < 2; ++k) dst[n][k] = *(const PG8_LAS bf16x8*)(lds + PG8_SB(b, h) + boff + n * 2048 + k * 1024); } while (0)
; #define PG8_MMA(ai, bj, At, Bt) do { __builtin_amdgcn_s_setprio(1); _Pragma("unroll") for (int m = 0; m < 4; ++m) _Pragma("unroll") for (int n = 0; n < 2; ++n) _Pragma("unroll") for (int k = 0; k < 2; ++k) \
;         acc[ai][bj][m][n] = __builtin_amdgcn_mfma_f32_16x16x32_bf16(Bt[n][k], At[m][k], acc[ai][bj][m][n], 0, 0, 0); __builtin_amdgcn_s_setprio(0); } while (0)
; #define PG8_WAIT_V(n) asm volatile("s_waitcnt vmcnt(" #n ")" ::: "memory")
; #define PG8_WAIT_L(n) asm volatile("s_waitcnt lgkmcnt(" #n ")" ::: "memory")
; #define PG8_BAR __builtin_amdgcn_s_barrier()
; #define PG8_SCHED __builtin_amdgcn_sched_barrier(0)
; template <class Epi, class Sched, bool ALIGN_EPI = false, bool SP2 = false>
; __device__ __forceinline__ void gemm_phase(PG8_LAS unsigned char* lds, const Gemm g, const Sched& S, const Epi& E, const int wave_id) {
;     ...
;             PG8_WAIT_V(8); PG8_WAIT_L(0); PG8_BAR; PG8_MMA(1, 0, At, B0); PG8_MMA(1, 1, At, B1); PG8_BAR; PG8_SCHED;
;             PG8_LDB(B0, 1, 0); PG8_LDB(B1, 1, 1); PG8_SCHED; PG8_LDA(At, 1, 0); PG8_STAGE(PG8_SA(0, 1), a2 + hstep, voffA);
;             PG8_WAIT_V(8); PG8_WAIT_L(0); PG8_BAR; PG8_MMA(0, 0, At, B0); PG8_MMA(0, 1, At, B1); PG8_BAR; PG8_SCHED;
	s_nop 0
	s_add_i32 s67, 0, 0x18000
	v_add_u32_e32 v142, s67, v145
	s_add_i32 s68, 0, 0x1c000
	ds_read_b128 v[138:141], v142
	ds_read_b128 v[148:151], v142 offset:1024
	ds_read_b128 v[152:155], v142 offset:2048
	ds_read_b128 v[156:159], v142 offset:3072
	v_add_u32_e32 v142, s68, v145
	ds_read_b128 v[160:163], v142
	ds_read_b128 v[164:167], v142 offset:1024
	ds_read_b128 v[168:171], v142 offset:2048
	ds_read_b128 v[172:175], v142 offset:3072
	s_add_u32 s42, s42, 0x40000
	s_addc_u32 s43, s43, 0
	s_mov_b32 m0, s53
	v_lshl_add_u64 v[218:219], s[42:43], 0, v[128:129]
	ds_read_b128 v[176:179], v146 offset:32768
	ds_read_b128 v[180:183], v146 offset:33792
	ds_read_b128 v[184:187], v146 offset:34816
	ds_read_b128 v[188:191], v146 offset:35840
	ds_read_b128 v[192:195], v146 offset:36864
	ds_read_b128 v[196:199], v146 offset:37888
	ds_read_b128 v[202:205], v146 offset:38912
	ds_read_b128 v[206:209], v146 offset:39936
	global_load_lds_dwordx4 v[218:219], off
	v_lshl_add_u64 v[218:219], s[42:43], 0, v[130:131]
	s_mov_b32 m0, s54
	s_nop 0
	global_load_lds_dwordx4 v[218:219], off
	s_waitcnt vmcnt(8)
	s_waitcnt lgkmcnt(0)
	s_barrier
	s_setprio 1
	s_waitcnt lgkmcnt(0)
	v_mfma_f32_16x16x32_bf16 v[124:127], v[138:141], v[176:179], v[124:127]
	v_mfma_f32_16x16x32_bf16 v[120:123], v[152:155], v[176:179], v[120:123]
	v_mfma_f32_16x16x32_bf16 v[108:111], v[138:141], v[184:187], v[108:111]
	v_mfma_f32_16x16x32_bf16 v[104:107], v[152:155], v[184:187], v[104:107]
	v_mfma_f32_16x16x32_bf16 v[92:95], v[138:141], v[192:195], v[92:95]
	v_mfma_f32_16x16x32_bf16 v[88:91], v[152:155], v[192:195], v[88:91]
	v_mfma_f32_16x16x32_bf16 v[76:79], v[138:141], v[202:205], v[76:79]
	v_mfma_f32_16x16x32_bf16 v[72:75], v[152:155], v[202:205], v[72:75]
	v_mfma_f32_16x16x32_bf16 v[124:127], v[148:151], v[180:183], v[124:127]
	v_mfma_f32_16x16x32_bf16 v[120:123], v[156:159], v[180:183], v[120:123]
	v_mfma_f32_16x16x32_bf16 v[108:111], v[148:151], v[188:191], v[108:111]
	v_mfma_f32_16x16x32_bf16 v[104:107], v[156:159], v[188:191], v[104:107]
	v_mfma_f32_16x16x32_bf16 v[92:95], v[148:151], v[196:199], v[92:95]
	v_mfma_f32_16x16x32_bf16 v[88:91], v[156:159], v[196:199], v[88:91]
	v_mfma_f32_16x16x32_bf16 v[76:79], v[148:151], v[206:209], v[76:79]
	v_mfma_f32_16x16x32_bf16 v[72:75], v[156:159], v[206:209], v[72:75]
	s_setprio 0
	s_setprio 1
	v_mfma_f32_16x16x32_bf16 v[116:119], v[160:163], v[176:179], v[116:119]
	v_mfma_f32_16x16x32_bf16 v[112:115], v[168:171], v[176:179], v[112:115]
	v_mfma_f32_16x16x32_bf16 v[100:103], v[160:163], v[184:187], v[100:103]
	v_mfma_f32_16x16x32_bf16 v[96:99], v[168:171], v[184:187], v[96:99]
	v_mfma_f32_16x16x32_bf16 v[84:87], v[160:163], v[192:195], v[84:87]
	v_mfma_f32_16x16x32_bf16 v[80:83], v[168:171], v[192:195], v[80:83]
	v_mfma_f32_16x16x32_bf16 v[68:71], v[160:163], v[202:205], v[68:71]
	v_mfma_f32_16x16x32_bf16 v[64:67], v[168:171], v[202:205], v[64:67]
	v_mfma_f32_16x16x32_bf16 v[116:119], v[164:167], v[180:183], v[116:119]
	v_mfma_f32_16x16x32_bf16 v[112:115], v[172:175], v[180:183], v[112:115]
	v_mfma_f32_16x16x32_bf16 v[100:103], v[164:167], v[188:191], v[100:103]
	v_mfma_f32_16x16x32_bf16 v[96:99], v[172:175], v[188:191], v[96:99]
	v_mfma_f32_16x16x32_bf16 v[84:87], v[164:167], v[196:199], v[84:87]
	v_mfma_f32_16x16x32_bf16 v[80:83], v[172:175], v[196:199], v[80:83]
	v_mfma_f32_16x16x32_bf16 v[68:71], v[164:167], v[206:209], v[68:71]
	v_mfma_f32_16x16x32_bf16 v[64:67], v[172:175], v[206:209], v[64:67]
	s_setprio 0
	s_barrier
; #define PG8_STAGE(bufoff, gbase, voff) do { _Pragma("unroll") for (int _i = 0; _i < 2; ++_i) \
;         __builtin_amdgcn_global_load_lds((const unsigned*)((const char*)(gbase) + (voff)[_i]), (PG8_LAS unsigned*)(lds + (bufoff) + ldsw + _i * 8192), 16, 0, 0); } while (0)
; #define PG8_LDA(dst, b, h) do { _Pragma("unroll") for (int m = 0; m < 4; ++m) _Pragma("unroll") for (int k = 0; k < 2; ++k) dst[m][k] = *(const PG8_LAS bf16x8*)(lds + PG8_SA(b, h) + aoff + m * 2048 + k * 1024); } while (0)
; #define PG8_MMA(ai, bj, At, Bt) do { __builtin_amdgcn_s_setprio(1); _Pragma("unroll") for (int m = 0; m < 4; ++m) _Pragma("unroll") for (int n = 0; n < 2; ++n) _Pragma("unroll") for (int k = 0; k < 2; ++k) \
;         acc[ai][bj][m][n] = __builtin_amdgcn_mfma_f32_16x16x32_bf16(Bt[n][k], At[m][k], acc[ai][bj][m][n], 0, 0, 0); __builtin_amdgcn_s_setprio(0); } while (0)
; #define PG8_WAIT_V(n) asm volatile("s_waitcnt vmcnt(" #n ")" ::: "memory")
; #define PG8_WAIT_L(n) asm volatile("s_waitcnt lgkmcnt(" #n ")" ::: "memory")
; #define PG8_BAR __builtin_amdgcn_s_barrier()
; #define PG8_SCHED __builtin_amdgcn_sched_barrier(0)
; template <class Epi, class Sched, bool ALIGN_EPI = false, bool SP2 = false>
; __device__ __forceinline__ void gemm_phase(PG8_LAS unsigned char* lds, const Gemm g, const Sched& S, const Epi& E, const int wave_id) {
;     ...
;             PG8_WAIT_V(8); PG8_WAIT_L(0); PG8_BAR; PG8_MMA(0, 0, At, B0); PG8_MMA(0, 1, At, B1); PG8_BAR; PG8_SCHED;
;             PG8_LDA(At, 1, 1); PG8_STAGE(PG8_SB(1, 0), b3, voffB); PG8_STAGE(PG8_SB(1, 1), b3 + hstep, voffB); PG8_STAGE(PG8_SA(1, 0), a3, voffA);
;             PG8_WAIT_V(8); PG8_WAIT_L(0); PG8_BAR; PG8_MMA(1, 0, At, B0); PG8_MMA(1, 1, At, B1); PG8_BAR; PG8_SCHED;
;     ...
;         if constexpr (ALIGN_EPI) { if (wr == 0) PG8_BAR; }
	s_add_i32 s42, s67, s17
	v_lshl_add_u64 v[210:211], v[210:211], 0, s[88:89]
	s_mov_b32 m0, s42
	ds_read_b128 v[176:179], v146 offset:49152
	ds_read_b128 v[180:183], v146 offset:50176
	ds_read_b128 v[184:187], v146 offset:51200
	ds_read_b128 v[188:191], v146 offset:52224
	ds_read_b128 v[192:195], v146 offset:53248
	ds_read_b128 v[196:199], v146 offset:54272
	ds_read_b128 v[202:205], v146 offset:55296
	ds_read_b128 v[206:209], v146 offset:56320
	global_load_lds_dwordx4 v[210:211], off
	s_add_i32 m0, s42, 0x2000
	s_add_u32 s40, s40, 0x40080
	v_lshl_add_u64 v[210:211], v[212:213], 0, s[88:89]
	s_addc_u32 s41, s41, 0
	s_add_i32 s42, s68, s17
	global_load_lds_dwordx4 v[210:211], off
	v_lshl_add_u64 v[210:211], s[40:41], 0, v[200:201]
	s_mov_b32 m0, s42
	s_nop 0
	global_load_lds_dwordx4 v[210:211], off
	v_lshl_add_u64 v[210:211], s[40:41], 0, v[132:133]
	s_add_i32 m0, s42, 0x2000
	s_nop 0
	global_load_lds_dwordx4 v[210:211], off
	v_lshl_add_u64 v[210:211], v[214:215], 0, s[88:89]
	s_mov_b32 m0, s55
	s_nop 0
	global_load_lds_dwordx4 v[210:211], off
	v_lshl_add_u64 v[210:211], v[216:217], 0, s[88:89]
	s_mov_b32 m0, s56
	s_nop 0
	global_load_lds_dwordx4 v[210:211], off
	s_waitcnt vmcnt(8)
	s_waitcnt lgkmcnt(0)
	s_barrier
	s_setprio 1
	s_waitcnt lgkmcnt(0)
	v_mfma_f32_16x16x32_bf16 v[60:63], v[138:141], v[176:179], v[60:63]
	v_mfma_f32_16x16x32_bf16 v[56:59], v[152:155], v[176:179], v[56:59]
	v_mfma_f32_16x16x32_bf16 v[44:47], v[138:141], v[184:187], v[44:47]
	v_mfma_f32_16x16x32_bf16 v[40:43], v[152:155], v[184:187], v[40:43]
	v_mfma_f32_16x16x32_bf16 v[28:31], v[138:141], v[192:195], v[28:31]
	v_mfma_f32_16x16x32_bf16 v[24:27], v[152:155], v[192:195], v[24:27]
	v_mfma_f32_16x16x32_bf16 v[12:15], v[138:141], v[202:205], v[12:15]
	v_mfma_f32_16x16x32_bf16 v[8:11], v[152:155], v[202:205], v[8:11]
	v_mfma_f32_16x16x32_bf16 v[60:63], v[148:151], v[180:183], v[60:63]
	v_mfma_f32_16x16x32_bf16 v[56:59], v[156:159], v[180:183], v[56:59]
	v_mfma_f32_16x16x32_bf16 v[44:47], v[148:151], v[188:191], v[44:47]
	v_mfma_f32_16x16x32_bf16 v[40:43], v[156:159], v[188:191], v[40:43]
	v_mfma_f32_16x16x32_bf16 v[28:31], v[148:151], v[196:199], v[28:31]
	v_mfma_f32_16x16x32_bf16 v[24:27], v[156:159], v[196:199], v[24:27]
	v_mfma_f32_16x16x32_bf16 v[12:15], v[148:151], v[206:209], v[12:15]
	v_mfma_f32_16x16x32_bf16 v[8:11], v[156:159], v[206:209], v[8:11]
	s_setprio 0
	s_setprio 1
	v_mfma_f32_16x16x32_bf16 v[52:55], v[160:163], v[176:179], v[52:55]
	v_mfma_f32_16x16x32_bf16 v[48:51], v[168:171], v[176:179], v[48:51]
	v_mfma_f32_16x16x32_bf16 v[36:39], v[160:163], v[184:187], v[36:39]
	v_mfma_f32_16x16x32_bf16 v[32:35], v[168:171], v[184:187], v[32:35]
	v_mfma_f32_16x16x32_bf16 v[20:23], v[160:163], v[192:195], v[20:23]
	v_mfma_f32_16x16x32_bf16 v[16:19], v[168:171], v[192:195], v[16:19]
	v_mfma_f32_16x16x32_bf16 v[4:7], v[160:163], v[202:205], v[4:7]
	v_mfma_f32_16x16x32_bf16 v[0:3], v[168:171], v[202:205], v[0:3]
	v_mfma_f32_16x16x32_bf16 v[52:55], v[164:167], v[180:183], v[52:55]
	v_mfma_f32_16x16x32_bf16 v[48:51], v[172:175], v[180:183], v[48:51]
	v_mfma_f32_16x16x32_bf16 v[36:39], v[164:167], v[188:191], v[36:39]
	v_mfma_f32_16x16x32_bf16 v[32:35], v[172:175], v[188:191], v[32:35]
	v_mfma_f32_16x16x32_bf16 v[20:23], v[164:167], v[196:199], v[20:23]
	v_mfma_f32_16x16x32_bf16 v[16:19], v[172:175], v[196:199], v[16:19]
	v_mfma_f32_16x16x32_bf16 v[4:7], v[164:167], v[206:209], v[4:7]
	v_mfma_f32_16x16x32_bf16 v[0:3], v[172:175], v[206:209], v[0:3]
	s_setprio 0
	s_barrier
	s_add_i32 s65, s65, 2
	s_add_u32 s38, s38, 0x100
	s_addc_u32 s39, s39, 0
	s_add_u32 s63, s63, 0x100
	s_addc_u32 s64, s64, 0
	s_cmp_gt_u32 s65, 13
	s_cbranch_scc0 .LBB0_1863
	s_and_b64 vcc, exec, s[24:25]
	s_cbranch_vccz .LBB0_1866
	s_barrier

; #define PG8_STAGE(bufoff, gbase, voff) do { _Pragma("unroll") for (int _i = 0; _i < 2; ++_i) \
;         __builtin_amdgcn_global_load_lds((const unsigned*)((const char*)(gbase) + (voff)[_i]), (PG8_LAS unsigned*)(lds + (bufoff) + ldsw + _i * 8192), 16, 0, 0); } while (0)
; #define PG8_LDA(dst, b, h) do { _Pragma("unroll") for (int m = 0; m < 4; ++m) _Pragma("unroll") for (int k = 0; k < 2; ++k) dst[m][k] = *(const PG8_LAS bf16x8*)(lds + PG8_SA(b, h) + aoff + m * 2048 + k * 1024); } while (0)
; #define PG8_LDB(dst, b, h) do { _Pragma("unroll") for (int n = 0; n < 2; ++n) _Pragma("unroll") for (int k = 0; k < 2; ++k) dst[n][k] = *(const PG8_LAS bf16x8*)(lds + PG8_SB(b, h) + boff + n * 2048 + k * 1024); } while (0)
; #define PG8_MMA(ai, bj, At, Bt) do { __builtin_amdgcn_s_setprio(1); _Pragma("unroll") for (int m = 0; m < 4; ++m) _Pragma("unroll") for (int n = 0; n < 2; ++n) _Pragma("unroll") for (int k = 0; k < 2; ++k) \
;         acc[ai][bj][m][n] = __builtin_amdgcn_mfma_f32_16x16x32_bf16(Bt[n][k], At[m][k], acc[ai][bj][m][n], 0, 0, 0); __builtin_amdgcn_s_setprio(0); } while (0)
; #define PG8_WAIT_V(n) asm volatile("s_waitcnt vmcnt(" #n ")" ::: "memory")
; #define PG8_WAIT_L(n) asm volatile("s_waitcnt lgkmcnt(" #n ")" ::: "memory")
; #define PG8_BAR __builtin_amdgcn_s_barrier()
; #define PG8_SCHED __builtin_amdgcn_sched_barrier(0)
; template <class Epi, class Sched, bool ALIGN_EPI = false, bool SP2 = false>
; __device__ __forceinline__ void gemm_phase(PG8_LAS unsigned char* lds, const Gemm g, const Sched& S, const Epi& E, const int wave_id) {
;     ...
;             PG8_LDB(B0, 0, 0); PG8_LDB(B1, 0, 1); PG8_SCHED; PG8_LDA(At, 0, 0); PG8_STAGE(PG8_SA(1, 1), a1 + hstep, voffA);
;             PG8_WAIT_V(8); PG8_WAIT_L(0); PG8_BAR; PG8_MMA(0, 0, At, B0); PG8_MMA(0, 1, At, B1); PG8_BAR; PG8_SCHED;
;             PG8_LDA(At, 0, 1); PG8_STAGE(PG8_SB(0, 0), b2, voffB); PG8_STAGE(PG8_SB(0, 1), b2 + hstep, voffB); PG8_STAGE(PG8_SA(0, 0), a2, voffA);
.LBB0_2237:
	s_add_u32 s34, s36, 0xfffc0080
	s_addc_u32 s35, s37, -1
	s_add_i32 s63, 0, 0x10000
	s_cmp_eq_u32 s62, 12
	s_cselect_b32 s39, s23, s35
	s_cselect_b32 s38, s29, s34
	s_cselect_b32 s35, s21, s61
	s_cselect_b32 s34, s31, s60
	s_add_i32 s67, 0, 0x14000
	v_add_u32_e32 v154, s63, v140
	v_add_u32_e32 v170, s67, v140
	ds_read_b128 v[142:145], v154
	ds_read_b128 v[146:149], v154 offset:1024
	ds_read_b128 v[150:153], v154 offset:2048
	ds_read_b128 v[154:157], v154 offset:3072
	ds_read_b128 v[158:161], v170
	ds_read_b128 v[162:165], v170 offset:1024
	ds_read_b128 v[166:169], v170 offset:2048
	ds_read_b128 v[170:173], v170 offset:3072
	v_lshl_add_u64 v[198:199], s[36:37], 0, v[134:135]
	s_add_i32 m0, s49, 0xc000
	ds_read_b128 v[174:177], v141
	ds_read_b128 v[178:181], v141 offset:1024
	ds_read_b128 v[182:185], v141 offset:2048
	ds_read_b128 v[186:189], v141 offset:3072
	ds_read_b128 v[190:193], v141 offset:4096
	ds_read_b128 v[194:197], v141 offset:5120
	ds_read_b128 v[202:205], v141 offset:6144
	ds_read_b128 v[206:209], v141 offset:7168
	global_load_lds_dwordx4 v[198:199], off
	v_lshl_add_u64 v[198:199], s[36:37], 0, v[136:137]
	s_add_i32 m0, s49, 0xe000
	s_nop 0
	global_load_lds_dwordx4 v[198:199], off
	s_waitcnt vmcnt(8)
	s_waitcnt lgkmcnt(0)
	s_barrier
	s_setprio 1
	s_waitcnt lgkmcnt(0)
	v_mfma_f32_16x16x32_bf16 v[112:115], v[142:145], v[174:177], v[112:115]
	v_mfma_f32_16x16x32_bf16 v[116:119], v[150:153], v[174:177], v[116:119]
	v_mfma_f32_16x16x32_bf16 v[96:99], v[142:145], v[182:185], v[96:99]
	v_mfma_f32_16x16x32_bf16 v[100:103], v[150:153], v[182:185], v[100:103]
	v_mfma_f32_16x16x32_bf16 v[80:83], v[142:145], v[190:193], v[80:83]
	v_mfma_f32_16x16x32_bf16 v[84:87], v[150:153], v[190:193], v[84:87]
	v_mfma_f32_16x16x32_bf16 v[60:63], v[142:145], v[202:205], v[60:63]
	v_mfma_f32_16x16x32_bf16 v[68:71], v[150:153], v[202:205], v[68:71]
	v_mfma_f32_16x16x32_bf16 v[112:115], v[146:149], v[178:181], v[112:115]
	v_mfma_f32_16x16x32_bf16 v[116:119], v[154:157], v[178:181], v[116:119]
	v_mfma_f32_16x16x32_bf16 v[96:99], v[146:149], v[186:189], v[96:99]
	v_mfma_f32_16x16x32_bf16 v[100:103], v[154:157], v[186:189], v[100:103]
	v_mfma_f32_16x16x32_bf16 v[80:83], v[146:149], v[194:197], v[80:83]
	v_mfma_f32_16x16x32_bf16 v[84:87], v[154:157], v[194:197], v[84:87]
	v_mfma_f32_16x16x32_bf16 v[60:63], v[146:149], v[206:209], v[60:63]
	v_mfma_f32_16x16x32_bf16 v[68:71], v[154:157], v[206:209], v[68:71]
	s_setprio 0
	s_setprio 1
	v_mfma_f32_16x16x32_bf16 v[120:123], v[158:161], v[174:177], v[120:123]
	v_mfma_f32_16x16x32_bf16 v[124:127], v[166:169], v[174:177], v[124:127]
	v_mfma_f32_16x16x32_bf16 v[104:107], v[158:161], v[182:185], v[104:107]
	v_mfma_f32_16x16x32_bf16 v[108:111], v[166:169], v[182:185], v[108:111]
	v_mfma_f32_16x16x32_bf16 v[88:91], v[158:161], v[190:193], v[88:91]
	v_mfma_f32_16x16x32_bf16 v[92:95], v[166:169], v[190:193], v[92:95]
	v_mfma_f32_16x16x32_bf16 v[72:75], v[158:161], v[202:205], v[72:75]
	v_mfma_f32_16x16x32_bf16 v[76:79], v[166:169], v[202:205], v[76:79]
	v_mfma_f32_16x16x32_bf16 v[120:123], v[162:165], v[178:181], v[120:123]
	v_mfma_f32_16x16x32_bf16 v[124:127], v[170:173], v[178:181], v[124:127]
	v_mfma_f32_16x16x32_bf16 v[104:107], v[162:165], v[186:189], v[104:107]
	v_mfma_f32_16x16x32_bf16 v[108:111], v[170:173], v[186:189], v[108:111]
	v_mfma_f32_16x16x32_bf16 v[88:91], v[162:165], v[194:197], v[88:91]
	v_mfma_f32_16x16x32_bf16 v[92:95], v[170:173], v[194:197], v[92:95]
	v_mfma_f32_16x16x32_bf16 v[72:75], v[162:165], v[206:209], v[72:75]
	v_mfma_f32_16x16x32_bf16 v[76:79], v[170:173], v[206:209], v[76:79]
	s_setprio 0
	s_barrier
	s_nop 0
	s_add_i32 s63, s63, s46
	v_lshl_add_u64 v[198:199], s[34:35], 0, v[200:201]
	s_mov_b32 m0, s63
	ds_read_b128 v[174:177], v141 offset:16384
	ds_read_b128 v[178:181], v141 offset:17408
	ds_read_b128 v[182:185], v141 offset:18432
	ds_read_b128 v[186:189], v141 offset:19456
	ds_read_b128 v[190:193], v141 offset:20480
	ds_read_b128 v[194:197], v141 offset:21504
	ds_read_b128 v[202:205], v141 offset:22528
	ds_read_b128 v[206:209], v141 offset:23552
	global_load_lds_dwordx4 v[198:199], off
	s_add_i32 m0, s63, 0x2000
	s_add_u32 s64, s34, 0x40000
	v_lshl_add_u64 v[210:211], s[34:35], 0, v[132:133]
	s_addc_u32 s65, s35, 0
	s_add_i32 s63, s67, s46
	global_load_lds_dwordx4 v[210:211], off
	v_lshl_add_u64 v[212:213], s[64:65], 0, v[200:201]
	s_mov_b32 m0, s63
	v_lshl_add_u64 v[214:215], s[38:39], 0, v[130:131]
	global_load_lds_dwordx4 v[212:213], off
	v_lshl_add_u64 v[212:213], s[64:65], 0, v[132:133]
	s_add_i32 m0, s63, 0x2000
	s_nop 0
	global_load_lds_dwordx4 v[212:213], off
	v_lshl_add_u64 v[212:213], s[38:39], 0, v[128:129]
	s_mov_b32 m0, s49
	s_nop 0
	global_load_lds_dwordx4 v[212:213], off
	s_mov_b32 m0, s50
	s_nop 0
	global_load_lds_dwordx4 v[214:215], off
	s_waitcnt vmcnt(8)
	s_waitcnt lgkmcnt(0)
	s_barrier
; #define PG8_STAGE(bufoff, gbase, voff) do { _Pragma("unroll") for (int _i = 0; _i < 2; ++_i) \
;         __builtin_amdgcn_global_load_lds((const unsigned*)((const char*)(gbase) + (voff)[_i]), (PG8_LAS unsigned*)(lds + (bufoff) + ldsw + _i * 8192), 16, 0, 0); } while (0)
; #define PG8_LDA(dst, b, h) do { _Pragma("unroll") for (int m = 0; m < 4; ++m) _Pragma("unroll") for (int k = 0; k < 2; ++k) dst[m][k] = *(const PG8_LAS bf16x8*)(lds + PG8_SA(b, h) + aoff + m * 2048 + k * 1024); } while (0)
; #define PG8_LDB(dst, b, h) do { _Pragma("unroll") for (int n = 0; n < 2; ++n) _Pragma("unroll") for (int k = 0; k < 2; ++k) dst[n][k] = *(const PG8_LAS bf16x8*)(lds + PG8_SB(b, h) + boff + n * 2048 + k * 1024); } while (0)
; #define PG8_MMA(ai, bj, At, Bt) do { __builtin_amdgcn_s_setprio(1); _Pragma("unroll") for (int m = 0; m < 4; ++m) _Pragma("unroll") for (int n = 0; n < 2; ++n) _Pragma("unroll") for (int k = 0; k < 2; ++k) \
;         acc[ai][bj][m][n] = __builtin_amdgcn_mfma_f32_16x16x32_bf16(Bt[n][k], At[m][k], acc[ai][bj][m][n], 0, 0, 0); __builtin_amdgcn_s_setprio(0); } while (0)
; #define PG8_WAIT_V(n) asm volatile("s_waitcnt vmcnt(" #n ")" ::: "memory")
; #define PG8_WAIT_L(n) asm volatile("s_waitcnt lgkmcnt(" #n ")" ::: "memory")
; #define PG8_BAR __builtin_amdgcn_s_barrier()
; #define PG8_SCHED __builtin_amdgcn_sched_barrier(0)
; template <class Epi, class Sched, bool ALIGN_EPI = false, bool SP2 = false>
; __device__ __forceinline__ void gemm_phase(PG8_LAS unsigned char* lds, const Gemm g, const Sched& S, const Epi& E, const int wave_id) {
;     ...
;             PG8_WAIT_V(8); PG8_WAIT_L(0); PG8_BAR; PG8_MMA(1, 0, At, B0); PG8_MMA(1, 1, At, B1); PG8_BAR; PG8_SCHED;
;             PG8_LDB(B0, 1, 0); PG8_LDB(B1, 1, 1); PG8_SCHED; PG8_LDA(At, 1, 0); PG8_STAGE(PG8_SA(0, 1), a2 + hstep, voffA);
;             PG8_WAIT_V(8); PG8_WAIT_L(0); PG8_BAR; PG8_MMA(0, 0, At, B0); PG8_MMA(0, 1, At, B1); PG8_BAR; PG8_SCHED;
	s_setprio 1
	s_waitcnt lgkmcnt(0)
	v_mfma_f32_16x16x32_bf16 v[48:51], v[142:145], v[174:177], v[48:51]
	v_mfma_f32_16x16x32_bf16 v[52:55], v[150:153], v[174:177], v[52:55]
	v_mfma_f32_16x16x32_bf16 v[32:35], v[142:145], v[182:185], v[32:35]
	v_mfma_f32_16x16x32_bf16 v[36:39], v[150:153], v[182:185], v[36:39]
	v_mfma_f32_16x16x32_bf16 v[16:19], v[142:145], v[190:193], v[16:19]
	v_mfma_f32_16x16x32_bf16 v[20:23], v[150:153], v[190:193], v[20:23]
	v_mfma_f32_16x16x32_bf16 v[0:3], v[142:145], v[202:205], v[0:3]
	v_mfma_f32_16x16x32_bf16 v[4:7], v[150:153], v[202:205], v[4:7]
	v_mfma_f32_16x16x32_bf16 v[48:51], v[146:149], v[178:181], v[48:51]
	v_mfma_f32_16x16x32_bf16 v[52:55], v[154:157], v[178:181], v[52:55]
	v_mfma_f32_16x16x32_bf16 v[32:35], v[146:149], v[186:189], v[32:35]
	v_mfma_f32_16x16x32_bf16 v[36:39], v[154:157], v[186:189], v[36:39]
	v_mfma_f32_16x16x32_bf16 v[16:19], v[146:149], v[194:197], v[16:19]
	v_mfma_f32_16x16x32_bf16 v[20:23], v[154:157], v[194:197], v[20:23]
	v_mfma_f32_16x16x32_bf16 v[0:3], v[146:149], v[206:209], v[0:3]
	v_mfma_f32_16x16x32_bf16 v[4:7], v[154:157], v[206:209], v[4:7]
	s_setprio 0
	s_setprio 1
	v_mfma_f32_16x16x32_bf16 v[56:59], v[158:161], v[174:177], v[56:59]
	v_mfma_f32_16x16x32_bf16 v[64:67], v[166:169], v[174:177], v[64:67]
	v_mfma_f32_16x16x32_bf16 v[40:43], v[158:161], v[182:185], v[40:43]
	v_mfma_f32_16x16x32_bf16 v[44:47], v[166:169], v[182:185], v[44:47]
	v_mfma_f32_16x16x32_bf16 v[24:27], v[158:161], v[190:193], v[24:27]
	v_mfma_f32_16x16x32_bf16 v[28:31], v[166:169], v[190:193], v[28:31]
	v_mfma_f32_16x16x32_bf16 v[8:11], v[158:161], v[202:205], v[8:11]
	v_mfma_f32_16x16x32_bf16 v[12:15], v[166:169], v[202:205], v[12:15]
	v_mfma_f32_16x16x32_bf16 v[56:59], v[162:165], v[178:181], v[56:59]
	v_mfma_f32_16x16x32_bf16 v[64:67], v[170:173], v[178:181], v[64:67]
	v_mfma_f32_16x16x32_bf16 v[40:43], v[162:165], v[186:189], v[40:43]
	v_mfma_f32_16x16x32_bf16 v[44:47], v[170:173], v[186:189], v[44:47]
	v_mfma_f32_16x16x32_bf16 v[24:27], v[162:165], v[194:197], v[24:27]
	v_mfma_f32_16x16x32_bf16 v[28:31], v[170:173], v[194:197], v[28:31]
	v_mfma_f32_16x16x32_bf16 v[8:11], v[162:165], v[206:209], v[8:11]
	v_mfma_f32_16x16x32_bf16 v[12:15], v[170:173], v[206:209], v[12:15]
	s_setprio 0
	s_barrier
	s_nop 0
	s_add_i32 s63, 0, 0x18000
	s_add_i32 s64, 0, 0x1c000
	v_add_u32_e32 v154, s63, v140
	v_add_u32_e32 v170, s64, v140
	ds_read_b128 v[142:145], v154
	ds_read_b128 v[146:149], v154 offset:1024
	ds_read_b128 v[150:153], v154 offset:2048
	ds_read_b128 v[154:157], v154 offset:3072
	ds_read_b128 v[158:161], v170
	ds_read_b128 v[162:165], v170 offset:1024
	ds_read_b128 v[166:169], v170 offset:2048
	ds_read_b128 v[170:173], v170 offset:3072
	s_add_u32 s38, s38, 0x40000
	s_addc_u32 s39, s39, 0
	s_mov_b32 m0, s51
	v_lshl_add_u64 v[216:217], s[38:39], 0, v[128:129]
	ds_read_b128 v[174:177], v141 offset:32768
	ds_read_b128 v[178:181], v141 offset:33792
	ds_read_b128 v[182:185], v141 offset:34816
	ds_read_b128 v[186:189], v141 offset:35840
	ds_read_b128 v[190:193], v141 offset:36864
	ds_read_b128 v[194:197], v141 offset:37888
	ds_read_b128 v[202:205], v141 offset:38912
	ds_read_b128 v[206:209], v141 offset:39936
	global_load_lds_dwordx4 v[216:217], off
	v_lshl_add_u64 v[216:217], s[38:39], 0, v[130:131]
	s_mov_b32 m0, s52
	s_nop 0
	global_load_lds_dwordx4 v[216:217], off
	s_waitcnt vmcnt(8)
	s_waitcnt lgkmcnt(0)
	s_barrier
	s_setprio 1
	s_waitcnt lgkmcnt(0)
	v_mfma_f32_16x16x32_bf16 v[112:115], v[142:145], v[174:177], v[112:115]
	v_mfma_f32_16x16x32_bf16 v[116:119], v[150:153], v[174:177], v[116:119]
	v_mfma_f32_16x16x32_bf16 v[96:99], v[142:145], v[182:185], v[96:99]
	v_mfma_f32_16x16x32_bf16 v[100:103], v[150:153], v[182:185], v[100:103]
	v_mfma_f32_16x16x32_bf16 v[80:83], v[142:145], v[190:193], v[80:83]
	v_mfma_f32_16x16x32_bf16 v[84:87], v[150:153], v[190:193], v[84:87]
	v_mfma_f32_16x16x32_bf16 v[60:63], v[142:145], v[202:205], v[60:63]
	v_mfma_f32_16x16x32_bf16 v[68:71], v[150:153], v[202:205], v[68:71]
	v_mfma_f32_16x16x32_bf16 v[112:115], v[146:149], v[178:181], v[112:115]
	v_mfma_f32_16x16x32_bf16 v[116:119], v[154:157], v[178:181], v[116:119]
	v_mfma_f32_16x16x32_bf16 v[96:99], v[146:149], v[186:189], v[96:99]
	v_mfma_f32_16x16x32_bf16 v[100:103], v[154:157], v[186:189], v[100:103]
	v_mfma_f32_16x16x32_bf16 v[80:83], v[146:149], v[194:197], v[80:83]
	v_mfma_f32_16x16x32_bf16 v[84:87], v[154:157], v[194:197], v[84:87]
	v_mfma_f32_16x16x32_bf16 v[60:63], v[146:149], v[206:209], v[60:63]
	v_mfma_f32_16x16x32_bf16 v[68:71], v[154:157], v[206:209], v[68:71]
	s_setprio 0
	s_setprio 1
	v_mfma_f32_16x16x32_bf16 v[120:123], v[158:161], v[174:177], v[120:123]
	v_mfma_f32_16x16x32_bf16 v[124:127], v[166:169], v[174:177], v[124:127]
	v_mfma_f32_16x16x32_bf16 v[104:107], v[158:161], v[182:185], v[104:107]
	v_mfma_f32_16x16x32_bf16 v[108:111], v[166:169], v[182:185], v[108:111]
	v_mfma_f32_16x16x32_bf16 v[88:91], v[158:161], v[190:193], v[88:91]
	v_mfma_f32_16x16x32_bf16 v[92:95], v[166:169], v[190:193], v[92:95]
	v_mfma_f32_16x16x32_bf16 v[72:75], v[158:161], v[202:205], v[72:75]
	v_mfma_f32_16x16x32_bf16 v[76:79], v[166:169], v[202:205], v[76:79]
	v_mfma_f32_16x16x32_bf16 v[120:123], v[162:165], v[178:181], v[120:123]
	v_mfma_f32_16x16x32_bf16 v[124:127], v[170:173], v[178:181], v[124:127]
	v_mfma_f32_16x16x32_bf16 v[104:107], v[162:165], v[186:189], v[104:107]
	v_mfma_f32_16x16x32_bf16 v[108:111], v[170:173], v[186:189], v[108:111]
	v_mfma_f32_16x16x32_bf16 v[88:91], v[162:165], v[194:197], v[88:91]
	v_mfma_f32_16x16x32_bf16 v[92:95], v[170:173], v[194:197], v[92:95]
	v_mfma_f32_16x16x32_bf16 v[72:75], v[162:165], v[206:209], v[72:75]
	v_mfma_f32_16x16x32_bf16 v[76:79], v[170:173], v[206:209], v[76:79]
	s_setprio 0
	s_barrier
; #define PG8_STAGE(bufoff, gbase, voff) do { _Pragma("unroll") for (int _i = 0; _i < 2; ++_i) \
;         __builtin_amdgcn_global_load_lds((const unsigned*)((const char*)(gbase) + (voff)[_i]), (PG8_LAS unsigned*)(lds + (bufoff) + ldsw + _i * 8192), 16, 0, 0); } while (0)
; #define PG8_LDA(dst, b, h) do { _Pragma("unroll") for (int m = 0; m < 4; ++m) _Pragma("unroll") for (int k = 0; k < 2; ++k) dst[m][k] = *(const PG8_LAS bf16x8*)(lds + PG8_SA(b, h) + aoff + m * 2048 + k * 1024); } while (0)
; #define PG8_MMA(ai, bj, At, Bt) do { __builtin_amdgcn_s_setprio(1); _Pragma("unroll") for (int m = 0; m < 4; ++m) _Pragma("unroll") for (int n = 0; n < 2; ++n) _Pragma("unroll") for (int k = 0; k < 2; ++k) \
;         acc[ai][bj][m][n] = __builtin_amdgcn_mfma_f32_16x16x32_bf16(Bt[n][k], At[m][k], acc[ai][bj][m][n], 0, 0, 0); __builtin_amdgcn_s_setprio(0); } while (0)
; #define PG8_WAIT_V(n) asm volatile("s_waitcnt vmcnt(" #n ")" ::: "memory")
; #define PG8_WAIT_L(n) asm volatile("s_waitcnt lgkmcnt(" #n ")" ::: "memory")
; #define PG8_BAR __builtin_amdgcn_s_barrier()
; #define PG8_SCHED __builtin_amdgcn_sched_barrier(0)
; template <class Epi, class Sched, bool ALIGN_EPI = false, bool SP2 = false>
; __device__ __forceinline__ void gemm_phase(PG8_LAS unsigned char* lds, const Gemm g, const Sched& S, const Epi& E, const int wave_id) {
;     ...
;             PG8_WAIT_V(8); PG8_WAIT_L(0); PG8_BAR; PG8_MMA(0, 0, At, B0); PG8_MMA(0, 1, At, B1); PG8_BAR; PG8_SCHED;
;             PG8_LDA(At, 1, 1); PG8_STAGE(PG8_SB(1, 0), b3, voffB); PG8_STAGE(PG8_SB(1, 1), b3 + hstep, voffB); PG8_STAGE(PG8_SA(1, 0), a3, voffA);
;             PG8_WAIT_V(8); PG8_WAIT_L(0); PG8_BAR; PG8_MMA(1, 0, At, B0); PG8_MMA(1, 1, At, B1); PG8_BAR; PG8_SCHED;
;     ...
;         if constexpr (ALIGN_EPI) { if (wr == 0) PG8_BAR; }
	s_add_i32 s38, s63, s46
	v_lshl_add_u64 v[198:199], v[198:199], 0, s[88:89]
	s_mov_b32 m0, s38
	ds_read_b128 v[174:177], v141 offset:49152
	ds_read_b128 v[178:181], v141 offset:50176
	ds_read_b128 v[182:185], v141 offset:51200
	ds_read_b128 v[186:189], v141 offset:52224
	ds_read_b128 v[190:193], v141 offset:53248
	ds_read_b128 v[194:197], v141 offset:54272
	ds_read_b128 v[202:205], v141 offset:55296
	ds_read_b128 v[206:209], v141 offset:56320
	global_load_lds_dwordx4 v[198:199], off
	s_add_i32 m0, s38, 0x2000
	s_add_u32 s34, s34, 0x40080
	v_lshl_add_u64 v[198:199], v[210:211], 0, s[88:89]
	s_addc_u32 s35, s35, 0
	s_add_i32 s38, s64, s46
	global_load_lds_dwordx4 v[198:199], off
	v_lshl_add_u64 v[198:199], s[34:35], 0, v[200:201]
	s_mov_b32 m0, s38
	s_nop 0
	global_load_lds_dwordx4 v[198:199], off
	v_lshl_add_u64 v[198:199], s[34:35], 0, v[132:133]
	s_add_i32 m0, s38, 0x2000
	s_nop 0
	global_load_lds_dwordx4 v[198:199], off
	v_lshl_add_u64 v[198:199], v[212:213], 0, s[88:89]
	s_mov_b32 m0, s53
	s_nop 0
	global_load_lds_dwordx4 v[198:199], off
	v_lshl_add_u64 v[198:199], v[214:215], 0, s[88:89]
	s_mov_b32 m0, s54
	s_nop 0
	global_load_lds_dwordx4 v[198:199], off
	s_waitcnt vmcnt(8)
	s_waitcnt lgkmcnt(0)
	s_barrier
	s_setprio 1
	s_waitcnt lgkmcnt(0)
	v_mfma_f32_16x16x32_bf16 v[48:51], v[142:145], v[174:177], v[48:51]
	v_mfma_f32_16x16x32_bf16 v[52:55], v[150:153], v[174:177], v[52:55]
	v_mfma_f32_16x16x32_bf16 v[32:35], v[142:145], v[182:185], v[32:35]
	v_mfma_f32_16x16x32_bf16 v[36:39], v[150:153], v[182:185], v[36:39]
	v_mfma_f32_16x16x32_bf16 v[16:19], v[142:145], v[190:193], v[16:19]
	v_mfma_f32_16x16x32_bf16 v[20:23], v[150:153], v[190:193], v[20:23]
	v_mfma_f32_16x16x32_bf16 v[0:3], v[142:145], v[202:205], v[0:3]
	v_mfma_f32_16x16x32_bf16 v[4:7], v[150:153], v[202:205], v[4:7]
	v_mfma_f32_16x16x32_bf16 v[48:51], v[146:149], v[178:181], v[48:51]
	v_mfma_f32_16x16x32_bf16 v[52:55], v[154:157], v[178:181], v[52:55]
	v_mfma_f32_16x16x32_bf16 v[32:35], v[146:149], v[186:189], v[32:35]
	v_mfma_f32_16x16x32_bf16 v[36:39], v[154:157], v[186:189], v[36:39]
	v_mfma_f32_16x16x32_bf16 v[16:19], v[146:149], v[194:197], v[16:19]
	v_mfma_f32_16x16x32_bf16 v[20:23], v[154:157], v[194:197], v[20:23]
	v_mfma_f32_16x16x32_bf16 v[0:3], v[146:149], v[206:209], v[0:3]
	v_mfma_f32_16x16x32_bf16 v[4:7], v[154:157], v[206:209], v[4:7]
	s_setprio 0
	s_setprio 1
	v_mfma_f32_16x16x32_bf16 v[56:59], v[158:161], v[174:177], v[56:59]
	v_mfma_f32_16x16x32_bf16 v[64:67], v[166:169], v[174:177], v[64:67]
	v_mfma_f32_16x16x32_bf16 v[40:43], v[158:161], v[182:185], v[40:43]
	v_mfma_f32_16x16x32_bf16 v[44:47], v[166:169], v[182:185], v[44:47]
	v_mfma_f32_16x16x32_bf16 v[24:27], v[158:161], v[190:193], v[24:27]
	v_mfma_f32_16x16x32_bf16 v[28:31], v[166:169], v[190:193], v[28:31]
	v_mfma_f32_16x16x32_bf16 v[8:11], v[158:161], v[202:205], v[8:11]
	v_mfma_f32_16x16x32_bf16 v[12:15], v[166:169], v[202:205], v[12:15]
	v_mfma_f32_16x16x32_bf16 v[56:59], v[162:165], v[178:181], v[56:59]
	v_mfma_f32_16x16x32_bf16 v[64:67], v[170:173], v[178:181], v[64:67]
	v_mfma_f32_16x16x32_bf16 v[40:43], v[162:165], v[186:189], v[40:43]
	v_mfma_f32_16x16x32_bf16 v[44:47], v[170:173], v[186:189], v[44:47]
	v_mfma_f32_16x16x32_bf16 v[24:27], v[162:165], v[194:197], v[24:27]
	v_mfma_f32_16x16x32_bf16 v[28:31], v[170:173], v[194:197], v[28:31]
	v_mfma_f32_16x16x32_bf16 v[8:11], v[162:165], v[206:209], v[8:11]
	v_mfma_f32_16x16x32_bf16 v[12:15], v[170:173], v[206:209], v[12:15]
	s_setprio 0
	s_barrier
	s_add_i32 s62, s62, 2
	s_add_u32 s36, s36, 0x100
	s_addc_u32 s37, s37, 0
	s_add_u32 s60, s60, 0x100
	s_addc_u32 s61, s61, 0
	s_cmp_gt_u32 s62, 13
	s_cbranch_scc0 .LBB0_2237
	s_and_b64 vcc, exec, s[18:19]
	s_cbranch_vccz .LBB0_2240
	s_barrier
